# tile boundaries inside a GEMM phase keep the steady-state barrier pairing: per-tile align barrier (leading half) and re-stagger barrier (trailing half) removed
# baseline (speedup 1.0000x reference)
; #define PG8_STAGE(bufoff, gbase, voff) do { _Pragma("unroll") for (int _i = 0; _i < 2; ++_i) \
;         __builtin_amdgcn_global_load_lds((const unsigned*)((const char*)(gbase) + (voff)[_i]), (PG8_LAS unsigned*)(lds + (bufoff) + ldsw + _i * 8192), 16, 0, 0); } while (0)
; #define PG8_LDA(dst, b, h) do { _Pragma("unroll") for (int m = 0; m < 4; ++m) _Pragma("unroll") for (int k = 0; k < 2; ++k) dst[m][k] = *(const PG8_LAS bf16x8*)(lds + PG8_SA(b, h) + aoff + m * 2048 + k * 1024); } while (0)
; #define PG8_LDB(dst, b, h) do { _Pragma("unroll") for (int n = 0; n < 2; ++n) _Pragma("unroll") for (int k = 0; k < 2; ++k) dst[n][k] = *(const PG8_LAS bf16x8*)(lds + PG8_SB(b, h) + boff + n * 2048 + k * 1024); } while (0)
; #define PG8_MMA(ai, bj, At, Bt) do { __builtin_amdgcn_s_setprio(1); _Pragma("unroll") for (int m = 0; m < 4; ++m) _Pragma("unroll") for (int n = 0; n < 2; ++n) _Pragma("unroll") for (int k = 0; k < 2; ++k) \
;         acc[ai][bj][m][n] = __builtin_amdgcn_mfma_f32_16x16x32_bf16(Bt[n][k], At[m][k], acc[ai][bj][m][n], 0, 0, 0); __builtin_amdgcn_s_setprio(0); } while (0)
; #define PG8_WAIT_V(n) asm volatile("s_waitcnt vmcnt(" #n ")" ::: "memory")
; template <class Epi, class Sched, bool ALIGN_EPI = false, bool SP2 = false>
; __device__ __forceinline__ void gemm_phase(PG8_LAS unsigned char* lds, const Gemm g, const Sched& S, const Epi& E) {
;     ...
;             PG8_LDB(B0, 0, 0); PG8_LDB(B1, 0, 1); PG8_SCHED; PG8_LDA(At, 0, 0); PG8_STAGE(PG8_SA(1, 1), a1 + hstep, voffA);
;             PG8_WAIT_V(8); PG8_WAIT_L(0); PG8_BAR; PG8_MMA(0, 0, At, B0); PG8_MMA(0, 1, At, B1); PG8_BAR; PG8_SCHED;
;             PG8_LDA(At, 0, 1); PG8_STAGE(PG8_SB(0, 0), b2, voffB); PG8_STAGE(PG8_SB(0, 1), b2 + hstep, voffB); PG8_STAGE(PG8_SA(0, 0), a2, voffA);
;             PG8_WAIT_V(8); PG8_WAIT_L(0); PG8_BAR; PG8_MMA(1, 0, At, B0); PG8_MMA(1, 1, At, B1); PG8_BAR; PG8_SCHED;
;             PG8_LDB(B0, 1, 0); PG8_LDB(B1, 1, 1); PG8_SCHED; PG8_LDA(At, 1, 0); PG8_STAGE(PG8_SA(0, 1), a2 + hstep, voffA);
;             PG8_WAIT_V(8); PG8_WAIT_L(0); PG8_BAR; PG8_MMA(0, 0, At, B0); PG8_MMA(0, 1, At, B1); PG8_BAR; PG8_SCHED;
;             PG8_LDA(At, 1, 1); PG8_STAGE(PG8_SB(1, 0), b3, voffB); PG8_STAGE(PG8_SB(1, 1), b3 + hstep, voffB); PG8_STAGE(PG8_SA(1, 0), a3, voffA);
;             PG8_WAIT_V(8); PG8_WAIT_L(0); PG8_BAR; PG8_MMA(1, 0, At, B0); PG8_MMA(1, 1, At, B1); PG8_BAR; PG8_SCHED;
.LBB0_36:
	s_add_u32 s18, s58, 0xffe00080
	s_addc_u32 s19, s59, -1
	s_add_i32 s47, 0, 0x10000
	s_cmpk_eq_i32 s46, 0x7c
	s_cselect_b32 s63, s45, s19
	s_cselect_b32 s62, s73, s18
	v_add_u32_e32 v160, s47, v143
	s_cselect_b32 s19, s37, s79
	s_cselect_b32 s18, s84, s78
	s_add_i32 s80, 0, 0x14000
	ds_read_b128 v[156:159], v160
	ds_read_b128 v[164:167], v160 offset:1024
	ds_read_b128 v[168:171], v160 offset:2048
	ds_read_b128 v[172:175], v160 offset:3072
	v_add_u32_e32 v160, s80, v143
	ds_read_b128 v[176:179], v160
	ds_read_b128 v[180:183], v160 offset:1024
	ds_read_b128 v[184:187], v160 offset:2048
	ds_read_b128 v[204:207], v160 offset:3072
	v_lshl_add_u64 v[160:161], s[58:59], 0, v[152:153]
	s_add_i32 m0, s5, 0xc000
	ds_read_b128 v[208:211], v163
	ds_read_b128 v[212:215], v163 offset:1024
	ds_read_b128 v[216:219], v163 offset:2048
	ds_read_b128 v[220:223], v163 offset:3072
	ds_read_b128 v[224:227], v163 offset:4096
	ds_read_b128 v[228:231], v163 offset:5120
	ds_read_b128 v[232:235], v163 offset:6144
	ds_read_b128 v[236:239], v163 offset:7168
	global_load_lds_dwordx4 v[160:161], off
	v_lshl_add_u64 v[160:161], s[58:59], 0, v[154:155]
	s_add_i32 m0, s5, 0xe000
	s_nop 0
	global_load_lds_dwordx4 v[160:161], off
	s_nop 0
	s_waitcnt vmcnt(8)
	s_waitcnt lgkmcnt(0)
	s_setprio 1
	s_barrier
	v_mfma_f32_16x16x32_bf16 v[126:129], v[156:159], v[208:211], v[126:129]
	v_mfma_f32_16x16x32_bf16 v[122:125], v[168:171], v[208:211], v[122:125]
	v_mfma_f32_16x16x32_bf16 v[110:113], v[156:159], v[216:219], v[110:113]
	v_mfma_f32_16x16x32_bf16 v[106:109], v[168:171], v[216:219], v[106:109]
	v_mfma_f32_16x16x32_bf16 v[94:97], v[156:159], v[224:227], v[94:97]
	v_mfma_f32_16x16x32_bf16 v[90:93], v[168:171], v[224:227], v[90:93]
	v_mfma_f32_16x16x32_bf16 v[78:81], v[156:159], v[232:235], v[78:81]
	v_mfma_f32_16x16x32_bf16 v[74:77], v[168:171], v[232:235], v[74:77]
	s_setprio 0
	s_setprio 1
	v_mfma_f32_16x16x32_bf16 v[126:129], v[164:167], v[212:215], v[126:129]
	v_mfma_f32_16x16x32_bf16 v[122:125], v[172:175], v[212:215], v[122:125]
	v_mfma_f32_16x16x32_bf16 v[110:113], v[164:167], v[220:223], v[110:113]
	v_mfma_f32_16x16x32_bf16 v[106:109], v[172:175], v[220:223], v[106:109]
	v_mfma_f32_16x16x32_bf16 v[94:97], v[164:167], v[228:231], v[94:97]
	v_mfma_f32_16x16x32_bf16 v[90:93], v[172:175], v[228:231], v[90:93]
	v_mfma_f32_16x16x32_bf16 v[78:81], v[164:167], v[236:239], v[78:81]
	v_mfma_f32_16x16x32_bf16 v[74:77], v[172:175], v[236:239], v[74:77]
	s_setprio 0
	s_setprio 1
	v_mfma_f32_16x16x32_bf16 v[118:121], v[176:179], v[208:211], v[118:121]
	v_mfma_f32_16x16x32_bf16 v[114:117], v[184:187], v[208:211], v[114:117]
	v_mfma_f32_16x16x32_bf16 v[102:105], v[176:179], v[216:219], v[102:105]
	v_mfma_f32_16x16x32_bf16 v[98:101], v[184:187], v[216:219], v[98:101]
	v_mfma_f32_16x16x32_bf16 v[86:89], v[176:179], v[224:227], v[86:89]
	v_mfma_f32_16x16x32_bf16 v[82:85], v[184:187], v[224:227], v[82:85]
	v_mfma_f32_16x16x32_bf16 v[70:73], v[176:179], v[232:235], v[70:73]
	v_mfma_f32_16x16x32_bf16 v[66:69], v[184:187], v[232:235], v[66:69]
	s_setprio 0
	s_setprio 1
	v_mfma_f32_16x16x32_bf16 v[118:121], v[180:183], v[212:215], v[118:121]
	v_mfma_f32_16x16x32_bf16 v[114:117], v[204:207], v[212:215], v[114:117]
	v_mfma_f32_16x16x32_bf16 v[102:105], v[180:183], v[220:223], v[102:105]
	v_mfma_f32_16x16x32_bf16 v[98:101], v[204:207], v[220:223], v[98:101]
	v_mfma_f32_16x16x32_bf16 v[86:89], v[180:183], v[228:231], v[86:89]
	v_mfma_f32_16x16x32_bf16 v[82:85], v[204:207], v[228:231], v[82:85]
	v_mfma_f32_16x16x32_bf16 v[70:73], v[180:183], v[236:239], v[70:73]
	v_mfma_f32_16x16x32_bf16 v[66:69], v[204:207], v[236:239], v[66:69]
	s_setprio 0
	s_barrier
	s_add_i32 s47, s47, s4
	v_lshl_add_u64 v[160:161], s[18:19], 0, v[148:149]
	s_mov_b32 m0, s47
	ds_read_b128 v[208:211], v163 offset:16384
	ds_read_b128 v[212:215], v163 offset:17408
	ds_read_b128 v[216:219], v163 offset:18432
	ds_read_b128 v[220:223], v163 offset:19456
	ds_read_b128 v[224:227], v163 offset:20480
	ds_read_b128 v[228:231], v163 offset:21504
	ds_read_b128 v[232:235], v163 offset:22528
	ds_read_b128 v[236:239], v163 offset:23552
	global_load_lds_dwordx4 v[160:161], off
	s_add_i32 m0, s47, 0x2000
	s_add_u32 s76, s18, 0x200000
	v_lshl_add_u64 v[240:241], s[18:19], 0, v[144:145]
	s_addc_u32 s77, s19, 0
	s_add_i32 s47, s80, s4
	global_load_lds_dwordx4 v[240:241], off
	v_lshl_add_u64 v[242:243], s[76:77], 0, v[148:149]
	s_mov_b32 m0, s47
	v_lshl_add_u64 v[244:245], s[62:63], 0, v[146:147]
	global_load_lds_dwordx4 v[242:243], off
	v_lshl_add_u64 v[242:243], s[76:77], 0, v[144:145]
	s_add_i32 m0, s47, 0x2000
	s_nop 0
	global_load_lds_dwordx4 v[242:243], off
	v_lshl_add_u64 v[242:243], s[62:63], 0, v[150:151]
	s_mov_b32 m0, s5
	s_nop 0
	global_load_lds_dwordx4 v[242:243], off
	s_mov_b32 m0, s30
	s_nop 0
	global_load_lds_dwordx4 v[244:245], off
	s_waitcnt vmcnt(8)
	s_waitcnt lgkmcnt(0)
	s_setprio 1
	s_barrier
; #define PG8_STAGE(bufoff, gbase, voff) do { _Pragma("unroll") for (int _i = 0; _i < 2; ++_i) \
;         __builtin_amdgcn_global_load_lds((const unsigned*)((const char*)(gbase) + (voff)[_i]), (PG8_LAS unsigned*)(lds + (bufoff) + ldsw + _i * 8192), 16, 0, 0); } while (0)
; #define PG8_LDA(dst, b, h) do { _Pragma("unroll") for (int m = 0; m < 4; ++m) _Pragma("unroll") for (int k = 0; k < 2; ++k) dst[m][k] = *(const PG8_LAS bf16x8*)(lds + PG8_SA(b, h) + aoff + m * 2048 + k * 1024); } while (0)
; #define PG8_LDB(dst, b, h) do { _Pragma("unroll") for (int n = 0; n < 2; ++n) _Pragma("unroll") for (int k = 0; k < 2; ++k) dst[n][k] = *(const PG8_LAS bf16x8*)(lds + PG8_SB(b, h) + boff + n * 2048 + k * 1024); } while (0)
; #define PG8_MMA(ai, bj, At, Bt) do { __builtin_amdgcn_s_setprio(1); _Pragma("unroll") for (int m = 0; m < 4; ++m) _Pragma("unroll") for (int n = 0; n < 2; ++n) _Pragma("unroll") for (int k = 0; k < 2; ++k) \
;         acc[ai][bj][m][n] = __builtin_amdgcn_mfma_f32_16x16x32_bf16(Bt[n][k], At[m][k], acc[ai][bj][m][n], 0, 0, 0); __builtin_amdgcn_s_setprio(0); } while (0)
; #define PG8_WAIT_V(n) asm volatile("s_waitcnt vmcnt(" #n ")" ::: "memory")
; #define PG8_WAIT_L(n) asm volatile("s_waitcnt lgkmcnt(" #n ")" ::: "memory")
; #define PG8_BAR __builtin_amdgcn_s_barrier()
; #define PG8_SCHED __builtin_amdgcn_sched_barrier(0)
; template <class Epi, class Sched, bool ALIGN_EPI = false, bool SP2 = false>
; __device__ __forceinline__ void gemm_phase(PG8_LAS unsigned char* lds, const Gemm g, const Sched& S, const Epi& E) {
;     ...
;             PG8_WAIT_V(8); PG8_WAIT_L(0); PG8_BAR; PG8_MMA(1, 0, At, B0); PG8_MMA(1, 1, At, B1); PG8_BAR; PG8_SCHED;
;             PG8_LDB(B0, 1, 0); PG8_LDB(B1, 1, 1); PG8_SCHED; PG8_LDA(At, 1, 0); PG8_STAGE(PG8_SA(0, 1), a2 + hstep, voffA);
;             PG8_WAIT_V(8); PG8_WAIT_L(0); PG8_BAR; PG8_MMA(0, 0, At, B0); PG8_MMA(0, 1, At, B1); PG8_BAR; PG8_SCHED;
	v_mfma_f32_16x16x32_bf16 v[62:65], v[156:159], v[208:211], v[62:65]
	v_mfma_f32_16x16x32_bf16 v[58:61], v[168:171], v[208:211], v[58:61]
	v_mfma_f32_16x16x32_bf16 v[46:49], v[156:159], v[216:219], v[46:49]
	v_mfma_f32_16x16x32_bf16 v[42:45], v[168:171], v[216:219], v[42:45]
	v_mfma_f32_16x16x32_bf16 v[30:33], v[156:159], v[224:227], v[30:33]
	v_mfma_f32_16x16x32_bf16 v[26:29], v[168:171], v[224:227], v[26:29]
	v_mfma_f32_16x16x32_bf16 v[14:17], v[156:159], v[232:235], v[14:17]
	v_mfma_f32_16x16x32_bf16 v[10:13], v[168:171], v[232:235], v[10:13]
	v_mfma_f32_16x16x32_bf16 v[62:65], v[164:167], v[212:215], v[62:65]
	v_mfma_f32_16x16x32_bf16 v[58:61], v[172:175], v[212:215], v[58:61]
	v_mfma_f32_16x16x32_bf16 v[46:49], v[164:167], v[220:223], v[46:49]
	v_mfma_f32_16x16x32_bf16 v[42:45], v[172:175], v[220:223], v[42:45]
	v_mfma_f32_16x16x32_bf16 v[30:33], v[164:167], v[228:231], v[30:33]
	v_mfma_f32_16x16x32_bf16 v[26:29], v[172:175], v[228:231], v[26:29]
	v_mfma_f32_16x16x32_bf16 v[14:17], v[164:167], v[236:239], v[14:17]
	v_mfma_f32_16x16x32_bf16 v[10:13], v[172:175], v[236:239], v[10:13]
	v_mfma_f32_16x16x32_bf16 v[54:57], v[176:179], v[208:211], v[54:57]
	v_mfma_f32_16x16x32_bf16 v[50:53], v[184:187], v[208:211], v[50:53]
	v_mfma_f32_16x16x32_bf16 v[38:41], v[176:179], v[216:219], v[38:41]
	v_mfma_f32_16x16x32_bf16 v[34:37], v[184:187], v[216:219], v[34:37]
	v_mfma_f32_16x16x32_bf16 v[22:25], v[176:179], v[224:227], v[22:25]
	v_mfma_f32_16x16x32_bf16 v[18:21], v[184:187], v[224:227], v[18:21]
	v_mfma_f32_16x16x32_bf16 v[6:9], v[176:179], v[232:235], v[6:9]
	v_mfma_f32_16x16x32_bf16 v[2:5], v[184:187], v[232:235], v[2:5]
	v_mfma_f32_16x16x32_bf16 v[54:57], v[180:183], v[212:215], v[54:57]
	v_mfma_f32_16x16x32_bf16 v[50:53], v[204:207], v[212:215], v[50:53]
	v_mfma_f32_16x16x32_bf16 v[38:41], v[180:183], v[220:223], v[38:41]
	v_mfma_f32_16x16x32_bf16 v[34:37], v[204:207], v[220:223], v[34:37]
	v_mfma_f32_16x16x32_bf16 v[22:25], v[180:183], v[228:231], v[22:25]
	v_mfma_f32_16x16x32_bf16 v[18:21], v[204:207], v[228:231], v[18:21]
	v_mfma_f32_16x16x32_bf16 v[6:9], v[180:183], v[236:239], v[6:9]
	v_mfma_f32_16x16x32_bf16 v[2:5], v[204:207], v[236:239], v[2:5]
	s_setprio 0
	s_barrier
	s_add_i32 s47, 0, 0x18000
	s_add_i32 s76, 0, 0x1c000
	v_add_u32_e32 v172, s47, v143
	v_add_u32_e32 v203, s76, v143
	ds_read_b128 v[156:159], v172
	ds_read_b128 v[164:167], v172 offset:1024
	ds_read_b128 v[168:171], v172 offset:2048
	ds_read_b128 v[172:175], v172 offset:3072
	ds_read_b128 v[176:179], v203
	ds_read_b128 v[180:183], v203 offset:1024
	ds_read_b128 v[184:187], v203 offset:2048
	ds_read_b128 v[204:207], v203 offset:3072
	s_add_u32 s62, s62, 0x200000
	s_addc_u32 s63, s63, 0
	s_mov_b32 m0, s57
	v_lshl_add_u64 v[246:247], s[62:63], 0, v[150:151]
	ds_read_b128 v[208:211], v163 offset:32768
	ds_read_b128 v[212:215], v163 offset:33792
	ds_read_b128 v[216:219], v163 offset:34816
	ds_read_b128 v[220:223], v163 offset:35840
	ds_read_b128 v[224:227], v163 offset:36864
	ds_read_b128 v[228:231], v163 offset:37888
	ds_read_b128 v[232:235], v163 offset:38912
	ds_read_b128 v[236:239], v163 offset:39936
	global_load_lds_dwordx4 v[246:247], off
	v_lshl_add_u64 v[246:247], s[62:63], 0, v[146:147]
	s_mov_b32 m0, s67
	s_nop 0
	global_load_lds_dwordx4 v[246:247], off
	s_waitcnt vmcnt(8)
	s_waitcnt lgkmcnt(0)
	s_setprio 1
	s_barrier
	v_mfma_f32_16x16x32_bf16 v[126:129], v[156:159], v[208:211], v[126:129]
	v_mfma_f32_16x16x32_bf16 v[122:125], v[168:171], v[208:211], v[122:125]
	v_mfma_f32_16x16x32_bf16 v[110:113], v[156:159], v[216:219], v[110:113]
	v_mfma_f32_16x16x32_bf16 v[106:109], v[168:171], v[216:219], v[106:109]
	v_mfma_f32_16x16x32_bf16 v[94:97], v[156:159], v[224:227], v[94:97]
	v_mfma_f32_16x16x32_bf16 v[90:93], v[168:171], v[224:227], v[90:93]
	v_mfma_f32_16x16x32_bf16 v[78:81], v[156:159], v[232:235], v[78:81]
	v_mfma_f32_16x16x32_bf16 v[74:77], v[168:171], v[232:235], v[74:77]
	s_setprio 0
	s_setprio 1
	v_mfma_f32_16x16x32_bf16 v[126:129], v[164:167], v[212:215], v[126:129]
	v_mfma_f32_16x16x32_bf16 v[122:125], v[172:175], v[212:215], v[122:125]
	v_mfma_f32_16x16x32_bf16 v[110:113], v[164:167], v[220:223], v[110:113]
	v_mfma_f32_16x16x32_bf16 v[106:109], v[172:175], v[220:223], v[106:109]
	v_mfma_f32_16x16x32_bf16 v[94:97], v[164:167], v[228:231], v[94:97]
	v_mfma_f32_16x16x32_bf16 v[90:93], v[172:175], v[228:231], v[90:93]
	v_mfma_f32_16x16x32_bf16 v[78:81], v[164:167], v[236:239], v[78:81]
	v_mfma_f32_16x16x32_bf16 v[74:77], v[172:175], v[236:239], v[74:77]
	s_setprio 0
	s_setprio 1
	v_mfma_f32_16x16x32_bf16 v[118:121], v[176:179], v[208:211], v[118:121]
	v_mfma_f32_16x16x32_bf16 v[114:117], v[184:187], v[208:211], v[114:117]
	v_mfma_f32_16x16x32_bf16 v[102:105], v[176:179], v[216:219], v[102:105]
	v_mfma_f32_16x16x32_bf16 v[98:101], v[184:187], v[216:219], v[98:101]
	v_mfma_f32_16x16x32_bf16 v[86:89], v[176:179], v[224:227], v[86:89]
	v_mfma_f32_16x16x32_bf16 v[82:85], v[184:187], v[224:227], v[82:85]
	v_mfma_f32_16x16x32_bf16 v[70:73], v[176:179], v[232:235], v[70:73]
	v_mfma_f32_16x16x32_bf16 v[66:69], v[184:187], v[232:235], v[66:69]
	s_setprio 0
	s_setprio 1
	v_mfma_f32_16x16x32_bf16 v[118:121], v[180:183], v[212:215], v[118:121]
	v_mfma_f32_16x16x32_bf16 v[114:117], v[204:207], v[212:215], v[114:117]
	v_mfma_f32_16x16x32_bf16 v[102:105], v[180:183], v[220:223], v[102:105]
	v_mfma_f32_16x16x32_bf16 v[98:101], v[204:207], v[220:223], v[98:101]
	v_mfma_f32_16x16x32_bf16 v[86:89], v[180:183], v[228:231], v[86:89]
	v_mfma_f32_16x16x32_bf16 v[82:85], v[204:207], v[228:231], v[82:85]
	v_mfma_f32_16x16x32_bf16 v[70:73], v[180:183], v[236:239], v[70:73]
	v_mfma_f32_16x16x32_bf16 v[66:69], v[204:207], v[236:239], v[66:69]
	s_setprio 0
	s_barrier
; #define PG8_STAGE(bufoff, gbase, voff) do { _Pragma("unroll") for (int _i = 0; _i < 2; ++_i) \
;         __builtin_amdgcn_global_load_lds((const unsigned*)((const char*)(gbase) + (voff)[_i]), (PG8_LAS unsigned*)(lds + (bufoff) + ldsw + _i * 8192), 16, 0, 0); } while (0)
; #define PG8_LDA(dst, b, h) do { _Pragma("unroll") for (int m = 0; m < 4; ++m) _Pragma("unroll") for (int k = 0; k < 2; ++k) dst[m][k] = *(const PG8_LAS bf16x8*)(lds + PG8_SA(b, h) + aoff + m * 2048 + k * 1024); } while (0)
; #define PG8_MMA(ai, bj, At, Bt) do { __builtin_amdgcn_s_setprio(1); _Pragma("unroll") for (int m = 0; m < 4; ++m) _Pragma("unroll") for (int n = 0; n < 2; ++n) _Pragma("unroll") for (int k = 0; k < 2; ++k) \
;         acc[ai][bj][m][n] = __builtin_amdgcn_mfma_f32_16x16x32_bf16(Bt[n][k], At[m][k], acc[ai][bj][m][n], 0, 0, 0); __builtin_amdgcn_s_setprio(0); } while (0)
; #define PG8_WAIT_V(n) asm volatile("s_waitcnt vmcnt(" #n ")" ::: "memory")
; #define PG8_WAIT_L(n) asm volatile("s_waitcnt lgkmcnt(" #n ")" ::: "memory")
; #define PG8_BAR __builtin_amdgcn_s_barrier()
; #define PG8_SCHED __builtin_amdgcn_sched_barrier(0)
; template <class Epi, class Sched, bool ALIGN_EPI = false, bool SP2 = false>
; __device__ __forceinline__ void gemm_phase(PG8_LAS unsigned char* lds, const Gemm g, const Sched& S, const Epi& E) {
;     ...
;             PG8_LDA(At, 1, 1); PG8_STAGE(PG8_SB(1, 0), b3, voffB); PG8_STAGE(PG8_SB(1, 1), b3 + hstep, voffB); PG8_STAGE(PG8_SA(1, 0), a3, voffA);
;             PG8_WAIT_V(8); PG8_WAIT_L(0); PG8_BAR; PG8_MMA(1, 0, At, B0); PG8_MMA(1, 1, At, B1); PG8_BAR; PG8_SCHED;
;     ...
;         if constexpr (ALIGN_EPI) { if (wr == 0) PG8_BAR; }
	s_add_i32 s47, s47, s4
	v_lshl_add_u64 v[160:161], v[160:161], 0, s[68:69]
	s_mov_b32 m0, s47
	ds_read_b128 v[208:211], v163 offset:49152
	ds_read_b128 v[212:215], v163 offset:50176
	ds_read_b128 v[216:219], v163 offset:51200
	ds_read_b128 v[220:223], v163 offset:52224
	ds_read_b128 v[224:227], v163 offset:53248
	ds_read_b128 v[228:231], v163 offset:54272
	ds_read_b128 v[232:235], v163 offset:55296
	ds_read_b128 v[236:239], v163 offset:56320
	global_load_lds_dwordx4 v[160:161], off
	s_add_i32 m0, s47, 0x2000
	s_add_u32 s18, s18, 0x200080
	v_lshl_add_u64 v[160:161], v[240:241], 0, s[68:69]
	s_addc_u32 s19, s19, 0
	s_add_i32 s47, s76, s4
	global_load_lds_dwordx4 v[160:161], off
	v_lshl_add_u64 v[160:161], s[18:19], 0, v[148:149]
	s_mov_b32 m0, s47
	s_nop 0
	global_load_lds_dwordx4 v[160:161], off
	v_lshl_add_u64 v[160:161], s[18:19], 0, v[144:145]
	s_add_i32 m0, s47, 0x2000
	s_nop 0
	global_load_lds_dwordx4 v[160:161], off
	v_lshl_add_u64 v[160:161], v[242:243], 0, s[68:69]
	s_mov_b32 m0, s1
	s_nop 0
	global_load_lds_dwordx4 v[160:161], off
	v_lshl_add_u64 v[160:161], v[244:245], 0, s[68:69]
	s_mov_b32 m0, s60
	s_nop 0
	global_load_lds_dwordx4 v[160:161], off
	s_nop 0
	s_waitcnt vmcnt(8)
	s_waitcnt lgkmcnt(0)
	s_setprio 1
	s_barrier
	v_mfma_f32_16x16x32_bf16 v[62:65], v[156:159], v[208:211], v[62:65]
	v_mfma_f32_16x16x32_bf16 v[58:61], v[168:171], v[208:211], v[58:61]
	v_mfma_f32_16x16x32_bf16 v[46:49], v[156:159], v[216:219], v[46:49]
	v_mfma_f32_16x16x32_bf16 v[42:45], v[168:171], v[216:219], v[42:45]
	v_mfma_f32_16x16x32_bf16 v[30:33], v[156:159], v[224:227], v[30:33]
	v_mfma_f32_16x16x32_bf16 v[26:29], v[168:171], v[224:227], v[26:29]
	v_mfma_f32_16x16x32_bf16 v[14:17], v[156:159], v[232:235], v[14:17]
	v_mfma_f32_16x16x32_bf16 v[10:13], v[168:171], v[232:235], v[10:13]
	v_mfma_f32_16x16x32_bf16 v[62:65], v[164:167], v[212:215], v[62:65]
	v_mfma_f32_16x16x32_bf16 v[58:61], v[172:175], v[212:215], v[58:61]
	v_mfma_f32_16x16x32_bf16 v[46:49], v[164:167], v[220:223], v[46:49]
	v_mfma_f32_16x16x32_bf16 v[42:45], v[172:175], v[220:223], v[42:45]
	v_mfma_f32_16x16x32_bf16 v[30:33], v[164:167], v[228:231], v[30:33]
	v_mfma_f32_16x16x32_bf16 v[26:29], v[172:175], v[228:231], v[26:29]
	v_mfma_f32_16x16x32_bf16 v[14:17], v[164:167], v[236:239], v[14:17]
	v_mfma_f32_16x16x32_bf16 v[10:13], v[172:175], v[236:239], v[10:13]
	v_mfma_f32_16x16x32_bf16 v[54:57], v[176:179], v[208:211], v[54:57]
	v_mfma_f32_16x16x32_bf16 v[50:53], v[184:187], v[208:211], v[50:53]
	v_mfma_f32_16x16x32_bf16 v[38:41], v[176:179], v[216:219], v[38:41]
	v_mfma_f32_16x16x32_bf16 v[34:37], v[184:187], v[216:219], v[34:37]
	v_mfma_f32_16x16x32_bf16 v[22:25], v[176:179], v[224:227], v[22:25]
	v_mfma_f32_16x16x32_bf16 v[18:21], v[184:187], v[224:227], v[18:21]
	v_mfma_f32_16x16x32_bf16 v[6:9], v[176:179], v[232:235], v[6:9]
	v_mfma_f32_16x16x32_bf16 v[2:5], v[184:187], v[232:235], v[2:5]
	v_mfma_f32_16x16x32_bf16 v[54:57], v[180:183], v[212:215], v[54:57]
	v_mfma_f32_16x16x32_bf16 v[50:53], v[204:207], v[212:215], v[50:53]
	v_mfma_f32_16x16x32_bf16 v[38:41], v[180:183], v[220:223], v[38:41]
	v_mfma_f32_16x16x32_bf16 v[34:37], v[204:207], v[220:223], v[34:37]
	v_mfma_f32_16x16x32_bf16 v[22:25], v[180:183], v[228:231], v[22:25]
	v_mfma_f32_16x16x32_bf16 v[18:21], v[204:207], v[228:231], v[18:21]
	v_mfma_f32_16x16x32_bf16 v[6:9], v[180:183], v[236:239], v[6:9]
	v_mfma_f32_16x16x32_bf16 v[2:5], v[204:207], v[236:239], v[2:5]
	s_setprio 0
	s_barrier
	s_add_i32 s46, s46, 2
	s_add_u32 s58, s58, 0x100
	s_addc_u32 s59, s59, 0
	s_add_u32 s78, s78, 0x100
	s_addc_u32 s79, s79, 0
	s_cmpk_gt_u32 s46, 0x7d
	s_cbranch_scc0 .LBB0_36
	s_mov_b32 s32, 1
	s_andn2_b64 vcc, s[12:13], s[42:43]
	s_cbranch_vccz .LBB0_39
	s_barrier

; #define PG8_BAR __builtin_amdgcn_s_barrier()
; template <class Epi, class Sched, bool ALIGN_EPI = false, bool SP2 = false>
; __device__ __forceinline__ void gemm_phase(PG8_LAS unsigned char* lds, const Gemm g, const Sched& S, const Epi& E) {
;     ...
;         if (!has_next) break;
;     ...
;         if constexpr (ALIGN_EPI) { if (wr == 1) PG8_BAR; }
.LBB0_55:
	s_or_b64 exec, exec, s[18:19]
	s_andn2_b64 vcc, exec, s[42:43]
	s_mov_b64 s[18:19], -1
	s_cbranch_vccnz .LBB0_28
	v_readlane_b32 s18, v255, 0
	v_readlane_b32 s19, v255, 1
	s_andn2_b64 vcc, exec, s[18:19]
	s_cbranch_vccnz .LBB0_27
	s_nop 0
	s_branch .LBB0_27

; #define PG8_STAGE(bufoff, gbase, voff) do { _Pragma("unroll") for (int _i = 0; _i < 2; ++_i) \
;         __builtin_amdgcn_global_load_lds((const unsigned*)((const char*)(gbase) + (voff)[_i]), (PG8_LAS unsigned*)(lds + (bufoff) + ldsw + _i * 8192), 16, 0, 0); } while (0)
; #define PG8_LDA(dst, b, h) do { _Pragma("unroll") for (int m = 0; m < 4; ++m) _Pragma("unroll") for (int k = 0; k < 2; ++k) dst[m][k] = *(const PG8_LAS bf16x8*)(lds + PG8_SA(b, h) + aoff + m * 2048 + k * 1024); } while (0)
; #define PG8_LDB(dst, b, h) do { _Pragma("unroll") for (int n = 0; n < 2; ++n) _Pragma("unroll") for (int k = 0; k < 2; ++k) dst[n][k] = *(const PG8_LAS bf16x8*)(lds + PG8_SB(b, h) + boff + n * 2048 + k * 1024); } while (0)
; #define PG8_MMA(ai, bj, At, Bt) do { __builtin_amdgcn_s_setprio(1); _Pragma("unroll") for (int m = 0; m < 4; ++m) _Pragma("unroll") for (int n = 0; n < 2; ++n) _Pragma("unroll") for (int k = 0; k < 2; ++k) \
;         acc[ai][bj][m][n] = __builtin_amdgcn_mfma_f32_16x16x32_bf16(Bt[n][k], At[m][k], acc[ai][bj][m][n], 0, 0, 0); __builtin_amdgcn_s_setprio(0); } while (0)
; #define PG8_WAIT_V(n) asm volatile("s_waitcnt vmcnt(" #n ")" ::: "memory")
; #define PG8_WAIT_L(n) asm volatile("s_waitcnt lgkmcnt(" #n ")" ::: "memory")
; #define PG8_BAR __builtin_amdgcn_s_barrier()
; #define PG8_SCHED __builtin_amdgcn_sched_barrier(0)
; template <class Epi, class Sched, bool ALIGN_EPI = false, bool SP2 = false>
; __device__ __forceinline__ void gemm_phase(PG8_LAS unsigned char* lds, const Gemm g, const Sched& S, const Epi& E) {
;     ...
;             PG8_LDB(B0, 0, 0); PG8_LDB(B1, 0, 1); PG8_SCHED; PG8_LDA(At, 0, 0); PG8_STAGE(PG8_SA(1, 1), a1 + hstep, voffA);
;             PG8_WAIT_V(8); PG8_WAIT_L(0); PG8_BAR; PG8_MMA(0, 0, At, B0); PG8_MMA(0, 1, At, B1); PG8_BAR; PG8_SCHED;
;             PG8_LDA(At, 0, 1); PG8_STAGE(PG8_SB(0, 0), b2, voffB); PG8_STAGE(PG8_SB(0, 1), b2 + hstep, voffB); PG8_STAGE(PG8_SA(0, 0), a2, voffA);
;             PG8_WAIT_V(8); PG8_WAIT_L(0); PG8_BAR; PG8_MMA(1, 0, At, B0); PG8_MMA(1, 1, At, B1); PG8_BAR; PG8_SCHED;
.LBB0_76:
	s_add_u32 s18, s0, 0xfff80080
	s_addc_u32 s19, s1, -1
	s_add_i32 s47, 0, 0x10000
	s_cmp_eq_u32 s46, 28
	s_cselect_b32 s59, s60, s19
	s_cselect_b32 s58, s73, s18
	v_add_u32_e32 v158, s47, v143
	s_cselect_b32 s19, s45, s79
	s_cselect_b32 s18, s84, s78
	s_add_i32 s80, 0, 0x14000
	ds_read_b128 v[162:165], v158
	ds_read_b128 v[166:169], v158 offset:1024
	ds_read_b128 v[170:173], v158 offset:2048
	ds_read_b128 v[174:177], v158 offset:3072
	v_add_u32_e32 v158, s80, v143
	ds_read_b128 v[178:181], v158
	ds_read_b128 v[182:185], v158 offset:1024
	ds_read_b128 v[204:207], v158 offset:2048
	ds_read_b128 v[208:211], v158 offset:3072
	v_lshl_add_u64 v[158:159], s[0:1], 0, v[154:155]
	s_add_i32 m0, s62, 0xc000
	ds_read_b128 v[212:215], v161
	ds_read_b128 v[216:219], v161 offset:1024
	ds_read_b128 v[220:223], v161 offset:2048
	ds_read_b128 v[224:227], v161 offset:3072
	ds_read_b128 v[228:231], v161 offset:4096
	ds_read_b128 v[232:235], v161 offset:5120
	ds_read_b128 v[236:239], v161 offset:6144
	ds_read_b128 v[240:243], v161 offset:7168
	global_load_lds_dwordx4 v[158:159], off
	v_lshl_add_u64 v[158:159], s[0:1], 0, v[156:157]
	s_add_i32 m0, s62, 0xe000
	s_nop 0
	global_load_lds_dwordx4 v[158:159], off
	s_nop 0
	s_waitcnt vmcnt(8)
	s_waitcnt lgkmcnt(0)
	s_setprio 1
	s_barrier
	v_mfma_f32_16x16x32_bf16 v[126:129], v[162:165], v[212:215], v[126:129]
	v_mfma_f32_16x16x32_bf16 v[122:125], v[170:173], v[212:215], v[122:125]
	v_mfma_f32_16x16x32_bf16 v[110:113], v[162:165], v[220:223], v[110:113]
	v_mfma_f32_16x16x32_bf16 v[106:109], v[170:173], v[220:223], v[106:109]
	v_mfma_f32_16x16x32_bf16 v[94:97], v[162:165], v[228:231], v[94:97]
	v_mfma_f32_16x16x32_bf16 v[90:93], v[170:173], v[228:231], v[90:93]
	v_mfma_f32_16x16x32_bf16 v[78:81], v[162:165], v[236:239], v[78:81]
	v_mfma_f32_16x16x32_bf16 v[74:77], v[170:173], v[236:239], v[74:77]
	s_setprio 0
	s_setprio 1
	v_mfma_f32_16x16x32_bf16 v[126:129], v[166:169], v[216:219], v[126:129]
	v_mfma_f32_16x16x32_bf16 v[122:125], v[174:177], v[216:219], v[122:125]
	v_mfma_f32_16x16x32_bf16 v[110:113], v[166:169], v[224:227], v[110:113]
	v_mfma_f32_16x16x32_bf16 v[106:109], v[174:177], v[224:227], v[106:109]
	v_mfma_f32_16x16x32_bf16 v[94:97], v[166:169], v[232:235], v[94:97]
	v_mfma_f32_16x16x32_bf16 v[90:93], v[174:177], v[232:235], v[90:93]
	v_mfma_f32_16x16x32_bf16 v[78:81], v[166:169], v[240:243], v[78:81]
	v_mfma_f32_16x16x32_bf16 v[74:77], v[174:177], v[240:243], v[74:77]
	s_setprio 0
	s_setprio 1
	v_mfma_f32_16x16x32_bf16 v[118:121], v[178:181], v[212:215], v[118:121]
	v_mfma_f32_16x16x32_bf16 v[114:117], v[204:207], v[212:215], v[114:117]
	v_mfma_f32_16x16x32_bf16 v[102:105], v[178:181], v[220:223], v[102:105]
	v_mfma_f32_16x16x32_bf16 v[98:101], v[204:207], v[220:223], v[98:101]
	v_mfma_f32_16x16x32_bf16 v[86:89], v[178:181], v[228:231], v[86:89]
	v_mfma_f32_16x16x32_bf16 v[82:85], v[204:207], v[228:231], v[82:85]
	v_mfma_f32_16x16x32_bf16 v[70:73], v[178:181], v[236:239], v[70:73]
	v_mfma_f32_16x16x32_bf16 v[66:69], v[204:207], v[236:239], v[66:69]
	s_setprio 0
	s_setprio 1
	v_mfma_f32_16x16x32_bf16 v[118:121], v[182:185], v[216:219], v[118:121]
	v_mfma_f32_16x16x32_bf16 v[114:117], v[208:211], v[216:219], v[114:117]
	v_mfma_f32_16x16x32_bf16 v[102:105], v[182:185], v[224:227], v[102:105]
	v_mfma_f32_16x16x32_bf16 v[98:101], v[208:211], v[224:227], v[98:101]
	v_mfma_f32_16x16x32_bf16 v[86:89], v[182:185], v[232:235], v[86:89]
	v_mfma_f32_16x16x32_bf16 v[82:85], v[208:211], v[232:235], v[82:85]
	v_mfma_f32_16x16x32_bf16 v[70:73], v[182:185], v[240:243], v[70:73]
	v_mfma_f32_16x16x32_bf16 v[66:69], v[208:211], v[240:243], v[66:69]
	s_setprio 0
	s_barrier
	s_add_i32 s47, s47, s54
	v_lshl_add_u64 v[158:159], s[18:19], 0, v[148:149]
	s_mov_b32 m0, s47
	ds_read_b128 v[212:215], v161 offset:16384
	ds_read_b128 v[216:219], v161 offset:17408
	ds_read_b128 v[220:223], v161 offset:18432
	ds_read_b128 v[224:227], v161 offset:19456
	ds_read_b128 v[228:231], v161 offset:20480
	ds_read_b128 v[232:235], v161 offset:21504
	ds_read_b128 v[236:239], v161 offset:22528
	ds_read_b128 v[240:243], v161 offset:23552
	global_load_lds_dwordx4 v[158:159], off
	s_add_i32 m0, s47, 0x2000
	s_add_u32 s76, s18, 0x80000
	v_lshl_add_u64 v[186:187], s[18:19], 0, v[144:145]
	s_addc_u32 s77, s19, 0
	s_add_i32 s47, s80, s54
	global_load_lds_dwordx4 v[186:187], off
	v_lshl_add_u64 v[244:245], s[76:77], 0, v[148:149]
	s_mov_b32 m0, s47
	v_lshl_add_u64 v[246:247], s[58:59], 0, v[146:147]
	global_load_lds_dwordx4 v[244:245], off
	v_lshl_add_u64 v[244:245], s[76:77], 0, v[144:145]
	s_add_i32 m0, s47, 0x2000
	s_nop 0
	global_load_lds_dwordx4 v[244:245], off
	v_lshl_add_u64 v[244:245], s[58:59], 0, v[150:151]
	s_mov_b32 m0, s62
	s_nop 0
	global_load_lds_dwordx4 v[244:245], off
	s_mov_b32 m0, s63
	s_nop 0
	global_load_lds_dwordx4 v[246:247], off
	s_waitcnt vmcnt(8)
	s_waitcnt lgkmcnt(0)
	s_setprio 1
	s_barrier
; #define PG8_STAGE(bufoff, gbase, voff) do { _Pragma("unroll") for (int _i = 0; _i < 2; ++_i) \
;         __builtin_amdgcn_global_load_lds((const unsigned*)((const char*)(gbase) + (voff)[_i]), (PG8_LAS unsigned*)(lds + (bufoff) + ldsw + _i * 8192), 16, 0, 0); } while (0)
; #define PG8_LDA(dst, b, h) do { _Pragma("unroll") for (int m = 0; m < 4; ++m) _Pragma("unroll") for (int k = 0; k < 2; ++k) dst[m][k] = *(const PG8_LAS bf16x8*)(lds + PG8_SA(b, h) + aoff + m * 2048 + k * 1024); } while (0)
; #define PG8_LDB(dst, b, h) do { _Pragma("unroll") for (int n = 0; n < 2; ++n) _Pragma("unroll") for (int k = 0; k < 2; ++k) dst[n][k] = *(const PG8_LAS bf16x8*)(lds + PG8_SB(b, h) + boff + n * 2048 + k * 1024); } while (0)
; #define PG8_MMA(ai, bj, At, Bt) do { __builtin_amdgcn_s_setprio(1); _Pragma("unroll") for (int m = 0; m < 4; ++m) _Pragma("unroll") for (int n = 0; n < 2; ++n) _Pragma("unroll") for (int k = 0; k < 2; ++k) \
;         acc[ai][bj][m][n] = __builtin_amdgcn_mfma_f32_16x16x32_bf16(Bt[n][k], At[m][k], acc[ai][bj][m][n], 0, 0, 0); __builtin_amdgcn_s_setprio(0); } while (0)
; #define PG8_WAIT_V(n) asm volatile("s_waitcnt vmcnt(" #n ")" ::: "memory")
; #define PG8_WAIT_L(n) asm volatile("s_waitcnt lgkmcnt(" #n ")" ::: "memory")
; #define PG8_BAR __builtin_amdgcn_s_barrier()
; #define PG8_SCHED __builtin_amdgcn_sched_barrier(0)
; template <class Epi, class Sched, bool ALIGN_EPI = false, bool SP2 = false>
; __device__ __forceinline__ void gemm_phase(PG8_LAS unsigned char* lds, const Gemm g, const Sched& S, const Epi& E) {
;     ...
;             PG8_WAIT_V(8); PG8_WAIT_L(0); PG8_BAR; PG8_MMA(1, 0, At, B0); PG8_MMA(1, 1, At, B1); PG8_BAR; PG8_SCHED;
;             PG8_LDB(B0, 1, 0); PG8_LDB(B1, 1, 1); PG8_SCHED; PG8_LDA(At, 1, 0); PG8_STAGE(PG8_SA(0, 1), a2 + hstep, voffA);
;             PG8_WAIT_V(8); PG8_WAIT_L(0); PG8_BAR; PG8_MMA(0, 0, At, B0); PG8_MMA(0, 1, At, B1); PG8_BAR; PG8_SCHED;
	v_mfma_f32_16x16x32_bf16 v[62:65], v[162:165], v[212:215], v[62:65]
	v_mfma_f32_16x16x32_bf16 v[58:61], v[170:173], v[212:215], v[58:61]
	v_mfma_f32_16x16x32_bf16 v[46:49], v[162:165], v[220:223], v[46:49]
	v_mfma_f32_16x16x32_bf16 v[42:45], v[170:173], v[220:223], v[42:45]
	v_mfma_f32_16x16x32_bf16 v[30:33], v[162:165], v[228:231], v[30:33]
	v_mfma_f32_16x16x32_bf16 v[26:29], v[170:173], v[228:231], v[26:29]
	v_mfma_f32_16x16x32_bf16 v[14:17], v[162:165], v[236:239], v[14:17]
	v_mfma_f32_16x16x32_bf16 v[10:13], v[170:173], v[236:239], v[10:13]
	v_mfma_f32_16x16x32_bf16 v[62:65], v[166:169], v[216:219], v[62:65]
	v_mfma_f32_16x16x32_bf16 v[58:61], v[174:177], v[216:219], v[58:61]
	v_mfma_f32_16x16x32_bf16 v[46:49], v[166:169], v[224:227], v[46:49]
	v_mfma_f32_16x16x32_bf16 v[42:45], v[174:177], v[224:227], v[42:45]
	v_mfma_f32_16x16x32_bf16 v[30:33], v[166:169], v[232:235], v[30:33]
	v_mfma_f32_16x16x32_bf16 v[26:29], v[174:177], v[232:235], v[26:29]
	v_mfma_f32_16x16x32_bf16 v[14:17], v[166:169], v[240:243], v[14:17]
	v_mfma_f32_16x16x32_bf16 v[10:13], v[174:177], v[240:243], v[10:13]
	v_mfma_f32_16x16x32_bf16 v[54:57], v[178:181], v[212:215], v[54:57]
	v_mfma_f32_16x16x32_bf16 v[50:53], v[204:207], v[212:215], v[50:53]
	v_mfma_f32_16x16x32_bf16 v[38:41], v[178:181], v[220:223], v[38:41]
	v_mfma_f32_16x16x32_bf16 v[34:37], v[204:207], v[220:223], v[34:37]
	v_mfma_f32_16x16x32_bf16 v[22:25], v[178:181], v[228:231], v[22:25]
	v_mfma_f32_16x16x32_bf16 v[18:21], v[204:207], v[228:231], v[18:21]
	v_mfma_f32_16x16x32_bf16 v[6:9], v[178:181], v[236:239], v[6:9]
	v_mfma_f32_16x16x32_bf16 v[2:5], v[204:207], v[236:239], v[2:5]
	v_mfma_f32_16x16x32_bf16 v[54:57], v[182:185], v[216:219], v[54:57]
	v_mfma_f32_16x16x32_bf16 v[50:53], v[208:211], v[216:219], v[50:53]
	v_mfma_f32_16x16x32_bf16 v[38:41], v[182:185], v[224:227], v[38:41]
	v_mfma_f32_16x16x32_bf16 v[34:37], v[208:211], v[224:227], v[34:37]
	v_mfma_f32_16x16x32_bf16 v[22:25], v[182:185], v[232:235], v[22:25]
	v_mfma_f32_16x16x32_bf16 v[18:21], v[208:211], v[232:235], v[18:21]
	v_mfma_f32_16x16x32_bf16 v[6:9], v[182:185], v[240:243], v[6:9]
	v_mfma_f32_16x16x32_bf16 v[2:5], v[208:211], v[240:243], v[2:5]
	s_setprio 0
	s_barrier
	s_add_i32 s47, 0, 0x18000
	s_add_i32 s76, 0, 0x1c000
	v_add_u32_e32 v174, s47, v143
	v_add_u32_e32 v203, s76, v143
	ds_read_b128 v[162:165], v174
	ds_read_b128 v[166:169], v174 offset:1024
	ds_read_b128 v[170:173], v174 offset:2048
	ds_read_b128 v[174:177], v174 offset:3072
	ds_read_b128 v[178:181], v203
	ds_read_b128 v[182:185], v203 offset:1024
	ds_read_b128 v[204:207], v203 offset:2048
	ds_read_b128 v[208:211], v203 offset:3072
	s_add_u32 s58, s58, 0x80000
	s_addc_u32 s59, s59, 0
	s_mov_b32 m0, s67
	v_lshl_add_u64 v[248:249], s[58:59], 0, v[150:151]
	ds_read_b128 v[212:215], v161 offset:32768
	ds_read_b128 v[216:219], v161 offset:33792
	ds_read_b128 v[220:223], v161 offset:34816
	ds_read_b128 v[224:227], v161 offset:35840
	ds_read_b128 v[228:231], v161 offset:36864
	ds_read_b128 v[232:235], v161 offset:37888
	ds_read_b128 v[236:239], v161 offset:38912
	ds_read_b128 v[240:243], v161 offset:39936
	global_load_lds_dwordx4 v[248:249], off
	v_lshl_add_u64 v[248:249], s[58:59], 0, v[146:147]
	s_mov_b32 m0, s4
	s_nop 0
	global_load_lds_dwordx4 v[248:249], off
	s_waitcnt vmcnt(8)
	s_waitcnt lgkmcnt(0)
	s_setprio 1
	s_barrier
	v_mfma_f32_16x16x32_bf16 v[126:129], v[162:165], v[212:215], v[126:129]
	v_mfma_f32_16x16x32_bf16 v[122:125], v[170:173], v[212:215], v[122:125]
	v_mfma_f32_16x16x32_bf16 v[110:113], v[162:165], v[220:223], v[110:113]
	v_mfma_f32_16x16x32_bf16 v[106:109], v[170:173], v[220:223], v[106:109]
	v_mfma_f32_16x16x32_bf16 v[94:97], v[162:165], v[228:231], v[94:97]
	v_mfma_f32_16x16x32_bf16 v[90:93], v[170:173], v[228:231], v[90:93]
	v_mfma_f32_16x16x32_bf16 v[78:81], v[162:165], v[236:239], v[78:81]
	v_mfma_f32_16x16x32_bf16 v[74:77], v[170:173], v[236:239], v[74:77]
	s_setprio 0
	s_setprio 1
	v_mfma_f32_16x16x32_bf16 v[126:129], v[166:169], v[216:219], v[126:129]
	v_mfma_f32_16x16x32_bf16 v[122:125], v[174:177], v[216:219], v[122:125]
	v_mfma_f32_16x16x32_bf16 v[110:113], v[166:169], v[224:227], v[110:113]
	v_mfma_f32_16x16x32_bf16 v[106:109], v[174:177], v[224:227], v[106:109]
	v_mfma_f32_16x16x32_bf16 v[94:97], v[166:169], v[232:235], v[94:97]
	v_mfma_f32_16x16x32_bf16 v[90:93], v[174:177], v[232:235], v[90:93]
	v_mfma_f32_16x16x32_bf16 v[78:81], v[166:169], v[240:243], v[78:81]
	v_mfma_f32_16x16x32_bf16 v[74:77], v[174:177], v[240:243], v[74:77]
	s_setprio 0
	s_setprio 1
	v_mfma_f32_16x16x32_bf16 v[118:121], v[178:181], v[212:215], v[118:121]
	v_mfma_f32_16x16x32_bf16 v[114:117], v[204:207], v[212:215], v[114:117]
	v_mfma_f32_16x16x32_bf16 v[102:105], v[178:181], v[220:223], v[102:105]
	v_mfma_f32_16x16x32_bf16 v[98:101], v[204:207], v[220:223], v[98:101]
	v_mfma_f32_16x16x32_bf16 v[86:89], v[178:181], v[228:231], v[86:89]
	v_mfma_f32_16x16x32_bf16 v[82:85], v[204:207], v[228:231], v[82:85]
	v_mfma_f32_16x16x32_bf16 v[70:73], v[178:181], v[236:239], v[70:73]
	v_mfma_f32_16x16x32_bf16 v[66:69], v[204:207], v[236:239], v[66:69]
	s_setprio 0
	s_setprio 1
	v_mfma_f32_16x16x32_bf16 v[118:121], v[182:185], v[216:219], v[118:121]
	v_mfma_f32_16x16x32_bf16 v[114:117], v[208:211], v[216:219], v[114:117]
	v_mfma_f32_16x16x32_bf16 v[102:105], v[182:185], v[224:227], v[102:105]
	v_mfma_f32_16x16x32_bf16 v[98:101], v[208:211], v[224:227], v[98:101]
	v_mfma_f32_16x16x32_bf16 v[86:89], v[182:185], v[232:235], v[86:89]
	v_mfma_f32_16x16x32_bf16 v[82:85], v[208:211], v[232:235], v[82:85]
	v_mfma_f32_16x16x32_bf16 v[70:73], v[182:185], v[240:243], v[70:73]
	v_mfma_f32_16x16x32_bf16 v[66:69], v[208:211], v[240:243], v[66:69]
	s_setprio 0
	s_barrier
; #define PG8_STAGE(bufoff, gbase, voff) do { _Pragma("unroll") for (int _i = 0; _i < 2; ++_i) \
;         __builtin_amdgcn_global_load_lds((const unsigned*)((const char*)(gbase) + (voff)[_i]), (PG8_LAS unsigned*)(lds + (bufoff) + ldsw + _i * 8192), 16, 0, 0); } while (0)
; #define PG8_LDA(dst, b, h) do { _Pragma("unroll") for (int m = 0; m < 4; ++m) _Pragma("unroll") for (int k = 0; k < 2; ++k) dst[m][k] = *(const PG8_LAS bf16x8*)(lds + PG8_SA(b, h) + aoff + m * 2048 + k * 1024); } while (0)
; #define PG8_MMA(ai, bj, At, Bt) do { __builtin_amdgcn_s_setprio(1); _Pragma("unroll") for (int m = 0; m < 4; ++m) _Pragma("unroll") for (int n = 0; n < 2; ++n) _Pragma("unroll") for (int k = 0; k < 2; ++k) \
;         acc[ai][bj][m][n] = __builtin_amdgcn_mfma_f32_16x16x32_bf16(Bt[n][k], At[m][k], acc[ai][bj][m][n], 0, 0, 0); __builtin_amdgcn_s_setprio(0); } while (0)
; #define PG8_WAIT_V(n) asm volatile("s_waitcnt vmcnt(" #n ")" ::: "memory")
; #define PG8_WAIT_L(n) asm volatile("s_waitcnt lgkmcnt(" #n ")" ::: "memory")
; #define PG8_BAR __builtin_amdgcn_s_barrier()
; #define PG8_SCHED __builtin_amdgcn_sched_barrier(0)
;     __device__ __forceinline__ void operator()(const f32x4 (&acc)[2][2][4][2], const Unit& u, int wr, int wc, int fr, int fq) const {
;     ...
;             for (int m = 0; m < 4; ++m) { const size_t row = (size_t)(row0 + ai * HALF + m * 16);
;                 const f32x4* sp = (const f32x4*)(SS + row * 32) + 2 * fq; float s;
;                 { const f32x4 t0 = sp[0], t1 = sp[1]; s = ((t0[0] + t0[1]) + (t0[2] + t0[3])) + ((t1[0] + t1[1]) + (t1[2] + t1[3])); }
; template <class Epi, class Sched, bool ALIGN_EPI = false, bool SP2 = false>
; __device__ __forceinline__ void gemm_phase(PG8_LAS unsigned char* lds, const Gemm g, const Sched& S, const Epi& E) {
;     ...
;             PG8_LDA(At, 1, 1); PG8_STAGE(PG8_SB(1, 0), b3, voffB); PG8_STAGE(PG8_SB(1, 1), b3 + hstep, voffB); PG8_STAGE(PG8_SA(1, 0), a3, voffA);
;             PG8_WAIT_V(8); PG8_WAIT_L(0); PG8_BAR; PG8_MMA(1, 0, At, B0); PG8_MMA(1, 1, At, B1); PG8_BAR; PG8_SCHED;
;     ...
;         if constexpr (ALIGN_EPI) { if (wr == 0) PG8_BAR; }
	s_add_i32 s47, s47, s54
	v_lshl_add_u64 v[158:159], v[158:159], 0, s[68:69]
	s_mov_b32 m0, s47
	ds_read_b128 v[212:215], v161 offset:49152
	ds_read_b128 v[216:219], v161 offset:50176
	ds_read_b128 v[220:223], v161 offset:51200
	ds_read_b128 v[224:227], v161 offset:52224
	ds_read_b128 v[228:231], v161 offset:53248
	ds_read_b128 v[232:235], v161 offset:54272
	ds_read_b128 v[236:239], v161 offset:55296
	ds_read_b128 v[240:243], v161 offset:56320
	global_load_lds_dwordx4 v[158:159], off
	s_add_i32 m0, s47, 0x2000
	s_add_u32 s18, s18, 0x80080
	v_lshl_add_u64 v[158:159], v[186:187], 0, s[68:69]
	s_addc_u32 s19, s19, 0
	s_add_i32 s47, s76, s54
	global_load_lds_dwordx4 v[158:159], off
	v_lshl_add_u64 v[158:159], s[18:19], 0, v[148:149]
	s_mov_b32 m0, s47
	s_nop 0
	global_load_lds_dwordx4 v[158:159], off
	v_lshl_add_u64 v[158:159], s[18:19], 0, v[144:145]
	s_add_i32 m0, s47, 0x2000
	s_nop 0
	global_load_lds_dwordx4 v[158:159], off
	v_lshl_add_u64 v[158:159], v[244:245], 0, s[68:69]
	s_mov_b32 m0, s5
	s_nop 0
	global_load_lds_dwordx4 v[158:159], off
	v_lshl_add_u64 v[158:159], v[246:247], 0, s[68:69]
	s_mov_b32 m0, s57
	s_nop 0
	global_load_lds_dwordx4 v[158:159], off
	s_nop 0
	s_waitcnt vmcnt(8)
	s_waitcnt lgkmcnt(0)
	s_setprio 1
	s_barrier
	v_mfma_f32_16x16x32_bf16 v[62:65], v[162:165], v[212:215], v[62:65]
	v_mfma_f32_16x16x32_bf16 v[58:61], v[170:173], v[212:215], v[58:61]
	v_mfma_f32_16x16x32_bf16 v[46:49], v[162:165], v[220:223], v[46:49]
	v_mfma_f32_16x16x32_bf16 v[42:45], v[170:173], v[220:223], v[42:45]
	v_mfma_f32_16x16x32_bf16 v[30:33], v[162:165], v[228:231], v[30:33]
	v_mfma_f32_16x16x32_bf16 v[26:29], v[170:173], v[228:231], v[26:29]
	v_mfma_f32_16x16x32_bf16 v[14:17], v[162:165], v[236:239], v[14:17]
	v_mfma_f32_16x16x32_bf16 v[10:13], v[170:173], v[236:239], v[10:13]
	v_mfma_f32_16x16x32_bf16 v[62:65], v[166:169], v[216:219], v[62:65]
	v_mfma_f32_16x16x32_bf16 v[58:61], v[174:177], v[216:219], v[58:61]
	v_mfma_f32_16x16x32_bf16 v[46:49], v[166:169], v[224:227], v[46:49]
	v_mfma_f32_16x16x32_bf16 v[42:45], v[174:177], v[224:227], v[42:45]
	v_mfma_f32_16x16x32_bf16 v[30:33], v[166:169], v[232:235], v[30:33]
	v_mfma_f32_16x16x32_bf16 v[26:29], v[174:177], v[232:235], v[26:29]
	v_mfma_f32_16x16x32_bf16 v[14:17], v[166:169], v[240:243], v[14:17]
	v_mfma_f32_16x16x32_bf16 v[10:13], v[174:177], v[240:243], v[10:13]
	v_mfma_f32_16x16x32_bf16 v[54:57], v[178:181], v[212:215], v[54:57]
	v_mfma_f32_16x16x32_bf16 v[50:53], v[204:207], v[212:215], v[50:53]
	v_mfma_f32_16x16x32_bf16 v[38:41], v[178:181], v[220:223], v[38:41]
	v_mfma_f32_16x16x32_bf16 v[34:37], v[204:207], v[220:223], v[34:37]
	v_mfma_f32_16x16x32_bf16 v[22:25], v[178:181], v[228:231], v[22:25]
	v_mfma_f32_16x16x32_bf16 v[18:21], v[204:207], v[228:231], v[18:21]
	v_mfma_f32_16x16x32_bf16 v[6:9], v[178:181], v[236:239], v[6:9]
	v_mfma_f32_16x16x32_bf16 v[2:5], v[204:207], v[236:239], v[2:5]
	v_mfma_f32_16x16x32_bf16 v[54:57], v[182:185], v[216:219], v[54:57]
	v_mfma_f32_16x16x32_bf16 v[50:53], v[208:211], v[216:219], v[50:53]
	v_mfma_f32_16x16x32_bf16 v[38:41], v[182:185], v[224:227], v[38:41]
	v_mfma_f32_16x16x32_bf16 v[34:37], v[208:211], v[224:227], v[34:37]
	v_mfma_f32_16x16x32_bf16 v[22:25], v[182:185], v[232:235], v[22:25]
	v_mfma_f32_16x16x32_bf16 v[18:21], v[208:211], v[232:235], v[18:21]
	v_mfma_f32_16x16x32_bf16 v[6:9], v[182:185], v[240:243], v[6:9]
	v_mfma_f32_16x16x32_bf16 v[2:5], v[208:211], v[240:243], v[2:5]
	s_setprio 0
	s_barrier
	s_add_i32 s46, s46, 2
	s_add_u32 s0, s0, 0x100
	s_addc_u32 s1, s1, 0
	s_add_u32 s78, s78, 0x100
	s_addc_u32 s79, s79, 0
	s_cmp_gt_u32 s46, 29
	s_cbranch_scc0 .LBB0_76
	s_mov_b32 s32, 1
	s_andn2_b64 vcc, s[42:43], s[40:41]
	s_cbranch_vccz .LBB0_79
	s_barrier
.LBB0_79:
	v_xor_b32_e32 v159, 16, v192
	v_add_u32_e32 v163, 64, v193
	v_cmp_lt_i32_e32 vcc, v159, v163
	v_lshl_add_u32 v158, s34, 8, v1
	v_lshl_or_b32 v172, s28, 8, v160
	v_cndmask_b32_e32 v159, v192, v159, vcc
	v_lshlrev_b32_e32 v162, 2, v159
	v_xor_b32_e32 v159, 32, v192
	v_cmp_lt_i32_e32 vcc, v159, v163
	v_ashrrev_i32_e32 v173, 31, v172
	s_nop 0
	v_cndmask_b32_e32 v159, v192, v159, vcc
	v_lshlrev_b32_e32 v163, 2, v159
	v_ashrrev_i32_e32 v159, 31, v158
	v_lshlrev_b64 v[164:165], 7, v[158:159]
	v_lshl_add_u64 v[168:169], v[152:153], 0, v[164:165]
	global_load_dwordx4 v[164:167], v[168:169], off
	s_nop 0
	global_load_dwordx4 v[168:171], v[168:169], off offset:16
	s_waitcnt vmcnt(0)
	v_mov_b32_e32 v174, v164
	v_mov_b32_e32 v175, v168
	v_mov_b32_e32 v168, v165
	v_pk_add_f32 v[164:165], v[174:175], v[168:169]
	v_mov_b32_e32 v168, v166
	v_mov_b32_e32 v169, v170
	v_mov_b32_e32 v170, v167
	v_pk_add_f32 v[166:167], v[168:169], v[170:171]
	s_nop 0
	v_pk_add_f32 v[164:165], v[164:165], v[166:167]
	s_nop 0
	v_add_f32_e32 v164, v164, v165
	ds_bpermute_b32 v165, v162, v164
	s_waitcnt lgkmcnt(0)
	v_add_f32_e32 v164, v164, v165
	ds_bpermute_b32 v165, v163, v164
	s_waitcnt lgkmcnt(0)
; __device__ __forceinline__ unsigned cvt_pk_bf16(float lo, float hi) { const f32x2c_t v = {lo, hi}; const bf16x2c_t b = __builtin_convertvector(v, bf16x2c_t); return __builtin_bit_cast(unsigned, b); }
;     __device__ __forceinline__ void operator()(const f32x4 (&acc)[2][2][4][2], const Unit& u, int wr, int wc, int fr, int fq) const {
;     ...
;             for (int m = 0; m < 4; ++m) { const size_t row = (size_t)(row0 + ai * HALF + m * 16);
;                 const f32x4* sp = (const f32x4*)(SS + row * 32) + 2 * fq; float s;
;                 { const f32x4 t0 = sp[0], t1 = sp[1]; s = ((t0[0] + t0[1]) + (t0[2] + t0[3])) + ((t1[0] + t1[1]) + (t1[2] + t1[3])); }
;                 s += __shfl_xor(s, 16); s += __shfl_xor(s, 32);
;                 const float rstd = 1.0f / sqrtf(s * (1.0f / DM) + NORM_EPS);
; #pragma unroll
;                 for (int bj = 0; bj < 2; ++bj) { f32x4 v0 = acc[ai][bj][m][0] * rstd, v1 = acc[ai][bj][m][1] * rstd;
; #pragma unroll
;                     for (int e = 0; e < 4; ++e) { const float a = fmaxf(v0[e], 0.f), b = fmaxf(v1[e], 0.f); v0[e] = a * a; v1[e] = b * b; }
;                     u32x4 w; w.x = cvt_pk_bf16(v0[0], v0[1]); w.y = cvt_pk_bf16(v0[2], v0[3]); w.z = cvt_pk_bf16(v1[0], v1[1]); w.w = cvt_pk_bf16(v1[2], v1[3]);
;                     *(u32x4*)(H + row * DFF + col0 + bj * HALF) = w; } }
	v_add_f32_e32 v164, v164, v165
	v_fmamk_f32 v164, v164, 0x3a000000, v190
	v_cmp_gt_f32_e32 vcc, s72, v164
	v_mul_f32_e32 v165, 0x4f800000, v164
	s_nop 0
	v_cndmask_b32_e32 v164, v164, v165, vcc
	v_sqrt_f32_e32 v165, v164
	s_nop 0
	v_add_u32_e32 v166, -1, v165
	v_fma_f32 v167, -v166, v165, v164
	v_cmp_ge_f32_e64 s[0:1], 0, v167
	v_add_u32_e32 v167, 1, v165
	s_nop 0
	v_cndmask_b32_e64 v166, v165, v166, s[0:1]
	v_fma_f32 v165, -v167, v165, v164
	v_cmp_lt_f32_e64 s[0:1], 0, v165
	s_nop 1
	v_cndmask_b32_e64 v165, v166, v167, s[0:1]
	v_mul_f32_e32 v166, 0x37800000, v165
	v_cndmask_b32_e32 v165, v165, v166, vcc
	v_cmp_class_f32_e32 vcc, v164, v191
	s_nop 1
	v_cndmask_b32_e32 v164, v165, v164, vcc
	v_div_scale_f32 v165, s[0:1], v164, v164, 1.0
	v_rcp_f32_e32 v166, v165
	s_nop 0
	v_fma_f32 v167, -v165, v166, 1.0
	v_fmac_f32_e32 v166, v167, v166
	v_div_scale_f32 v167, vcc, 1.0, v164, 1.0
	v_mul_f32_e32 v168, v167, v166
	v_fma_f32 v169, -v165, v168, v167
	v_fmac_f32_e32 v168, v169, v166
	v_fma_f32 v165, -v165, v168, v167
	v_div_fmas_f32 v165, v165, v166, v168
	v_div_fixup_f32 v164, v165, v164, 1.0
	v_pk_mul_f32 v[128:129], v[128:129], v[164:165] op_sel_hi:[1,0]
	v_pk_mul_f32 v[126:127], v[126:127], v[164:165] op_sel_hi:[1,0]
	v_pk_mul_f32 v[122:123], v[122:123], v[164:165] op_sel_hi:[1,0]
	v_pk_mul_f32 v[124:125], v[124:125], v[164:165] op_sel_hi:[1,0]
	v_max_f32_e32 v126, 0, v126
	v_max_f32_e32 v122, 0, v122
	v_max_f32_e32 v127, 0, v127
	v_max_f32_e32 v123, 0, v123
	v_max_f32_e32 v128, 0, v128
	v_max_f32_e32 v129, 0, v129
	v_lshlrev_b64 v[166:167], 14, v[158:159]
	v_pk_mul_f32 v[126:127], v[126:127], v[126:127]
	v_pk_mul_f32 v[122:123], v[122:123], v[122:123]
	v_max_f32_e32 v124, 0, v124
	v_max_f32_e32 v125, 0, v125
	v_pk_mul_f32 v[128:129], v[128:129], v[128:129]
	v_pk_mul_f32 v[168:169], v[124:125], v[124:125]
	v_cvt_pk_bf16_f32 v124, v126, v127
	v_cvt_pk_bf16_f32 v125, v128, v129
	v_cvt_pk_bf16_f32 v126, v122, v123
	v_lshl_add_u64 v[128:129], s[92:93], 0, v[166:167]
	v_lshlrev_b64 v[122:123], 1, v[172:173]
	v_pk_mul_f32 v[114:115], v[114:115], v[164:165] op_sel_hi:[1,0]
	v_cvt_pk_bf16_f32 v127, v168, v169
	v_lshl_add_u64 v[128:129], v[128:129], 0, v[122:123]
	v_pk_mul_f32 v[120:121], v[120:121], v[164:165] op_sel_hi:[1,0]
	v_pk_mul_f32 v[118:119], v[118:119], v[164:165] op_sel_hi:[1,0]
	v_pk_mul_f32 v[116:117], v[116:117], v[164:165] op_sel_hi:[1,0]
	v_max_f32_e32 v114, 0, v114
	v_max_f32_e32 v115, 0, v115
	global_store_dwordx4 v[128:129], v[124:127], off
	v_max_f32_e32 v118, 0, v118
	v_max_f32_e32 v119, 0, v119
	v_pk_mul_f32 v[124:125], v[114:115], v[114:115]
	v_max_f32_e32 v114, 0, v120
	v_max_f32_e32 v116, 0, v116
	v_max_f32_e32 v115, 0, v121
	v_max_f32_e32 v117, 0, v117
	v_pk_mul_f32 v[118:119], v[118:119], v[118:119]
	v_pk_mul_f32 v[120:121], v[114:115], v[114:115]
	v_pk_mul_f32 v[126:127], v[116:117], v[116:117]
	v_cvt_pk_bf16_f32 v114, v118, v119
	v_cvt_pk_bf16_f32 v115, v120, v121
	v_cvt_pk_bf16_f32 v116, v124, v125
	v_cvt_pk_bf16_f32 v117, v126, v127
	global_store_dwordx4 v[128:129], v[114:117], off offset:256
	s_nop 1
	v_or_b32_e32 v114, 16, v158
	v_ashrrev_i32_e32 v115, 31, v114
	v_lshlrev_b64 v[116:117], 7, v[114:115]
	v_lshl_add_u64 v[120:121], v[152:153], 0, v[116:117]
	global_load_dwordx4 v[116:119], v[120:121], off
	global_load_dwordx4 v[124:127], v[120:121], off offset:16
	v_lshlrev_b64 v[114:115], 14, v[114:115]
	s_waitcnt vmcnt(1)
	v_mov_b32_e32 v120, v116
	s_waitcnt vmcnt(0)
	v_mov_b32_e32 v121, v124
	v_mov_b32_e32 v124, v117
	v_pk_add_f32 v[116:117], v[120:121], v[124:125]
	v_mov_b32_e32 v120, v118
	v_mov_b32_e32 v121, v126
	v_mov_b32_e32 v126, v119
	v_pk_add_f32 v[118:119], v[120:121], v[126:127]
	s_nop 0
	v_pk_add_f32 v[116:117], v[116:117], v[118:119]
	s_nop 0
	v_add_f32_e32 v116, v116, v117
	ds_bpermute_b32 v117, v162, v116
	s_waitcnt lgkmcnt(0)
	v_add_f32_e32 v116, v116, v117
	ds_bpermute_b32 v117, v163, v116
	s_waitcnt lgkmcnt(0)
	v_add_f32_e32 v116, v116, v117
	v_fmamk_f32 v116, v116, 0x3a000000, v190
	v_cmp_gt_f32_e32 vcc, s72, v116
	v_mul_f32_e32 v117, 0x4f800000, v116
	s_nop 0
	v_cndmask_b32_e32 v116, v116, v117, vcc
	v_sqrt_f32_e32 v117, v116
	s_nop 0
	v_add_u32_e32 v118, -1, v117
	v_fma_f32 v119, -v118, v117, v116
	v_cmp_ge_f32_e64 s[0:1], 0, v119
	v_add_u32_e32 v119, 1, v117
	s_nop 0
	v_cndmask_b32_e64 v118, v117, v118, s[0:1]
	v_fma_f32 v117, -v119, v117, v116
	v_cmp_lt_f32_e64 s[0:1], 0, v117
	s_nop 1
	v_cndmask_b32_e64 v117, v118, v119, s[0:1]
	v_mul_f32_e32 v118, 0x37800000, v117
	v_cndmask_b32_e32 v117, v117, v118, vcc
	v_cmp_class_f32_e32 vcc, v116, v191
	s_nop 1
	v_cndmask_b32_e32 v116, v117, v116, vcc
	v_div_scale_f32 v117, s[0:1], v116, v116, 1.0
	v_rcp_f32_e32 v118, v117
	s_nop 0
	v_fma_f32 v119, -v117, v118, 1.0
	v_fmac_f32_e32 v118, v119, v118
	v_div_scale_f32 v119, vcc, 1.0, v116, 1.0
	v_mul_f32_e32 v120, v119, v118
	v_fma_f32 v121, -v117, v120, v119
	v_fmac_f32_e32 v120, v121, v118
	v_fma_f32 v117, -v117, v120, v119
	v_div_fmas_f32 v117, v117, v118, v120
	v_div_fixup_f32 v116, v117, v116, 1.0
	v_pk_mul_f32 v[110:111], v[110:111], v[116:117] op_sel_hi:[1,0]
	v_pk_mul_f32 v[106:107], v[106:107], v[116:117] op_sel_hi:[1,0]
	v_pk_mul_f32 v[112:113], v[112:113], v[116:117] op_sel_hi:[1,0]
	v_pk_mul_f32 v[108:109], v[108:109], v[116:117] op_sel_hi:[1,0]
	v_max_f32_e32 v110, 0, v110
	v_max_f32_e32 v106, 0, v106
	v_max_f32_e32 v111, 0, v111
	v_max_f32_e32 v107, 0, v107
	v_pk_mul_f32 v[110:111], v[110:111], v[110:111]
	v_pk_mul_f32 v[118:119], v[106:107], v[106:107]
	v_max_f32_e32 v106, 0, v112
	v_max_f32_e32 v108, 0, v108
	v_max_f32_e32 v107, 0, v113
	v_max_f32_e32 v109, 0, v109
; __device__ __forceinline__ unsigned cvt_pk_bf16(float lo, float hi) { const f32x2c_t v = {lo, hi}; const bf16x2c_t b = __builtin_convertvector(v, bf16x2c_t); return __builtin_bit_cast(unsigned, b); }
;     __device__ __forceinline__ void operator()(const f32x4 (&acc)[2][2][4][2], const Unit& u, int wr, int wc, int fr, int fq) const {
;     ...
;             for (int m = 0; m < 4; ++m) { const size_t row = (size_t)(row0 + ai * HALF + m * 16);
;                 const f32x4* sp = (const f32x4*)(SS + row * 32) + 2 * fq; float s;
;                 { const f32x4 t0 = sp[0], t1 = sp[1]; s = ((t0[0] + t0[1]) + (t0[2] + t0[3])) + ((t1[0] + t1[1]) + (t1[2] + t1[3])); }
;                 s += __shfl_xor(s, 16); s += __shfl_xor(s, 32);
;                 const float rstd = 1.0f / sqrtf(s * (1.0f / DM) + NORM_EPS);
; #pragma unroll
;                 for (int bj = 0; bj < 2; ++bj) { f32x4 v0 = acc[ai][bj][m][0] * rstd, v1 = acc[ai][bj][m][1] * rstd;
; #pragma unroll
;                     for (int e = 0; e < 4; ++e) { const float a = fmaxf(v0[e], 0.f), b = fmaxf(v1[e], 0.f); v0[e] = a * a; v1[e] = b * b; }
;                     u32x4 w; w.x = cvt_pk_bf16(v0[0], v0[1]); w.y = cvt_pk_bf16(v0[2], v0[3]); w.z = cvt_pk_bf16(v1[0], v1[1]); w.w = cvt_pk_bf16(v1[2], v1[3]);
;                     *(u32x4*)(H + row * DFF + col0 + bj * HALF) = w; } }
	v_pk_mul_f32 v[112:113], v[106:107], v[106:107]
	v_pk_mul_f32 v[120:121], v[108:109], v[108:109]
	v_cvt_pk_bf16_f32 v106, v110, v111
	v_lshl_add_u64 v[110:111], s[92:93], 0, v[114:115]
	v_pk_mul_f32 v[98:99], v[98:99], v[116:117] op_sel_hi:[1,0]
	v_cvt_pk_bf16_f32 v107, v112, v113
	v_cvt_pk_bf16_f32 v108, v118, v119
	v_cvt_pk_bf16_f32 v109, v120, v121
	v_lshl_add_u64 v[110:111], v[110:111], 0, v[122:123]
	v_pk_mul_f32 v[104:105], v[104:105], v[116:117] op_sel_hi:[1,0]
	v_pk_mul_f32 v[102:103], v[102:103], v[116:117] op_sel_hi:[1,0]
	v_pk_mul_f32 v[100:101], v[100:101], v[116:117] op_sel_hi:[1,0]
	v_max_f32_e32 v98, 0, v98
	v_max_f32_e32 v99, 0, v99
	global_store_dwordx4 v[110:111], v[106:109], off
	v_max_f32_e32 v102, 0, v102
	v_max_f32_e32 v103, 0, v103
	v_pk_mul_f32 v[106:107], v[98:99], v[98:99]
	v_max_f32_e32 v98, 0, v104
	v_max_f32_e32 v100, 0, v100
	v_max_f32_e32 v99, 0, v105
	v_max_f32_e32 v101, 0, v101
	v_pk_mul_f32 v[102:103], v[102:103], v[102:103]
	v_pk_mul_f32 v[104:105], v[98:99], v[98:99]
	v_pk_mul_f32 v[108:109], v[100:101], v[100:101]
	v_cvt_pk_bf16_f32 v98, v102, v103
	v_cvt_pk_bf16_f32 v99, v104, v105
	v_cvt_pk_bf16_f32 v100, v106, v107
	v_cvt_pk_bf16_f32 v101, v108, v109
	global_store_dwordx4 v[110:111], v[98:101], off offset:256
	s_nop 1
	v_or_b32_e32 v98, 32, v158
	v_ashrrev_i32_e32 v99, 31, v98
	v_lshlrev_b64 v[100:101], 7, v[98:99]
	v_lshl_add_u64 v[100:101], v[152:153], 0, v[100:101]
	global_load_dwordx4 v[102:105], v[100:101], off
	global_load_dwordx4 v[106:109], v[100:101], off offset:16
	v_lshlrev_b64 v[98:99], 14, v[98:99]
	s_waitcnt vmcnt(1)
	v_mov_b32_e32 v100, v102
	s_waitcnt vmcnt(0)
	v_mov_b32_e32 v101, v106
	v_mov_b32_e32 v106, v103
	v_mov_b32_e32 v102, v104
	v_mov_b32_e32 v103, v108
	v_mov_b32_e32 v108, v105
	v_pk_add_f32 v[100:101], v[100:101], v[106:107]
	v_pk_add_f32 v[102:103], v[102:103], v[108:109]
	s_nop 0
	v_pk_add_f32 v[100:101], v[100:101], v[102:103]
	s_nop 0
	v_add_f32_e32 v100, v100, v101
	ds_bpermute_b32 v101, v162, v100
	s_waitcnt lgkmcnt(0)
	v_add_f32_e32 v100, v100, v101
	ds_bpermute_b32 v101, v163, v100
	s_waitcnt lgkmcnt(0)
	v_add_f32_e32 v100, v100, v101
	v_fmamk_f32 v100, v100, 0x3a000000, v190
	v_cmp_gt_f32_e32 vcc, s72, v100
	v_mul_f32_e32 v101, 0x4f800000, v100
	s_nop 0
	v_cndmask_b32_e32 v100, v100, v101, vcc
	v_sqrt_f32_e32 v101, v100
	s_nop 0
	v_add_u32_e32 v102, -1, v101
	v_fma_f32 v103, -v102, v101, v100
	v_cmp_ge_f32_e64 s[0:1], 0, v103
	v_add_u32_e32 v103, 1, v101
	s_nop 0
	v_cndmask_b32_e64 v102, v101, v102, s[0:1]
	v_fma_f32 v101, -v103, v101, v100
	v_cmp_lt_f32_e64 s[0:1], 0, v101
	s_nop 1
	v_cndmask_b32_e64 v101, v102, v103, s[0:1]
	v_mul_f32_e32 v102, 0x37800000, v101
	v_cndmask_b32_e32 v101, v101, v102, vcc
	v_cmp_class_f32_e32 vcc, v100, v191
	s_nop 1
	v_cndmask_b32_e32 v100, v101, v100, vcc
	v_div_scale_f32 v101, s[0:1], v100, v100, 1.0
	v_rcp_f32_e32 v102, v101
	s_nop 0
	v_fma_f32 v103, -v101, v102, 1.0
	v_fmac_f32_e32 v102, v103, v102
	v_div_scale_f32 v103, vcc, 1.0, v100, 1.0
	v_mul_f32_e32 v104, v103, v102
	v_fma_f32 v105, -v101, v104, v103
	v_fmac_f32_e32 v104, v105, v102
	v_fma_f32 v101, -v101, v104, v103
	v_div_fmas_f32 v101, v101, v102, v104
	v_div_fixup_f32 v100, v101, v100, 1.0
	v_pk_mul_f32 v[94:95], v[94:95], v[100:101] op_sel_hi:[1,0]
	v_pk_mul_f32 v[90:91], v[90:91], v[100:101] op_sel_hi:[1,0]
	v_pk_mul_f32 v[96:97], v[96:97], v[100:101] op_sel_hi:[1,0]
	v_pk_mul_f32 v[92:93], v[92:93], v[100:101] op_sel_hi:[1,0]
	v_max_f32_e32 v94, 0, v94
	v_max_f32_e32 v90, 0, v90
	v_max_f32_e32 v95, 0, v95
	v_max_f32_e32 v91, 0, v91
	v_pk_mul_f32 v[94:95], v[94:95], v[94:95]
	v_pk_mul_f32 v[102:103], v[90:91], v[90:91]
	v_max_f32_e32 v90, 0, v96
	v_max_f32_e32 v92, 0, v92
	v_max_f32_e32 v91, 0, v97
	v_max_f32_e32 v93, 0, v93
	v_pk_mul_f32 v[96:97], v[90:91], v[90:91]
	v_pk_mul_f32 v[104:105], v[92:93], v[92:93]
	v_cvt_pk_bf16_f32 v90, v94, v95
	v_lshl_add_u64 v[94:95], s[92:93], 0, v[98:99]
	v_pk_mul_f32 v[82:83], v[82:83], v[100:101] op_sel_hi:[1,0]
	v_cvt_pk_bf16_f32 v91, v96, v97
	v_cvt_pk_bf16_f32 v92, v102, v103
	v_cvt_pk_bf16_f32 v93, v104, v105
	v_lshl_add_u64 v[94:95], v[94:95], 0, v[122:123]
	v_pk_mul_f32 v[88:89], v[88:89], v[100:101] op_sel_hi:[1,0]
	v_pk_mul_f32 v[86:87], v[86:87], v[100:101] op_sel_hi:[1,0]
	v_pk_mul_f32 v[84:85], v[84:85], v[100:101] op_sel_hi:[1,0]
	v_max_f32_e32 v82, 0, v82
	v_max_f32_e32 v83, 0, v83
	global_store_dwordx4 v[94:95], v[90:93], off
	v_max_f32_e32 v86, 0, v86
	v_max_f32_e32 v87, 0, v87
	v_pk_mul_f32 v[90:91], v[82:83], v[82:83]
	v_max_f32_e32 v82, 0, v88
	v_max_f32_e32 v84, 0, v84
	v_max_f32_e32 v83, 0, v89
	v_max_f32_e32 v85, 0, v85
	v_pk_mul_f32 v[86:87], v[86:87], v[86:87]
	v_pk_mul_f32 v[88:89], v[82:83], v[82:83]
	v_pk_mul_f32 v[92:93], v[84:85], v[84:85]
	v_cvt_pk_bf16_f32 v82, v86, v87
	v_cvt_pk_bf16_f32 v83, v88, v89
	v_cvt_pk_bf16_f32 v84, v90, v91
	v_cvt_pk_bf16_f32 v85, v92, v93
	global_store_dwordx4 v[94:95], v[82:85], off offset:256
	s_nop 1
	v_or_b32_e32 v82, 48, v158
	v_ashrrev_i32_e32 v83, 31, v82
	v_lshlrev_b64 v[84:85], 7, v[82:83]
	v_lshl_add_u64 v[84:85], v[152:153], 0, v[84:85]
	global_load_dwordx4 v[86:89], v[84:85], off
	global_load_dwordx4 v[90:93], v[84:85], off offset:16
	v_lshlrev_b64 v[82:83], 14, v[82:83]
	s_waitcnt vmcnt(1)
	v_mov_b32_e32 v84, v86
	s_waitcnt vmcnt(0)
	v_mov_b32_e32 v85, v90
	v_mov_b32_e32 v90, v87
	v_mov_b32_e32 v86, v88
	v_mov_b32_e32 v87, v92
	v_mov_b32_e32 v92, v89
	v_pk_add_f32 v[84:85], v[84:85], v[90:91]
	v_pk_add_f32 v[86:87], v[86:87], v[92:93]
	s_nop 0
	v_pk_add_f32 v[84:85], v[84:85], v[86:87]
	s_nop 0
	v_add_f32_e32 v84, v84, v85
	ds_bpermute_b32 v85, v162, v84
	s_waitcnt lgkmcnt(0)
; __device__ __forceinline__ unsigned cvt_pk_bf16(float lo, float hi) { const f32x2c_t v = {lo, hi}; const bf16x2c_t b = __builtin_convertvector(v, bf16x2c_t); return __builtin_bit_cast(unsigned, b); }
;     __device__ __forceinline__ void operator()(const f32x4 (&acc)[2][2][4][2], const Unit& u, int wr, int wc, int fr, int fq) const {
;     ...
;             for (int m = 0; m < 4; ++m) { const size_t row = (size_t)(row0 + ai * HALF + m * 16);
;                 const f32x4* sp = (const f32x4*)(SS + row * 32) + 2 * fq; float s;
;                 { const f32x4 t0 = sp[0], t1 = sp[1]; s = ((t0[0] + t0[1]) + (t0[2] + t0[3])) + ((t1[0] + t1[1]) + (t1[2] + t1[3])); }
;                 s += __shfl_xor(s, 16); s += __shfl_xor(s, 32);
;                 const float rstd = 1.0f / sqrtf(s * (1.0f / DM) + NORM_EPS);
; #pragma unroll
;                 for (int bj = 0; bj < 2; ++bj) { f32x4 v0 = acc[ai][bj][m][0] * rstd, v1 = acc[ai][bj][m][1] * rstd;
; #pragma unroll
;                     for (int e = 0; e < 4; ++e) { const float a = fmaxf(v0[e], 0.f), b = fmaxf(v1[e], 0.f); v0[e] = a * a; v1[e] = b * b; }
;                     u32x4 w; w.x = cvt_pk_bf16(v0[0], v0[1]); w.y = cvt_pk_bf16(v0[2], v0[3]); w.z = cvt_pk_bf16(v1[0], v1[1]); w.w = cvt_pk_bf16(v1[2], v1[3]);
;                     *(u32x4*)(H + row * DFF + col0 + bj * HALF) = w; } }
	v_add_f32_e32 v84, v84, v85
	ds_bpermute_b32 v85, v163, v84
	s_waitcnt lgkmcnt(0)
	v_add_f32_e32 v84, v84, v85
	v_fmamk_f32 v84, v84, 0x3a000000, v190
	v_cmp_gt_f32_e32 vcc, s72, v84
	v_mul_f32_e32 v85, 0x4f800000, v84
	s_nop 0
	v_cndmask_b32_e32 v84, v84, v85, vcc
	v_sqrt_f32_e32 v85, v84
	s_nop 0
	v_add_u32_e32 v86, -1, v85
	v_fma_f32 v87, -v86, v85, v84
	v_cmp_ge_f32_e64 s[0:1], 0, v87
	v_add_u32_e32 v87, 1, v85
	s_nop 0
	v_cndmask_b32_e64 v86, v85, v86, s[0:1]
	v_fma_f32 v85, -v87, v85, v84
	v_cmp_lt_f32_e64 s[0:1], 0, v85
	s_nop 1
	v_cndmask_b32_e64 v85, v86, v87, s[0:1]
	v_mul_f32_e32 v86, 0x37800000, v85
	v_cndmask_b32_e32 v85, v85, v86, vcc
	v_cmp_class_f32_e32 vcc, v84, v191
	s_nop 1
	v_cndmask_b32_e32 v84, v85, v84, vcc
	v_div_scale_f32 v85, s[0:1], v84, v84, 1.0
	v_rcp_f32_e32 v86, v85
	s_nop 0
	v_fma_f32 v87, -v85, v86, 1.0
	v_fmac_f32_e32 v86, v87, v86
	v_div_scale_f32 v87, vcc, 1.0, v84, 1.0
	v_mul_f32_e32 v88, v87, v86
	v_fma_f32 v89, -v85, v88, v87
	v_fmac_f32_e32 v88, v89, v86
	v_fma_f32 v85, -v85, v88, v87
	v_div_fmas_f32 v85, v85, v86, v88
	v_div_fixup_f32 v84, v85, v84, 1.0
	v_pk_mul_f32 v[78:79], v[78:79], v[84:85] op_sel_hi:[1,0]
	v_pk_mul_f32 v[74:75], v[74:75], v[84:85] op_sel_hi:[1,0]
	v_pk_mul_f32 v[80:81], v[80:81], v[84:85] op_sel_hi:[1,0]
	v_pk_mul_f32 v[76:77], v[76:77], v[84:85] op_sel_hi:[1,0]
	v_max_f32_e32 v78, 0, v78
	v_max_f32_e32 v74, 0, v74
	v_max_f32_e32 v79, 0, v79
	v_max_f32_e32 v75, 0, v75
	v_pk_mul_f32 v[78:79], v[78:79], v[78:79]
	v_pk_mul_f32 v[86:87], v[74:75], v[74:75]
	v_max_f32_e32 v74, 0, v80
	v_max_f32_e32 v76, 0, v76
	v_max_f32_e32 v75, 0, v81
	v_max_f32_e32 v77, 0, v77
	v_pk_mul_f32 v[80:81], v[74:75], v[74:75]
	v_pk_mul_f32 v[88:89], v[76:77], v[76:77]
	v_cvt_pk_bf16_f32 v74, v78, v79
	v_lshl_add_u64 v[78:79], s[92:93], 0, v[82:83]
	v_pk_mul_f32 v[66:67], v[66:67], v[84:85] op_sel_hi:[1,0]
	v_cvt_pk_bf16_f32 v75, v80, v81
	v_cvt_pk_bf16_f32 v76, v86, v87
	v_cvt_pk_bf16_f32 v77, v88, v89
	v_lshl_add_u64 v[78:79], v[78:79], 0, v[122:123]
	v_pk_mul_f32 v[72:73], v[72:73], v[84:85] op_sel_hi:[1,0]
	v_pk_mul_f32 v[70:71], v[70:71], v[84:85] op_sel_hi:[1,0]
	v_pk_mul_f32 v[68:69], v[68:69], v[84:85] op_sel_hi:[1,0]
	v_max_f32_e32 v66, 0, v66
	v_max_f32_e32 v67, 0, v67
	global_store_dwordx4 v[78:79], v[74:77], off
	v_max_f32_e32 v70, 0, v70
	v_max_f32_e32 v71, 0, v71
	v_pk_mul_f32 v[74:75], v[66:67], v[66:67]
	v_max_f32_e32 v66, 0, v72
	v_max_f32_e32 v68, 0, v68
	v_max_f32_e32 v67, 0, v73
	v_max_f32_e32 v69, 0, v69
	v_pk_mul_f32 v[70:71], v[70:71], v[70:71]
	v_pk_mul_f32 v[72:73], v[66:67], v[66:67]
	v_pk_mul_f32 v[76:77], v[68:69], v[68:69]
	v_cvt_pk_bf16_f32 v66, v70, v71
	v_cvt_pk_bf16_f32 v67, v72, v73
	v_cvt_pk_bf16_f32 v68, v74, v75
	v_cvt_pk_bf16_f32 v69, v76, v77
	global_store_dwordx4 v[78:79], v[66:69], off offset:256
	s_nop 1
	v_add_u32_e32 v66, 0x80, v158
	v_ashrrev_i32_e32 v67, 31, v66
	v_lshlrev_b64 v[68:69], 7, v[66:67]
	v_lshl_add_u64 v[68:69], v[152:153], 0, v[68:69]
	global_load_dwordx4 v[70:73], v[68:69], off
	global_load_dwordx4 v[74:77], v[68:69], off offset:16
	v_lshlrev_b64 v[66:67], 14, v[66:67]
	s_waitcnt vmcnt(1)
	v_mov_b32_e32 v68, v70
	s_waitcnt vmcnt(0)
	v_mov_b32_e32 v69, v74
	v_mov_b32_e32 v74, v71
	v_mov_b32_e32 v70, v72
	v_mov_b32_e32 v71, v76
	v_mov_b32_e32 v76, v73
	v_pk_add_f32 v[68:69], v[68:69], v[74:75]
	v_pk_add_f32 v[70:71], v[70:71], v[76:77]
	s_nop 0
	v_pk_add_f32 v[68:69], v[68:69], v[70:71]
	s_nop 0
	v_add_f32_e32 v68, v68, v69
	ds_bpermute_b32 v69, v162, v68
	s_waitcnt lgkmcnt(0)
	v_add_f32_e32 v68, v68, v69
	ds_bpermute_b32 v69, v163, v68
	s_waitcnt lgkmcnt(0)
	v_add_f32_e32 v68, v68, v69
	v_fmamk_f32 v68, v68, 0x3a000000, v190
	v_cmp_gt_f32_e32 vcc, s72, v68
	v_mul_f32_e32 v69, 0x4f800000, v68
	s_nop 0
	v_cndmask_b32_e32 v68, v68, v69, vcc
	v_sqrt_f32_e32 v69, v68
	s_nop 0
	v_add_u32_e32 v70, -1, v69
	v_fma_f32 v71, -v70, v69, v68
	v_cmp_ge_f32_e64 s[0:1], 0, v71
	v_add_u32_e32 v71, 1, v69
	s_nop 0
	v_cndmask_b32_e64 v70, v69, v70, s[0:1]
	v_fma_f32 v69, -v71, v69, v68
	v_cmp_lt_f32_e64 s[0:1], 0, v69
	s_nop 1
	v_cndmask_b32_e64 v69, v70, v71, s[0:1]
	v_mul_f32_e32 v70, 0x37800000, v69
	v_cndmask_b32_e32 v69, v69, v70, vcc
	v_cmp_class_f32_e32 vcc, v68, v191
	s_nop 1
	v_cndmask_b32_e32 v68, v69, v68, vcc
	v_div_scale_f32 v69, s[0:1], v68, v68, 1.0
	v_rcp_f32_e32 v70, v69
	s_nop 0
	v_fma_f32 v71, -v69, v70, 1.0
	v_fmac_f32_e32 v70, v71, v70
	v_div_scale_f32 v71, vcc, 1.0, v68, 1.0
	v_mul_f32_e32 v72, v71, v70
	v_fma_f32 v73, -v69, v72, v71
	v_fmac_f32_e32 v72, v73, v70
	v_fma_f32 v69, -v69, v72, v71
	v_div_fmas_f32 v69, v69, v70, v72
	v_div_fixup_f32 v68, v69, v68, 1.0
	v_pk_mul_f32 v[62:63], v[62:63], v[68:69] op_sel_hi:[1,0]
	v_pk_mul_f32 v[58:59], v[58:59], v[68:69] op_sel_hi:[1,0]
	v_pk_mul_f32 v[64:65], v[64:65], v[68:69] op_sel_hi:[1,0]
	v_pk_mul_f32 v[60:61], v[60:61], v[68:69] op_sel_hi:[1,0]
	v_max_f32_e32 v62, 0, v62
	v_max_f32_e32 v58, 0, v58
	v_max_f32_e32 v63, 0, v63
	v_max_f32_e32 v59, 0, v59
	v_pk_mul_f32 v[62:63], v[62:63], v[62:63]
	v_pk_mul_f32 v[70:71], v[58:59], v[58:59]
	v_max_f32_e32 v58, 0, v64
	v_max_f32_e32 v60, 0, v60
	v_max_f32_e32 v59, 0, v65
	v_max_f32_e32 v61, 0, v61
	v_pk_mul_f32 v[64:65], v[58:59], v[58:59]
	v_pk_mul_f32 v[72:73], v[60:61], v[60:61]
	v_cvt_pk_bf16_f32 v58, v62, v63
	v_lshl_add_u64 v[62:63], s[92:93], 0, v[66:67]
	v_pk_mul_f32 v[50:51], v[50:51], v[68:69] op_sel_hi:[1,0]
	v_cvt_pk_bf16_f32 v59, v64, v65
	v_cvt_pk_bf16_f32 v60, v70, v71
	v_cvt_pk_bf16_f32 v61, v72, v73
	v_lshl_add_u64 v[62:63], v[62:63], 0, v[122:123]
	v_pk_mul_f32 v[56:57], v[56:57], v[68:69] op_sel_hi:[1,0]
	v_pk_mul_f32 v[54:55], v[54:55], v[68:69] op_sel_hi:[1,0]
	v_pk_mul_f32 v[52:53], v[52:53], v[68:69] op_sel_hi:[1,0]
	v_max_f32_e32 v50, 0, v50
	v_max_f32_e32 v51, 0, v51
	global_store_dwordx4 v[62:63], v[58:61], off
	v_max_f32_e32 v54, 0, v54
	v_max_f32_e32 v55, 0, v55
	v_pk_mul_f32 v[58:59], v[50:51], v[50:51]
	v_max_f32_e32 v50, 0, v56
	v_max_f32_e32 v52, 0, v52
	v_max_f32_e32 v51, 0, v57
	v_max_f32_e32 v53, 0, v53
	v_pk_mul_f32 v[54:55], v[54:55], v[54:55]
	v_pk_mul_f32 v[56:57], v[50:51], v[50:51]
	v_pk_mul_f32 v[60:61], v[52:53], v[52:53]
	v_cvt_pk_bf16_f32 v50, v54, v55
	v_cvt_pk_bf16_f32 v51, v56, v57
	v_cvt_pk_bf16_f32 v52, v58, v59
	v_cvt_pk_bf16_f32 v53, v60, v61
	global_store_dwordx4 v[62:63], v[50:53], off offset:256
	s_nop 1
	v_add_u32_e32 v50, 0x90, v158
	v_ashrrev_i32_e32 v51, 31, v50
	v_lshlrev_b64 v[52:53], 7, v[50:51]
	v_lshl_add_u64 v[52:53], v[152:153], 0, v[52:53]
	global_load_dwordx4 v[54:57], v[52:53], off
	global_load_dwordx4 v[58:61], v[52:53], off offset:16
	v_lshlrev_b64 v[50:51], 14, v[50:51]
	s_waitcnt vmcnt(1)
; __device__ __forceinline__ unsigned cvt_pk_bf16(float lo, float hi) { const f32x2c_t v = {lo, hi}; const bf16x2c_t b = __builtin_convertvector(v, bf16x2c_t); return __builtin_bit_cast(unsigned, b); }
;     __device__ __forceinline__ void operator()(const f32x4 (&acc)[2][2][4][2], const Unit& u, int wr, int wc, int fr, int fq) const {
;     ...
;             for (int m = 0; m < 4; ++m) { const size_t row = (size_t)(row0 + ai * HALF + m * 16);
;                 const f32x4* sp = (const f32x4*)(SS + row * 32) + 2 * fq; float s;
;                 { const f32x4 t0 = sp[0], t1 = sp[1]; s = ((t0[0] + t0[1]) + (t0[2] + t0[3])) + ((t1[0] + t1[1]) + (t1[2] + t1[3])); }
;                 s += __shfl_xor(s, 16); s += __shfl_xor(s, 32);
;                 const float rstd = 1.0f / sqrtf(s * (1.0f / DM) + NORM_EPS);
; #pragma unroll
;                 for (int bj = 0; bj < 2; ++bj) { f32x4 v0 = acc[ai][bj][m][0] * rstd, v1 = acc[ai][bj][m][1] * rstd;
; #pragma unroll
;                     for (int e = 0; e < 4; ++e) { const float a = fmaxf(v0[e], 0.f), b = fmaxf(v1[e], 0.f); v0[e] = a * a; v1[e] = b * b; }
;                     u32x4 w; w.x = cvt_pk_bf16(v0[0], v0[1]); w.y = cvt_pk_bf16(v0[2], v0[3]); w.z = cvt_pk_bf16(v1[0], v1[1]); w.w = cvt_pk_bf16(v1[2], v1[3]);
;                     *(u32x4*)(H + row * DFF + col0 + bj * HALF) = w; } }
	v_mov_b32_e32 v52, v54
	s_waitcnt vmcnt(0)
	v_mov_b32_e32 v53, v58
	v_mov_b32_e32 v58, v55
	v_mov_b32_e32 v54, v56
	v_mov_b32_e32 v55, v60
	v_mov_b32_e32 v60, v57
	v_pk_add_f32 v[52:53], v[52:53], v[58:59]
	v_pk_add_f32 v[54:55], v[54:55], v[60:61]
	s_nop 0
	v_pk_add_f32 v[52:53], v[52:53], v[54:55]
	s_nop 0
	v_add_f32_e32 v52, v52, v53
	ds_bpermute_b32 v53, v162, v52
	s_waitcnt lgkmcnt(0)
	v_add_f32_e32 v52, v52, v53
	ds_bpermute_b32 v53, v163, v52
	s_waitcnt lgkmcnt(0)
	v_add_f32_e32 v52, v52, v53
	v_fmamk_f32 v52, v52, 0x3a000000, v190
	v_cmp_gt_f32_e32 vcc, s72, v52
	v_mul_f32_e32 v53, 0x4f800000, v52
	s_nop 0
	v_cndmask_b32_e32 v52, v52, v53, vcc
	v_sqrt_f32_e32 v53, v52
	s_nop 0
	v_add_u32_e32 v54, -1, v53
	v_fma_f32 v55, -v54, v53, v52
	v_cmp_ge_f32_e64 s[0:1], 0, v55
	v_add_u32_e32 v55, 1, v53
	s_nop 0
	v_cndmask_b32_e64 v54, v53, v54, s[0:1]
	v_fma_f32 v53, -v55, v53, v52
	v_cmp_lt_f32_e64 s[0:1], 0, v53
	s_nop 1
	v_cndmask_b32_e64 v53, v54, v55, s[0:1]
	v_mul_f32_e32 v54, 0x37800000, v53
	v_cndmask_b32_e32 v53, v53, v54, vcc
	v_cmp_class_f32_e32 vcc, v52, v191
	s_nop 1
	v_cndmask_b32_e32 v52, v53, v52, vcc
	v_div_scale_f32 v53, s[0:1], v52, v52, 1.0
	v_rcp_f32_e32 v54, v53
	s_nop 0
	v_fma_f32 v55, -v53, v54, 1.0
	v_fmac_f32_e32 v54, v55, v54
	v_div_scale_f32 v55, vcc, 1.0, v52, 1.0
	v_mul_f32_e32 v56, v55, v54
	v_fma_f32 v57, -v53, v56, v55
	v_fmac_f32_e32 v56, v57, v54
	v_fma_f32 v53, -v53, v56, v55
	v_div_fmas_f32 v53, v53, v54, v56
	v_div_fixup_f32 v52, v53, v52, 1.0
	v_pk_mul_f32 v[46:47], v[46:47], v[52:53] op_sel_hi:[1,0]
	v_pk_mul_f32 v[42:43], v[42:43], v[52:53] op_sel_hi:[1,0]
	v_pk_mul_f32 v[48:49], v[48:49], v[52:53] op_sel_hi:[1,0]
	v_pk_mul_f32 v[44:45], v[44:45], v[52:53] op_sel_hi:[1,0]
	v_max_f32_e32 v46, 0, v46
	v_max_f32_e32 v42, 0, v42
	v_max_f32_e32 v47, 0, v47
	v_max_f32_e32 v43, 0, v43
	v_pk_mul_f32 v[46:47], v[46:47], v[46:47]
	v_pk_mul_f32 v[54:55], v[42:43], v[42:43]
	v_max_f32_e32 v42, 0, v48
	v_max_f32_e32 v44, 0, v44
	v_max_f32_e32 v43, 0, v49
	v_max_f32_e32 v45, 0, v45
	v_pk_mul_f32 v[48:49], v[42:43], v[42:43]
	v_pk_mul_f32 v[56:57], v[44:45], v[44:45]
	v_cvt_pk_bf16_f32 v42, v46, v47
	v_lshl_add_u64 v[46:47], s[92:93], 0, v[50:51]
	v_pk_mul_f32 v[34:35], v[34:35], v[52:53] op_sel_hi:[1,0]
	v_cvt_pk_bf16_f32 v43, v48, v49
	v_cvt_pk_bf16_f32 v44, v54, v55
	v_cvt_pk_bf16_f32 v45, v56, v57
	v_lshl_add_u64 v[46:47], v[46:47], 0, v[122:123]
	v_pk_mul_f32 v[40:41], v[40:41], v[52:53] op_sel_hi:[1,0]
	v_pk_mul_f32 v[38:39], v[38:39], v[52:53] op_sel_hi:[1,0]
	v_pk_mul_f32 v[36:37], v[36:37], v[52:53] op_sel_hi:[1,0]
	v_max_f32_e32 v34, 0, v34
	v_max_f32_e32 v35, 0, v35
	global_store_dwordx4 v[46:47], v[42:45], off
	v_max_f32_e32 v38, 0, v38
	v_max_f32_e32 v39, 0, v39
	v_pk_mul_f32 v[42:43], v[34:35], v[34:35]
	v_max_f32_e32 v34, 0, v40
	v_max_f32_e32 v36, 0, v36
	v_max_f32_e32 v35, 0, v41
	v_max_f32_e32 v37, 0, v37
	v_pk_mul_f32 v[38:39], v[38:39], v[38:39]
	v_pk_mul_f32 v[40:41], v[34:35], v[34:35]
	v_pk_mul_f32 v[44:45], v[36:37], v[36:37]
	v_cvt_pk_bf16_f32 v34, v38, v39
	v_cvt_pk_bf16_f32 v35, v40, v41
	v_cvt_pk_bf16_f32 v36, v42, v43
	v_cvt_pk_bf16_f32 v37, v44, v45
	global_store_dwordx4 v[46:47], v[34:37], off offset:256
	s_nop 1
	v_add_u32_e32 v34, 0xa0, v158
	v_ashrrev_i32_e32 v35, 31, v34
	v_lshlrev_b64 v[36:37], 7, v[34:35]
	v_lshl_add_u64 v[36:37], v[152:153], 0, v[36:37]
	global_load_dwordx4 v[38:41], v[36:37], off
	global_load_dwordx4 v[42:45], v[36:37], off offset:16
	v_lshlrev_b64 v[34:35], 14, v[34:35]
	s_waitcnt vmcnt(1)
	v_mov_b32_e32 v36, v38
	s_waitcnt vmcnt(0)
	v_mov_b32_e32 v37, v42
	v_mov_b32_e32 v42, v39
	v_mov_b32_e32 v38, v40
	v_mov_b32_e32 v39, v44
	v_mov_b32_e32 v44, v41
	v_pk_add_f32 v[36:37], v[36:37], v[42:43]
	v_pk_add_f32 v[38:39], v[38:39], v[44:45]
	s_nop 0
	v_pk_add_f32 v[36:37], v[36:37], v[38:39]
	s_nop 0
	v_add_f32_e32 v36, v36, v37
	ds_bpermute_b32 v37, v162, v36
	s_waitcnt lgkmcnt(0)
	v_add_f32_e32 v36, v36, v37
	ds_bpermute_b32 v37, v163, v36
	s_waitcnt lgkmcnt(0)
; __device__ __forceinline__ unsigned cvt_pk_bf16(float lo, float hi) { const f32x2c_t v = {lo, hi}; const bf16x2c_t b = __builtin_convertvector(v, bf16x2c_t); return __builtin_bit_cast(unsigned, b); }
; #define PG8_BAR __builtin_amdgcn_s_barrier()
;     __device__ __forceinline__ void operator()(const f32x4 (&acc)[2][2][4][2], const Unit& u, int wr, int wc, int fr, int fq) const {
;     ...
;             for (int m = 0; m < 4; ++m) { const size_t row = (size_t)(row0 + ai * HALF + m * 16);
;                 const f32x4* sp = (const f32x4*)(SS + row * 32) + 2 * fq; float s;
;                 { const f32x4 t0 = sp[0], t1 = sp[1]; s = ((t0[0] + t0[1]) + (t0[2] + t0[3])) + ((t1[0] + t1[1]) + (t1[2] + t1[3])); }
;                 s += __shfl_xor(s, 16); s += __shfl_xor(s, 32);
;                 const float rstd = 1.0f / sqrtf(s * (1.0f / DM) + NORM_EPS);
; #pragma unroll
;                 for (int bj = 0; bj < 2; ++bj) { f32x4 v0 = acc[ai][bj][m][0] * rstd, v1 = acc[ai][bj][m][1] * rstd;
; #pragma unroll
;                     for (int e = 0; e < 4; ++e) { const float a = fmaxf(v0[e], 0.f), b = fmaxf(v1[e], 0.f); v0[e] = a * a; v1[e] = b * b; }
;                     u32x4 w; w.x = cvt_pk_bf16(v0[0], v0[1]); w.y = cvt_pk_bf16(v0[2], v0[3]); w.z = cvt_pk_bf16(v1[0], v1[1]); w.w = cvt_pk_bf16(v1[2], v1[3]);
;                     *(u32x4*)(H + row * DFF + col0 + bj * HALF) = w; } }
; template <class Epi, class Sched, bool ALIGN_EPI = false, bool SP2 = false>
; __device__ __forceinline__ void gemm_phase(PG8_LAS unsigned char* lds, const Gemm g, const Sched& S, const Epi& E) {
;     ...
;         if (!has_next) break;
;     ...
;         if constexpr (ALIGN_EPI) { if (wr == 1) PG8_BAR; }
	v_add_f32_e32 v36, v36, v37
	v_fmamk_f32 v36, v36, 0x3a000000, v190
	v_cmp_gt_f32_e32 vcc, s72, v36
	v_mul_f32_e32 v37, 0x4f800000, v36
	s_nop 0
	v_cndmask_b32_e32 v36, v36, v37, vcc
	v_sqrt_f32_e32 v37, v36
	s_nop 0
	v_add_u32_e32 v38, -1, v37
	v_fma_f32 v39, -v38, v37, v36
	v_cmp_ge_f32_e64 s[0:1], 0, v39
	v_add_u32_e32 v39, 1, v37
	s_nop 0
	v_cndmask_b32_e64 v38, v37, v38, s[0:1]
	v_fma_f32 v37, -v39, v37, v36
	v_cmp_lt_f32_e64 s[0:1], 0, v37
	s_nop 1
	v_cndmask_b32_e64 v37, v38, v39, s[0:1]
	v_mul_f32_e32 v38, 0x37800000, v37
	v_cndmask_b32_e32 v37, v37, v38, vcc
	v_cmp_class_f32_e32 vcc, v36, v191
	s_nop 1
	v_cndmask_b32_e32 v36, v37, v36, vcc
	v_div_scale_f32 v37, s[0:1], v36, v36, 1.0
	v_rcp_f32_e32 v38, v37
	s_nop 0
	v_fma_f32 v39, -v37, v38, 1.0
	v_fmac_f32_e32 v38, v39, v38
	v_div_scale_f32 v39, vcc, 1.0, v36, 1.0
	v_mul_f32_e32 v40, v39, v38
	v_fma_f32 v41, -v37, v40, v39
	v_fmac_f32_e32 v40, v41, v38
	v_fma_f32 v37, -v37, v40, v39
	v_div_fmas_f32 v37, v37, v38, v40
	v_div_fixup_f32 v36, v37, v36, 1.0
	v_pk_mul_f32 v[30:31], v[30:31], v[36:37] op_sel_hi:[1,0]
	v_pk_mul_f32 v[26:27], v[26:27], v[36:37] op_sel_hi:[1,0]
	v_pk_mul_f32 v[32:33], v[32:33], v[36:37] op_sel_hi:[1,0]
	v_pk_mul_f32 v[28:29], v[28:29], v[36:37] op_sel_hi:[1,0]
	v_max_f32_e32 v30, 0, v30
	v_max_f32_e32 v26, 0, v26
	v_max_f32_e32 v31, 0, v31
	v_max_f32_e32 v27, 0, v27
	v_pk_mul_f32 v[30:31], v[30:31], v[30:31]
	v_pk_mul_f32 v[38:39], v[26:27], v[26:27]
	v_max_f32_e32 v26, 0, v32
	v_max_f32_e32 v28, 0, v28
	v_max_f32_e32 v27, 0, v33
	v_max_f32_e32 v29, 0, v29
	v_pk_mul_f32 v[32:33], v[26:27], v[26:27]
	v_pk_mul_f32 v[40:41], v[28:29], v[28:29]
	v_cvt_pk_bf16_f32 v26, v30, v31
	v_lshl_add_u64 v[30:31], s[92:93], 0, v[34:35]
	v_pk_mul_f32 v[18:19], v[18:19], v[36:37] op_sel_hi:[1,0]
	v_cvt_pk_bf16_f32 v27, v32, v33
	v_cvt_pk_bf16_f32 v28, v38, v39
	v_cvt_pk_bf16_f32 v29, v40, v41
	v_lshl_add_u64 v[30:31], v[30:31], 0, v[122:123]
	v_pk_mul_f32 v[24:25], v[24:25], v[36:37] op_sel_hi:[1,0]
	v_pk_mul_f32 v[22:23], v[22:23], v[36:37] op_sel_hi:[1,0]
	v_pk_mul_f32 v[20:21], v[20:21], v[36:37] op_sel_hi:[1,0]
	v_max_f32_e32 v18, 0, v18
	v_max_f32_e32 v19, 0, v19
	global_store_dwordx4 v[30:31], v[26:29], off
	v_max_f32_e32 v22, 0, v22
	v_max_f32_e32 v23, 0, v23
	v_pk_mul_f32 v[26:27], v[18:19], v[18:19]
	v_max_f32_e32 v18, 0, v24
	v_max_f32_e32 v20, 0, v20
	v_max_f32_e32 v19, 0, v25
	v_max_f32_e32 v21, 0, v21
	v_pk_mul_f32 v[22:23], v[22:23], v[22:23]
	v_pk_mul_f32 v[24:25], v[18:19], v[18:19]
	v_pk_mul_f32 v[28:29], v[20:21], v[20:21]
	v_cvt_pk_bf16_f32 v18, v22, v23
	v_cvt_pk_bf16_f32 v19, v24, v25
	v_cvt_pk_bf16_f32 v20, v26, v27
	v_cvt_pk_bf16_f32 v21, v28, v29
	global_store_dwordx4 v[30:31], v[18:21], off offset:256
	s_nop 1
	v_add_u32_e32 v18, 0xb0, v158
	v_ashrrev_i32_e32 v19, 31, v18
	v_lshlrev_b64 v[20:21], 7, v[18:19]
	v_lshl_add_u64 v[20:21], v[152:153], 0, v[20:21]
	global_load_dwordx4 v[22:25], v[20:21], off
	global_load_dwordx4 v[26:29], v[20:21], off offset:16
	v_lshlrev_b64 v[18:19], 14, v[18:19]
	s_waitcnt vmcnt(1)
	v_mov_b32_e32 v20, v22
	s_waitcnt vmcnt(0)
	v_mov_b32_e32 v21, v26
	v_mov_b32_e32 v26, v23
	v_mov_b32_e32 v22, v24
	v_mov_b32_e32 v23, v28
	v_mov_b32_e32 v28, v25
	v_pk_add_f32 v[20:21], v[20:21], v[26:27]
	v_pk_add_f32 v[22:23], v[22:23], v[28:29]
	s_nop 0
	v_pk_add_f32 v[20:21], v[20:21], v[22:23]
	s_nop 0
	v_add_f32_e32 v20, v20, v21
	ds_bpermute_b32 v21, v162, v20
	s_waitcnt lgkmcnt(0)
	v_add_f32_e32 v20, v20, v21
	ds_bpermute_b32 v21, v163, v20
	s_waitcnt lgkmcnt(0)
	v_add_f32_e32 v20, v20, v21
	v_fmamk_f32 v20, v20, 0x3a000000, v190
	v_cmp_gt_f32_e32 vcc, s72, v20
	v_mul_f32_e32 v21, 0x4f800000, v20
	s_nop 0
	v_cndmask_b32_e32 v20, v20, v21, vcc
	v_sqrt_f32_e32 v21, v20
	s_nop 0
	v_add_u32_e32 v22, -1, v21
	v_fma_f32 v23, -v22, v21, v20
	v_cmp_ge_f32_e64 s[0:1], 0, v23
	v_add_u32_e32 v23, 1, v21
	s_nop 0
	v_cndmask_b32_e64 v22, v21, v22, s[0:1]
	v_fma_f32 v21, -v23, v21, v20
	v_cmp_lt_f32_e64 s[0:1], 0, v21
	s_nop 1
	v_cndmask_b32_e64 v21, v22, v23, s[0:1]
	v_mul_f32_e32 v22, 0x37800000, v21
	v_cndmask_b32_e32 v21, v21, v22, vcc
	v_cmp_class_f32_e32 vcc, v20, v191
	s_nop 1
	v_cndmask_b32_e32 v20, v21, v20, vcc
	v_div_scale_f32 v21, s[0:1], v20, v20, 1.0
	v_rcp_f32_e32 v22, v21
	s_mov_b64 s[0:1], -1
	v_fma_f32 v23, -v21, v22, 1.0
	v_fmac_f32_e32 v22, v23, v22
	v_div_scale_f32 v23, vcc, 1.0, v20, 1.0
	v_mul_f32_e32 v24, v23, v22
	v_fma_f32 v25, -v21, v24, v23
	v_fmac_f32_e32 v24, v25, v22
	v_fma_f32 v21, -v21, v24, v23
	v_div_fmas_f32 v21, v21, v22, v24
	v_div_fixup_f32 v20, v21, v20, 1.0
	v_pk_mul_f32 v[14:15], v[14:15], v[20:21] op_sel_hi:[1,0]
	v_pk_mul_f32 v[10:11], v[10:11], v[20:21] op_sel_hi:[1,0]
	v_pk_mul_f32 v[16:17], v[16:17], v[20:21] op_sel_hi:[1,0]
	v_pk_mul_f32 v[12:13], v[12:13], v[20:21] op_sel_hi:[1,0]
	v_max_f32_e32 v14, 0, v14
	v_max_f32_e32 v10, 0, v10
	v_max_f32_e32 v15, 0, v15
	v_max_f32_e32 v11, 0, v11
	v_pk_mul_f32 v[14:15], v[14:15], v[14:15]
	v_pk_mul_f32 v[22:23], v[10:11], v[10:11]
	v_max_f32_e32 v10, 0, v16
	v_max_f32_e32 v12, 0, v12
	v_max_f32_e32 v11, 0, v17
	v_max_f32_e32 v13, 0, v13
	v_pk_mul_f32 v[16:17], v[10:11], v[10:11]
	v_pk_mul_f32 v[24:25], v[12:13], v[12:13]
	v_cvt_pk_bf16_f32 v10, v14, v15
	v_lshl_add_u64 v[14:15], s[92:93], 0, v[18:19]
	v_pk_mul_f32 v[2:3], v[2:3], v[20:21] op_sel_hi:[1,0]
	v_cvt_pk_bf16_f32 v11, v16, v17
	v_cvt_pk_bf16_f32 v12, v22, v23
	v_cvt_pk_bf16_f32 v13, v24, v25
	v_lshl_add_u64 v[14:15], v[14:15], 0, v[122:123]
	v_pk_mul_f32 v[8:9], v[8:9], v[20:21] op_sel_hi:[1,0]
	v_pk_mul_f32 v[6:7], v[6:7], v[20:21] op_sel_hi:[1,0]
	v_pk_mul_f32 v[4:5], v[4:5], v[20:21] op_sel_hi:[1,0]
	v_max_f32_e32 v2, 0, v2
	v_max_f32_e32 v3, 0, v3
	global_store_dwordx4 v[14:15], v[10:13], off
	v_max_f32_e32 v6, 0, v6
	v_max_f32_e32 v7, 0, v7
	v_pk_mul_f32 v[10:11], v[2:3], v[2:3]
	v_max_f32_e32 v2, 0, v8
	v_max_f32_e32 v4, 0, v4
	v_max_f32_e32 v3, 0, v9
	v_max_f32_e32 v5, 0, v5
	v_pk_mul_f32 v[6:7], v[6:7], v[6:7]
	v_pk_mul_f32 v[8:9], v[2:3], v[2:3]
	v_pk_mul_f32 v[12:13], v[4:5], v[4:5]
	v_cvt_pk_bf16_f32 v2, v6, v7
	v_cvt_pk_bf16_f32 v3, v8, v9
	v_cvt_pk_bf16_f32 v4, v10, v11
	v_cvt_pk_bf16_f32 v5, v12, v13
	s_andn2_b64 vcc, exec, s[40:41]
	global_store_dwordx4 v[14:15], v[2:5], off offset:256
	s_cbranch_vccnz .LBB0_68
	s_andn2_b64 vcc, exec, s[12:13]
	s_cbranch_vccnz .LBB0_67
	s_nop 0
	s_branch .LBB0_67

; #define PG8_STAGE(bufoff, gbase, voff) do { _Pragma("unroll") for (int _i = 0; _i < 2; ++_i) \
;         __builtin_amdgcn_global_load_lds((const unsigned*)((const char*)(gbase) + (voff)[_i]), (PG8_LAS unsigned*)(lds + (bufoff) + ldsw + _i * 8192), 16, 0, 0); } while (0)
; #define PG8_LDA(dst, b, h) do { _Pragma("unroll") for (int m = 0; m < 4; ++m) _Pragma("unroll") for (int k = 0; k < 2; ++k) dst[m][k] = *(const PG8_LAS bf16x8*)(lds + PG8_SA(b, h) + aoff + m * 2048 + k * 1024); } while (0)
; #define PG8_LDB(dst, b, h) do { _Pragma("unroll") for (int n = 0; n < 2; ++n) _Pragma("unroll") for (int k = 0; k < 2; ++k) dst[n][k] = *(const PG8_LAS bf16x8*)(lds + PG8_SB(b, h) + boff + n * 2048 + k * 1024); } while (0)
; #define PG8_MMA(ai, bj, At, Bt) do { __builtin_amdgcn_s_setprio(1); _Pragma("unroll") for (int m = 0; m < 4; ++m) _Pragma("unroll") for (int n = 0; n < 2; ++n) _Pragma("unroll") for (int k = 0; k < 2; ++k) \
;         acc[ai][bj][m][n] = __builtin_amdgcn_mfma_f32_16x16x32_bf16(Bt[n][k], At[m][k], acc[ai][bj][m][n], 0, 0, 0); __builtin_amdgcn_s_setprio(0); } while (0)
; #define PG8_WAIT_V(n) asm volatile("s_waitcnt vmcnt(" #n ")" ::: "memory")
; #define PG8_WAIT_L(n) asm volatile("s_waitcnt lgkmcnt(" #n ")" ::: "memory")
; #define PG8_BAR __builtin_amdgcn_s_barrier()
; #define PG8_SCHED __builtin_amdgcn_sched_barrier(0)
; template <class Epi, class Sched, bool ALIGN_EPI = false, bool SP2 = false>
; __device__ __forceinline__ void gemm_phase(PG8_LAS unsigned char* lds, const Gemm g, const Sched& S, const Epi& E) {
;     ...
;             PG8_LDB(B0, 0, 0); PG8_LDB(B1, 0, 1); PG8_SCHED; PG8_LDA(At, 0, 0); PG8_STAGE(PG8_SA(1, 1), a1 + hstep, voffA);
;             PG8_WAIT_V(8); PG8_WAIT_L(0); PG8_BAR; PG8_MMA(0, 0, At, B0); PG8_MMA(0, 1, At, B1); PG8_BAR; PG8_SCHED;
;             PG8_LDA(At, 0, 1); PG8_STAGE(PG8_SB(0, 0), b2, voffB); PG8_STAGE(PG8_SB(0, 1), b2 + hstep, voffB); PG8_STAGE(PG8_SA(0, 0), a2, voffA);
;             PG8_WAIT_V(8); PG8_WAIT_L(0); PG8_BAR; PG8_MMA(1, 0, At, B0); PG8_MMA(1, 1, At, B1); PG8_BAR; PG8_SCHED;
.LBB0_98:
	s_add_u32 s40, vcc_lo, 0xfff80080
	s_addc_u32 s41, vcc_hi, -1
	s_add_i32 s47, 0, 0x10000
	s_cmp_eq_u32 s46, 28
	s_cselect_b32 s59, s97, s41
	s_cselect_b32 s58, s84, s40
	s_cselect_b32 s41, s85, s79
	s_cselect_b32 s40, s95, s78
	s_add_i32 s80, 0, 0x14000
	v_add_u32_e32 v170, s47, v143
	v_add_u32_e32 v186, s80, v143
	ds_read_b128 v[156:159], v170
	ds_read_b128 v[162:165], v170 offset:1024
	ds_read_b128 v[166:169], v170 offset:2048
	ds_read_b128 v[170:173], v170 offset:3072
	ds_read_b128 v[174:177], v186
	ds_read_b128 v[178:181], v186 offset:1024
	ds_read_b128 v[182:185], v186 offset:2048
	ds_read_b128 v[204:207], v186 offset:3072
	v_lshl_add_u64 v[186:187], vcc, 0, v[152:153]
	s_add_i32 m0, s5, 0xc000
	ds_read_b128 v[208:211], v161
	ds_read_b128 v[212:215], v161 offset:1024
	ds_read_b128 v[216:219], v161 offset:2048
	ds_read_b128 v[220:223], v161 offset:3072
	ds_read_b128 v[224:227], v161 offset:4096
	ds_read_b128 v[228:231], v161 offset:5120
	ds_read_b128 v[232:235], v161 offset:6144
	ds_read_b128 v[236:239], v161 offset:7168
	global_load_lds_dwordx4 v[186:187], off
	v_lshl_add_u64 v[186:187], vcc, 0, v[154:155]
	s_add_i32 m0, s5, 0xe000
	s_nop 0
	global_load_lds_dwordx4 v[186:187], off
	s_nop 0
	s_waitcnt vmcnt(8)
	s_waitcnt lgkmcnt(0)
	s_setprio 1
	s_barrier
	v_mfma_f32_16x16x32_bf16 v[126:129], v[156:159], v[208:211], v[126:129]
	v_mfma_f32_16x16x32_bf16 v[122:125], v[166:169], v[208:211], v[122:125]
	v_mfma_f32_16x16x32_bf16 v[110:113], v[156:159], v[216:219], v[110:113]
	v_mfma_f32_16x16x32_bf16 v[106:109], v[166:169], v[216:219], v[106:109]
	v_mfma_f32_16x16x32_bf16 v[94:97], v[156:159], v[224:227], v[94:97]
	v_mfma_f32_16x16x32_bf16 v[90:93], v[166:169], v[224:227], v[90:93]
	v_mfma_f32_16x16x32_bf16 v[78:81], v[156:159], v[232:235], v[78:81]
	v_mfma_f32_16x16x32_bf16 v[74:77], v[166:169], v[232:235], v[74:77]
	s_setprio 0
	s_setprio 1
	v_mfma_f32_16x16x32_bf16 v[126:129], v[162:165], v[212:215], v[126:129]
	v_mfma_f32_16x16x32_bf16 v[122:125], v[170:173], v[212:215], v[122:125]
	v_mfma_f32_16x16x32_bf16 v[110:113], v[162:165], v[220:223], v[110:113]
	v_mfma_f32_16x16x32_bf16 v[106:109], v[170:173], v[220:223], v[106:109]
	v_mfma_f32_16x16x32_bf16 v[94:97], v[162:165], v[228:231], v[94:97]
	v_mfma_f32_16x16x32_bf16 v[90:93], v[170:173], v[228:231], v[90:93]
	v_mfma_f32_16x16x32_bf16 v[78:81], v[162:165], v[236:239], v[78:81]
	v_mfma_f32_16x16x32_bf16 v[74:77], v[170:173], v[236:239], v[74:77]
	s_setprio 0
	s_setprio 1
	v_mfma_f32_16x16x32_bf16 v[118:121], v[174:177], v[208:211], v[118:121]
	v_mfma_f32_16x16x32_bf16 v[114:117], v[182:185], v[208:211], v[114:117]
	v_mfma_f32_16x16x32_bf16 v[102:105], v[174:177], v[216:219], v[102:105]
	v_mfma_f32_16x16x32_bf16 v[98:101], v[182:185], v[216:219], v[98:101]
	v_mfma_f32_16x16x32_bf16 v[86:89], v[174:177], v[224:227], v[86:89]
	v_mfma_f32_16x16x32_bf16 v[82:85], v[182:185], v[224:227], v[82:85]
	v_mfma_f32_16x16x32_bf16 v[70:73], v[174:177], v[232:235], v[70:73]
	v_mfma_f32_16x16x32_bf16 v[66:69], v[182:185], v[232:235], v[66:69]
	s_setprio 0
	s_setprio 1
	v_mfma_f32_16x16x32_bf16 v[118:121], v[178:181], v[212:215], v[118:121]
	v_mfma_f32_16x16x32_bf16 v[114:117], v[204:207], v[212:215], v[114:117]
	v_mfma_f32_16x16x32_bf16 v[102:105], v[178:181], v[220:223], v[102:105]
	v_mfma_f32_16x16x32_bf16 v[98:101], v[204:207], v[220:223], v[98:101]
	v_mfma_f32_16x16x32_bf16 v[86:89], v[178:181], v[228:231], v[86:89]
	v_mfma_f32_16x16x32_bf16 v[82:85], v[204:207], v[228:231], v[82:85]
	v_mfma_f32_16x16x32_bf16 v[70:73], v[178:181], v[236:239], v[70:73]
	v_mfma_f32_16x16x32_bf16 v[66:69], v[204:207], v[236:239], v[66:69]
	s_setprio 0
	s_barrier
	s_add_i32 s47, s47, s4
	v_lshl_add_u64 v[186:187], s[40:41], 0, v[148:149]
	s_mov_b32 m0, s47
	ds_read_b128 v[208:211], v161 offset:16384
	ds_read_b128 v[212:215], v161 offset:17408
	ds_read_b128 v[216:219], v161 offset:18432
	ds_read_b128 v[220:223], v161 offset:19456
	ds_read_b128 v[224:227], v161 offset:20480
	ds_read_b128 v[228:231], v161 offset:21504
	ds_read_b128 v[232:235], v161 offset:22528
	ds_read_b128 v[236:239], v161 offset:23552
	global_load_lds_dwordx4 v[186:187], off
	s_add_i32 m0, s47, 0x2000
	s_add_u32 s76, s40, 0x80000
	v_lshl_add_u64 v[240:241], s[40:41], 0, v[144:145]
	s_addc_u32 s77, s41, 0
	s_add_i32 s47, s80, s4
	global_load_lds_dwordx4 v[240:241], off
	v_lshl_add_u64 v[242:243], s[76:77], 0, v[148:149]
	s_mov_b32 m0, s47
	v_lshl_add_u64 v[244:245], s[58:59], 0, v[146:147]
	global_load_lds_dwordx4 v[242:243], off
	v_lshl_add_u64 v[242:243], s[76:77], 0, v[144:145]
	s_add_i32 m0, s47, 0x2000
	s_nop 0
	global_load_lds_dwordx4 v[242:243], off
	v_lshl_add_u64 v[242:243], s[58:59], 0, v[150:151]
	s_mov_b32 m0, s5
	s_nop 0
	global_load_lds_dwordx4 v[242:243], off
	s_mov_b32 m0, s30
	s_nop 0
	global_load_lds_dwordx4 v[244:245], off
	s_waitcnt vmcnt(8)
	s_waitcnt lgkmcnt(0)
	s_setprio 1
	s_barrier
; #define PG8_STAGE(bufoff, gbase, voff) do { _Pragma("unroll") for (int _i = 0; _i < 2; ++_i) \
;         __builtin_amdgcn_global_load_lds((const unsigned*)((const char*)(gbase) + (voff)[_i]), (PG8_LAS unsigned*)(lds + (bufoff) + ldsw + _i * 8192), 16, 0, 0); } while (0)
; #define PG8_LDA(dst, b, h) do { _Pragma("unroll") for (int m = 0; m < 4; ++m) _Pragma("unroll") for (int k = 0; k < 2; ++k) dst[m][k] = *(const PG8_LAS bf16x8*)(lds + PG8_SA(b, h) + aoff + m * 2048 + k * 1024); } while (0)
; #define PG8_LDB(dst, b, h) do { _Pragma("unroll") for (int n = 0; n < 2; ++n) _Pragma("unroll") for (int k = 0; k < 2; ++k) dst[n][k] = *(const PG8_LAS bf16x8*)(lds + PG8_SB(b, h) + boff + n * 2048 + k * 1024); } while (0)
; #define PG8_MMA(ai, bj, At, Bt) do { __builtin_amdgcn_s_setprio(1); _Pragma("unroll") for (int m = 0; m < 4; ++m) _Pragma("unroll") for (int n = 0; n < 2; ++n) _Pragma("unroll") for (int k = 0; k < 2; ++k) \
;         acc[ai][bj][m][n] = __builtin_amdgcn_mfma_f32_16x16x32_bf16(Bt[n][k], At[m][k], acc[ai][bj][m][n], 0, 0, 0); __builtin_amdgcn_s_setprio(0); } while (0)
; #define PG8_WAIT_V(n) asm volatile("s_waitcnt vmcnt(" #n ")" ::: "memory")
; #define PG8_WAIT_L(n) asm volatile("s_waitcnt lgkmcnt(" #n ")" ::: "memory")
; #define PG8_BAR __builtin_amdgcn_s_barrier()
; #define PG8_SCHED __builtin_amdgcn_sched_barrier(0)
; template <class Epi, class Sched, bool ALIGN_EPI = false, bool SP2 = false>
; __device__ __forceinline__ void gemm_phase(PG8_LAS unsigned char* lds, const Gemm g, const Sched& S, const Epi& E) {
;     ...
;             PG8_WAIT_V(8); PG8_WAIT_L(0); PG8_BAR; PG8_MMA(1, 0, At, B0); PG8_MMA(1, 1, At, B1); PG8_BAR; PG8_SCHED;
;             PG8_LDB(B0, 1, 0); PG8_LDB(B1, 1, 1); PG8_SCHED; PG8_LDA(At, 1, 0); PG8_STAGE(PG8_SA(0, 1), a2 + hstep, voffA);
;             PG8_WAIT_V(8); PG8_WAIT_L(0); PG8_BAR; PG8_MMA(0, 0, At, B0); PG8_MMA(0, 1, At, B1); PG8_BAR; PG8_SCHED;
	v_mfma_f32_16x16x32_bf16 v[62:65], v[156:159], v[208:211], v[62:65]
	v_mfma_f32_16x16x32_bf16 v[58:61], v[166:169], v[208:211], v[58:61]
	v_mfma_f32_16x16x32_bf16 v[46:49], v[156:159], v[216:219], v[46:49]
	v_mfma_f32_16x16x32_bf16 v[42:45], v[166:169], v[216:219], v[42:45]
	v_mfma_f32_16x16x32_bf16 v[30:33], v[156:159], v[224:227], v[30:33]
	v_mfma_f32_16x16x32_bf16 v[26:29], v[166:169], v[224:227], v[26:29]
	v_mfma_f32_16x16x32_bf16 v[14:17], v[156:159], v[232:235], v[14:17]
	v_mfma_f32_16x16x32_bf16 v[10:13], v[166:169], v[232:235], v[10:13]
	v_mfma_f32_16x16x32_bf16 v[62:65], v[162:165], v[212:215], v[62:65]
	v_mfma_f32_16x16x32_bf16 v[58:61], v[170:173], v[212:215], v[58:61]
	v_mfma_f32_16x16x32_bf16 v[46:49], v[162:165], v[220:223], v[46:49]
	v_mfma_f32_16x16x32_bf16 v[42:45], v[170:173], v[220:223], v[42:45]
	v_mfma_f32_16x16x32_bf16 v[30:33], v[162:165], v[228:231], v[30:33]
	v_mfma_f32_16x16x32_bf16 v[26:29], v[170:173], v[228:231], v[26:29]
	v_mfma_f32_16x16x32_bf16 v[14:17], v[162:165], v[236:239], v[14:17]
	v_mfma_f32_16x16x32_bf16 v[10:13], v[170:173], v[236:239], v[10:13]
	v_mfma_f32_16x16x32_bf16 v[54:57], v[174:177], v[208:211], v[54:57]
	v_mfma_f32_16x16x32_bf16 v[50:53], v[182:185], v[208:211], v[50:53]
	v_mfma_f32_16x16x32_bf16 v[38:41], v[174:177], v[216:219], v[38:41]
	v_mfma_f32_16x16x32_bf16 v[34:37], v[182:185], v[216:219], v[34:37]
	v_mfma_f32_16x16x32_bf16 v[22:25], v[174:177], v[224:227], v[22:25]
	v_mfma_f32_16x16x32_bf16 v[18:21], v[182:185], v[224:227], v[18:21]
	v_mfma_f32_16x16x32_bf16 v[6:9], v[174:177], v[232:235], v[6:9]
	v_mfma_f32_16x16x32_bf16 v[2:5], v[182:185], v[232:235], v[2:5]
	v_mfma_f32_16x16x32_bf16 v[54:57], v[178:181], v[212:215], v[54:57]
	v_mfma_f32_16x16x32_bf16 v[50:53], v[204:207], v[212:215], v[50:53]
	v_mfma_f32_16x16x32_bf16 v[38:41], v[178:181], v[220:223], v[38:41]
	v_mfma_f32_16x16x32_bf16 v[34:37], v[204:207], v[220:223], v[34:37]
	v_mfma_f32_16x16x32_bf16 v[22:25], v[178:181], v[228:231], v[22:25]
	v_mfma_f32_16x16x32_bf16 v[18:21], v[204:207], v[228:231], v[18:21]
	v_mfma_f32_16x16x32_bf16 v[6:9], v[178:181], v[236:239], v[6:9]
	v_mfma_f32_16x16x32_bf16 v[2:5], v[204:207], v[236:239], v[2:5]
	s_setprio 0
	s_barrier
	s_add_i32 s47, 0, 0x18000
	s_add_i32 s76, 0, 0x1c000
	v_add_u32_e32 v170, s47, v143
	v_add_u32_e32 v203, s76, v143
	ds_read_b128 v[156:159], v170
	ds_read_b128 v[162:165], v170 offset:1024
	ds_read_b128 v[166:169], v170 offset:2048
	ds_read_b128 v[170:173], v170 offset:3072
	ds_read_b128 v[174:177], v203
	ds_read_b128 v[178:181], v203 offset:1024
	ds_read_b128 v[182:185], v203 offset:2048
	ds_read_b128 v[204:207], v203 offset:3072
	s_add_u32 s58, s58, 0x80000
	s_addc_u32 s59, s59, 0
	s_mov_b32 m0, s34
	v_lshl_add_u64 v[246:247], s[58:59], 0, v[150:151]
	ds_read_b128 v[208:211], v161 offset:32768
	ds_read_b128 v[212:215], v161 offset:33792
	ds_read_b128 v[216:219], v161 offset:34816
	ds_read_b128 v[220:223], v161 offset:35840
	ds_read_b128 v[224:227], v161 offset:36864
	ds_read_b128 v[228:231], v161 offset:37888
	ds_read_b128 v[232:235], v161 offset:38912
	ds_read_b128 v[236:239], v161 offset:39936
	global_load_lds_dwordx4 v[246:247], off
	v_lshl_add_u64 v[246:247], s[58:59], 0, v[146:147]
	s_mov_b32 m0, s57
	s_nop 0
	global_load_lds_dwordx4 v[246:247], off
	s_waitcnt vmcnt(8)
	s_waitcnt lgkmcnt(0)
	s_setprio 1
	s_barrier
	v_mfma_f32_16x16x32_bf16 v[126:129], v[156:159], v[208:211], v[126:129]
	v_mfma_f32_16x16x32_bf16 v[122:125], v[166:169], v[208:211], v[122:125]
	v_mfma_f32_16x16x32_bf16 v[110:113], v[156:159], v[216:219], v[110:113]
	v_mfma_f32_16x16x32_bf16 v[106:109], v[166:169], v[216:219], v[106:109]
	v_mfma_f32_16x16x32_bf16 v[94:97], v[156:159], v[224:227], v[94:97]
	v_mfma_f32_16x16x32_bf16 v[90:93], v[166:169], v[224:227], v[90:93]
	v_mfma_f32_16x16x32_bf16 v[78:81], v[156:159], v[232:235], v[78:81]
	v_mfma_f32_16x16x32_bf16 v[74:77], v[166:169], v[232:235], v[74:77]
	s_setprio 0
	s_setprio 1
	v_mfma_f32_16x16x32_bf16 v[126:129], v[162:165], v[212:215], v[126:129]
	v_mfma_f32_16x16x32_bf16 v[122:125], v[170:173], v[212:215], v[122:125]
	v_mfma_f32_16x16x32_bf16 v[110:113], v[162:165], v[220:223], v[110:113]
	v_mfma_f32_16x16x32_bf16 v[106:109], v[170:173], v[220:223], v[106:109]
	v_mfma_f32_16x16x32_bf16 v[94:97], v[162:165], v[228:231], v[94:97]
	v_mfma_f32_16x16x32_bf16 v[90:93], v[170:173], v[228:231], v[90:93]
	v_mfma_f32_16x16x32_bf16 v[78:81], v[162:165], v[236:239], v[78:81]
	v_mfma_f32_16x16x32_bf16 v[74:77], v[170:173], v[236:239], v[74:77]
	s_setprio 0
	s_setprio 1
	v_mfma_f32_16x16x32_bf16 v[118:121], v[174:177], v[208:211], v[118:121]
	v_mfma_f32_16x16x32_bf16 v[114:117], v[182:185], v[208:211], v[114:117]
	v_mfma_f32_16x16x32_bf16 v[102:105], v[174:177], v[216:219], v[102:105]
	v_mfma_f32_16x16x32_bf16 v[98:101], v[182:185], v[216:219], v[98:101]
	v_mfma_f32_16x16x32_bf16 v[86:89], v[174:177], v[224:227], v[86:89]
	v_mfma_f32_16x16x32_bf16 v[82:85], v[182:185], v[224:227], v[82:85]
	v_mfma_f32_16x16x32_bf16 v[70:73], v[174:177], v[232:235], v[70:73]
	v_mfma_f32_16x16x32_bf16 v[66:69], v[182:185], v[232:235], v[66:69]
	s_setprio 0
	s_setprio 1
	v_mfma_f32_16x16x32_bf16 v[118:121], v[178:181], v[212:215], v[118:121]
	v_mfma_f32_16x16x32_bf16 v[114:117], v[204:207], v[212:215], v[114:117]
	v_mfma_f32_16x16x32_bf16 v[102:105], v[178:181], v[220:223], v[102:105]
	v_mfma_f32_16x16x32_bf16 v[98:101], v[204:207], v[220:223], v[98:101]
	v_mfma_f32_16x16x32_bf16 v[86:89], v[178:181], v[228:231], v[86:89]
	v_mfma_f32_16x16x32_bf16 v[82:85], v[204:207], v[228:231], v[82:85]
	v_mfma_f32_16x16x32_bf16 v[70:73], v[178:181], v[236:239], v[70:73]
	v_mfma_f32_16x16x32_bf16 v[66:69], v[204:207], v[236:239], v[66:69]
	s_setprio 0
	s_barrier
; #define PG8_STAGE(bufoff, gbase, voff) do { _Pragma("unroll") for (int _i = 0; _i < 2; ++_i) \
;         __builtin_amdgcn_global_load_lds((const unsigned*)((const char*)(gbase) + (voff)[_i]), (PG8_LAS unsigned*)(lds + (bufoff) + ldsw + _i * 8192), 16, 0, 0); } while (0)
; #define PG8_LDA(dst, b, h) do { _Pragma("unroll") for (int m = 0; m < 4; ++m) _Pragma("unroll") for (int k = 0; k < 2; ++k) dst[m][k] = *(const PG8_LAS bf16x8*)(lds + PG8_SA(b, h) + aoff + m * 2048 + k * 1024); } while (0)
; #define PG8_MMA(ai, bj, At, Bt) do { __builtin_amdgcn_s_setprio(1); _Pragma("unroll") for (int m = 0; m < 4; ++m) _Pragma("unroll") for (int n = 0; n < 2; ++n) _Pragma("unroll") for (int k = 0; k < 2; ++k) \
;         acc[ai][bj][m][n] = __builtin_amdgcn_mfma_f32_16x16x32_bf16(Bt[n][k], At[m][k], acc[ai][bj][m][n], 0, 0, 0); __builtin_amdgcn_s_setprio(0); } while (0)
; #define PG8_WAIT_V(n) asm volatile("s_waitcnt vmcnt(" #n ")" ::: "memory")
; #define PG8_WAIT_L(n) asm volatile("s_waitcnt lgkmcnt(" #n ")" ::: "memory")
; #define PG8_BAR __builtin_amdgcn_s_barrier()
; #define PG8_SCHED __builtin_amdgcn_sched_barrier(0)
;     __device__ __forceinline__ void operator()(const f32x4 (&acc)[2][2][4][2], const Unit& u, int wr, int wc, int fr, int fq) const {
;     ...
;                 for (int bj = 0; bj < 2; ++bj) { const size_t off = row * DM + col0 + bj * HALF;
;                     f32x4 v0 = acc[ai][bj][m][0] + *(const f32x4*)(base + off), v1 = acc[ai][bj][m][1] + *(const f32x4*)(base + off + 4);
; template <class Epi, class Sched, bool ALIGN_EPI = false, bool SP2 = false>
; __device__ __forceinline__ void gemm_phase(PG8_LAS unsigned char* lds, const Gemm g, const Sched& S, const Epi& E) {
;     ...
;             PG8_LDA(At, 1, 1); PG8_STAGE(PG8_SB(1, 0), b3, voffB); PG8_STAGE(PG8_SB(1, 1), b3 + hstep, voffB); PG8_STAGE(PG8_SA(1, 0), a3, voffA);
;             PG8_WAIT_V(8); PG8_WAIT_L(0); PG8_BAR; PG8_MMA(1, 0, At, B0); PG8_MMA(1, 1, At, B1); PG8_BAR; PG8_SCHED;
;     ...
;         if constexpr (ALIGN_EPI) { if (wr == 0) PG8_BAR; }
	s_add_i32 s47, s47, s4
	v_lshl_add_u64 v[186:187], v[186:187], 0, s[68:69]
	s_mov_b32 m0, s47
	ds_read_b128 v[208:211], v161 offset:49152
	ds_read_b128 v[212:215], v161 offset:50176
	ds_read_b128 v[216:219], v161 offset:51200
	ds_read_b128 v[220:223], v161 offset:52224
	ds_read_b128 v[224:227], v161 offset:53248
	ds_read_b128 v[228:231], v161 offset:54272
	ds_read_b128 v[232:235], v161 offset:55296
	ds_read_b128 v[236:239], v161 offset:56320
	global_load_lds_dwordx4 v[186:187], off
	s_add_i32 m0, s47, 0x2000
	s_add_u32 s40, s40, 0x80080
	v_lshl_add_u64 v[186:187], v[240:241], 0, s[68:69]
	s_addc_u32 s41, s41, 0
	s_add_i32 s47, s76, s4
	global_load_lds_dwordx4 v[186:187], off
	v_lshl_add_u64 v[186:187], s[40:41], 0, v[148:149]
	s_mov_b32 m0, s47
	s_nop 0
	global_load_lds_dwordx4 v[186:187], off
	v_lshl_add_u64 v[186:187], s[40:41], 0, v[144:145]
	s_add_i32 m0, s47, 0x2000
	s_nop 0
	global_load_lds_dwordx4 v[186:187], off
	v_lshl_add_u64 v[186:187], v[242:243], 0, s[68:69]
	s_mov_b32 m0, s67
	s_nop 0
	global_load_lds_dwordx4 v[186:187], off
	v_lshl_add_u64 v[186:187], v[244:245], 0, s[68:69]
	s_mov_b32 m0, s28
	s_nop 0
	global_load_lds_dwordx4 v[186:187], off
	s_nop 0
	s_waitcnt vmcnt(8)
	s_waitcnt lgkmcnt(0)
	s_setprio 1
	s_barrier
	v_mfma_f32_16x16x32_bf16 v[62:65], v[156:159], v[208:211], v[62:65]
	v_mfma_f32_16x16x32_bf16 v[58:61], v[166:169], v[208:211], v[58:61]
	v_mfma_f32_16x16x32_bf16 v[46:49], v[156:159], v[216:219], v[46:49]
	v_mfma_f32_16x16x32_bf16 v[42:45], v[166:169], v[216:219], v[42:45]
	v_mfma_f32_16x16x32_bf16 v[30:33], v[156:159], v[224:227], v[30:33]
	v_mfma_f32_16x16x32_bf16 v[26:29], v[166:169], v[224:227], v[26:29]
	v_mfma_f32_16x16x32_bf16 v[14:17], v[156:159], v[232:235], v[14:17]
	v_mfma_f32_16x16x32_bf16 v[10:13], v[166:169], v[232:235], v[10:13]
	v_mfma_f32_16x16x32_bf16 v[62:65], v[162:165], v[212:215], v[62:65]
	v_mfma_f32_16x16x32_bf16 v[58:61], v[170:173], v[212:215], v[58:61]
	v_mfma_f32_16x16x32_bf16 v[46:49], v[162:165], v[220:223], v[46:49]
	v_mfma_f32_16x16x32_bf16 v[42:45], v[170:173], v[220:223], v[42:45]
	v_mfma_f32_16x16x32_bf16 v[30:33], v[162:165], v[228:231], v[30:33]
	v_mfma_f32_16x16x32_bf16 v[26:29], v[170:173], v[228:231], v[26:29]
	v_mfma_f32_16x16x32_bf16 v[14:17], v[162:165], v[236:239], v[14:17]
	v_mfma_f32_16x16x32_bf16 v[10:13], v[170:173], v[236:239], v[10:13]
	v_mfma_f32_16x16x32_bf16 v[54:57], v[174:177], v[208:211], v[54:57]
	v_mfma_f32_16x16x32_bf16 v[50:53], v[182:185], v[208:211], v[50:53]
	v_mfma_f32_16x16x32_bf16 v[38:41], v[174:177], v[216:219], v[38:41]
	v_mfma_f32_16x16x32_bf16 v[34:37], v[182:185], v[216:219], v[34:37]
	v_mfma_f32_16x16x32_bf16 v[22:25], v[174:177], v[224:227], v[22:25]
	v_mfma_f32_16x16x32_bf16 v[18:21], v[182:185], v[224:227], v[18:21]
	v_mfma_f32_16x16x32_bf16 v[6:9], v[174:177], v[232:235], v[6:9]
	v_mfma_f32_16x16x32_bf16 v[2:5], v[182:185], v[232:235], v[2:5]
	v_mfma_f32_16x16x32_bf16 v[54:57], v[178:181], v[212:215], v[54:57]
	v_mfma_f32_16x16x32_bf16 v[50:53], v[204:207], v[212:215], v[50:53]
	v_mfma_f32_16x16x32_bf16 v[38:41], v[178:181], v[220:223], v[38:41]
	v_mfma_f32_16x16x32_bf16 v[34:37], v[204:207], v[220:223], v[34:37]
	v_mfma_f32_16x16x32_bf16 v[22:25], v[178:181], v[228:231], v[22:25]
	v_mfma_f32_16x16x32_bf16 v[18:21], v[204:207], v[228:231], v[18:21]
	v_mfma_f32_16x16x32_bf16 v[6:9], v[178:181], v[236:239], v[6:9]
	v_mfma_f32_16x16x32_bf16 v[2:5], v[204:207], v[236:239], v[2:5]
	s_setprio 0
	s_barrier
	s_add_i32 s46, s46, 2
	s_add_u32 vcc_lo, vcc_lo, 0x100
	s_addc_u32 vcc_hi, vcc_hi, 0
	s_add_u32 s78, s78, 0x100
	s_addc_u32 s79, s79, 0
	s_cmp_gt_u32 s46, 29
	s_cbranch_scc0 .LBB0_98
	s_mov_b32 s32, 1
	v_lshl_add_u32 v156, s73, 8, v1
	v_lshl_or_b32 v157, s54, 8, v160
	v_lshl_add_u32 v157, v156, 11, v157
	v_mov_b32_e32 v247, 0
	v_lshlrev_b32_e32 v246, 2, v157
	v_lshl_add_u64 v[162:163], s[8:9], 0, v[246:247]
	v_lshlrev_b32_e32 v246, 1, v157
	v_lshl_add_u64 v[244:245], s[70:71], 0, v[246:247]
	s_mov_b32 s41, 0
	global_load_dwordx4 v[164:167], v[162:163], off
	global_load_dwordx4 v[168:171], v[162:163], off offset:16
	global_load_dwordx4 v[172:175], v[162:163], off offset:512
	global_load_dwordx4 v[176:179], v[162:163], off offset:528
	s_mov_b32 s40, 0x20000
	v_lshl_add_u64 v[246:247], v[162:163], 0, s[40:41]
	global_load_dwordx4 v[180:183], v[246:247], off
	global_load_dwordx4 v[184:187], v[246:247], off offset:16
	global_load_dwordx4 v[204:207], v[246:247], off offset:512
	global_load_dwordx4 v[208:211], v[246:247], off offset:528
	s_mov_b32 s40, 0x40000
	v_lshl_add_u64 v[246:247], v[162:163], 0, s[40:41]
	global_load_dwordx4 v[212:215], v[246:247], off
	global_load_dwordx4 v[216:219], v[246:247], off offset:16
	global_load_dwordx4 v[220:223], v[246:247], off offset:512
	global_load_dwordx4 v[224:227], v[246:247], off offset:528
	s_mov_b32 s40, 0x60000
	v_lshl_add_u64 v[246:247], v[162:163], 0, s[40:41]
	global_load_dwordx4 v[228:231], v[246:247], off
	global_load_dwordx4 v[232:235], v[246:247], off offset:16
	global_load_dwordx4 v[236:239], v[246:247], off offset:512
	global_load_dwordx4 v[240:243], v[246:247], off offset:528
	s_andn2_b64 vcc, s[36:37], s[44:45]
	s_cbranch_vccz .Lx1_nobar
	s_barrier
; __device__ __forceinline__ unsigned cvt_pk_bf16(float lo, float hi) { const f32x2c_t v = {lo, hi}; const bf16x2c_t b = __builtin_convertvector(v, bf16x2c_t); return __builtin_bit_cast(unsigned, b); }
; __device__ __forceinline__ float bf_lo(unsigned w) { return __uint_as_float(w << 16); }
; __device__ __forceinline__ float bf_hi(unsigned w) { return __uint_as_float(w & 0xffff0000u); }
;     __device__ __forceinline__ void operator()(const f32x4 (&acc)[2][2][4][2], const Unit& u, int wr, int wc, int fr, int fq) const {
;     ...
;                 for (int bj = 0; bj < 2; ++bj) { const size_t off = row * DM + col0 + bj * HALF;
;                     f32x4 v0 = acc[ai][bj][m][0] + *(const f32x4*)(base + off), v1 = acc[ai][bj][m][1] + *(const f32x4*)(base + off + 4);
;                     u32x4 w; w.x = cvt_pk_bf16(v0[0], v0[1]); w.y = cvt_pk_bf16(v0[2], v0[3]); w.z = cvt_pk_bf16(v1[0], v1[1]); w.w = cvt_pk_bf16(v1[2], v1[3]);
;                     *(u32x4*)(XN + off) = w;
;                     v0 = (f32x4){bf_lo(w.x), bf_hi(w.x), bf_lo(w.y), bf_hi(w.y)}; v1 = (f32x4){bf_lo(w.z), bf_hi(w.z), bf_lo(w.w), bf_hi(w.w)};
;                     ss += (v0[0] * v0[0] + v0[1] * v0[1]) + (v0[2] * v0[2] + v0[3] * v0[3]) + (v1[0] * v1[0] + v1[1] * v1[1]) + (v1[2] * v1[2] + v1[3] * v1[3]); }
.Lx1_nobar:
	s_waitcnt vmcnt(14)
	v_pk_add_f32 v[126:127], v[126:127], v[164:165]
	v_pk_add_f32 v[128:129], v[128:129], v[166:167]
	v_pk_add_f32 v[122:123], v[122:123], v[168:169]
	v_pk_add_f32 v[124:125], v[124:125], v[170:171]
	v_cvt_pk_bf16_f32 v164, v126, v127
	v_cvt_pk_bf16_f32 v165, v128, v129
	v_cvt_pk_bf16_f32 v166, v122, v123
	v_cvt_pk_bf16_f32 v167, v124, v125
	global_store_dwordx4 v[244:245], v[164:167], off
	v_lshlrev_b32_e32 v126, 16, v164
	v_lshlrev_b32_e32 v127, 16, v165
	v_and_b32_e32 v128, 0xffff0000, v164
	v_and_b32_e32 v129, 0xffff0000, v165
	v_mul_f32_e32 v128, v128, v128
	v_mul_f32_e32 v129, v129, v129
	v_lshlrev_b32_e32 v122, 16, v166
	v_and_b32_e32 v123, 0xffff0000, v166
	v_fmac_f32_e32 v128, v126, v126
	v_fmac_f32_e32 v129, v127, v127
	v_add_f32_e32 v128, v128, v129
	v_mul_f32_e32 v129, v123, v123
	v_lshlrev_b32_e32 v124, 16, v167
	v_and_b32_e32 v125, 0xffff0000, v167
	v_fmac_f32_e32 v129, v122, v122
	v_add_f32_e32 v128, v129, v128
	v_mul_f32_e32 v129, v125, v125
	v_fmac_f32_e32 v129, v124, v124
	v_add_f32_e32 v126, v129, v128
	s_waitcnt vmcnt(13)
	v_pk_add_f32 v[118:119], v[118:119], v[172:173]
	v_pk_add_f32 v[120:121], v[120:121], v[174:175]
	v_pk_add_f32 v[114:115], v[114:115], v[176:177]
	v_pk_add_f32 v[116:117], v[116:117], v[178:179]
	v_cvt_pk_bf16_f32 v172, v118, v119
	v_cvt_pk_bf16_f32 v173, v120, v121
	v_cvt_pk_bf16_f32 v174, v114, v115
	v_cvt_pk_bf16_f32 v175, v116, v117
	global_store_dwordx4 v[244:245], v[172:175], off offset:256
	v_lshlrev_b32_e32 v118, 16, v172
	v_lshlrev_b32_e32 v119, 16, v173
	v_and_b32_e32 v120, 0xffff0000, v172
	v_and_b32_e32 v121, 0xffff0000, v173
	v_mul_f32_e32 v120, v120, v120
	v_mul_f32_e32 v121, v121, v121
	v_lshlrev_b32_e32 v114, 16, v174
	v_and_b32_e32 v115, 0xffff0000, v174
	v_fmac_f32_e32 v120, v118, v118
	v_fmac_f32_e32 v121, v119, v119
	v_add_f32_e32 v120, v120, v121
	v_mul_f32_e32 v121, v115, v115
	v_lshlrev_b32_e32 v116, 16, v175
	v_and_b32_e32 v117, 0xffff0000, v175
	v_fmac_f32_e32 v121, v114, v114
	v_add_f32_e32 v120, v121, v120
	v_mul_f32_e32 v121, v117, v117
	v_fmac_f32_e32 v121, v116, v116
	v_add_f32_e32 v120, v121, v120
	v_add_f32_e32 v126, v126, v120
	s_mov_b32 s40, 0x100000
	v_lshl_add_u64 v[246:247], v[162:163], 0, s[40:41]
	global_load_dwordx4 v[164:167], v[246:247], off
	global_load_dwordx4 v[168:171], v[246:247], off offset:16
	global_load_dwordx4 v[172:175], v[246:247], off offset:512
	global_load_dwordx4 v[176:179], v[246:247], off offset:528
	s_mov_b32 s40, 0x10000
	v_lshl_add_u64 v[158:159], v[244:245], 0, s[40:41]
	s_waitcnt vmcnt(16)
	v_pk_add_f32 v[110:111], v[110:111], v[180:181]
	v_pk_add_f32 v[112:113], v[112:113], v[182:183]
	v_pk_add_f32 v[106:107], v[106:107], v[184:185]
	v_pk_add_f32 v[108:109], v[108:109], v[186:187]
	v_cvt_pk_bf16_f32 v180, v110, v111
	v_cvt_pk_bf16_f32 v181, v112, v113
	v_cvt_pk_bf16_f32 v182, v106, v107
	v_cvt_pk_bf16_f32 v183, v108, v109
	global_store_dwordx4 v[158:159], v[180:183], off
	v_lshlrev_b32_e32 v110, 16, v180
	v_lshlrev_b32_e32 v111, 16, v181
	v_and_b32_e32 v112, 0xffff0000, v180
	v_and_b32_e32 v113, 0xffff0000, v181
	v_mul_f32_e32 v112, v112, v112
	v_mul_f32_e32 v113, v113, v113
	v_lshlrev_b32_e32 v106, 16, v182
	v_and_b32_e32 v107, 0xffff0000, v182
	v_fmac_f32_e32 v112, v110, v110
	v_fmac_f32_e32 v113, v111, v111
	v_add_f32_e32 v112, v112, v113
	v_mul_f32_e32 v113, v107, v107
	v_lshlrev_b32_e32 v108, 16, v183
	v_and_b32_e32 v109, 0xffff0000, v183
	v_fmac_f32_e32 v113, v106, v106
	v_add_f32_e32 v112, v113, v112
	v_mul_f32_e32 v113, v109, v109
	v_fmac_f32_e32 v113, v108, v108
	v_add_f32_e32 v110, v113, v112
	s_waitcnt vmcnt(15)
	v_pk_add_f32 v[102:103], v[102:103], v[204:205]
	v_pk_add_f32 v[104:105], v[104:105], v[206:207]
	v_pk_add_f32 v[98:99], v[98:99], v[208:209]
	v_pk_add_f32 v[100:101], v[100:101], v[210:211]
	v_cvt_pk_bf16_f32 v204, v102, v103
	v_cvt_pk_bf16_f32 v205, v104, v105
	v_cvt_pk_bf16_f32 v206, v98, v99
	v_cvt_pk_bf16_f32 v207, v100, v101
	global_store_dwordx4 v[158:159], v[204:207], off offset:256
	v_lshlrev_b32_e32 v102, 16, v204
	v_lshlrev_b32_e32 v103, 16, v205
	v_and_b32_e32 v104, 0xffff0000, v204
	v_and_b32_e32 v105, 0xffff0000, v205
	v_mul_f32_e32 v104, v104, v104
	v_mul_f32_e32 v105, v105, v105
	v_lshlrev_b32_e32 v98, 16, v206
	v_and_b32_e32 v99, 0xffff0000, v206
	v_fmac_f32_e32 v104, v102, v102
	v_fmac_f32_e32 v105, v103, v103
	v_add_f32_e32 v104, v104, v105
	v_mul_f32_e32 v105, v99, v99
	v_lshlrev_b32_e32 v100, 16, v207
	v_and_b32_e32 v101, 0xffff0000, v207
	v_fmac_f32_e32 v105, v98, v98
	v_add_f32_e32 v104, v105, v104
	v_mul_f32_e32 v105, v101, v101
	v_fmac_f32_e32 v105, v100, v100
	v_add_f32_e32 v104, v105, v104
	v_add_f32_e32 v110, v110, v104
	s_mov_b32 s40, 0x120000
	v_lshl_add_u64 v[246:247], v[162:163], 0, s[40:41]
	global_load_dwordx4 v[180:183], v[246:247], off
	global_load_dwordx4 v[184:187], v[246:247], off offset:16
	global_load_dwordx4 v[204:207], v[246:247], off offset:512
	global_load_dwordx4 v[208:211], v[246:247], off offset:528
	s_mov_b32 s40, 0x20000
	v_lshl_add_u64 v[158:159], v[244:245], 0, s[40:41]
	s_waitcnt vmcnt(18)
	v_pk_add_f32 v[94:95], v[94:95], v[212:213]
	v_pk_add_f32 v[96:97], v[96:97], v[214:215]
	v_pk_add_f32 v[90:91], v[90:91], v[216:217]
	v_pk_add_f32 v[92:93], v[92:93], v[218:219]
	v_cvt_pk_bf16_f32 v212, v94, v95
	v_cvt_pk_bf16_f32 v213, v96, v97
	v_cvt_pk_bf16_f32 v214, v90, v91
	v_cvt_pk_bf16_f32 v215, v92, v93
	global_store_dwordx4 v[158:159], v[212:215], off
	v_lshlrev_b32_e32 v94, 16, v212
	v_lshlrev_b32_e32 v95, 16, v213
	v_and_b32_e32 v96, 0xffff0000, v212
	v_and_b32_e32 v97, 0xffff0000, v213
	v_mul_f32_e32 v96, v96, v96
	v_mul_f32_e32 v97, v97, v97
	v_lshlrev_b32_e32 v90, 16, v214
	v_and_b32_e32 v91, 0xffff0000, v214
	v_fmac_f32_e32 v96, v94, v94
	v_fmac_f32_e32 v97, v95, v95
	v_add_f32_e32 v96, v96, v97
	v_mul_f32_e32 v97, v91, v91
	v_lshlrev_b32_e32 v92, 16, v215
	v_and_b32_e32 v93, 0xffff0000, v215
	v_fmac_f32_e32 v97, v90, v90
	v_add_f32_e32 v96, v97, v96
	v_mul_f32_e32 v97, v93, v93
	v_fmac_f32_e32 v97, v92, v92
	v_add_f32_e32 v94, v97, v96
	s_waitcnt vmcnt(17)
; __device__ __forceinline__ unsigned cvt_pk_bf16(float lo, float hi) { const f32x2c_t v = {lo, hi}; const bf16x2c_t b = __builtin_convertvector(v, bf16x2c_t); return __builtin_bit_cast(unsigned, b); }
; __device__ __forceinline__ float bf_lo(unsigned w) { return __uint_as_float(w << 16); }
; __device__ __forceinline__ float bf_hi(unsigned w) { return __uint_as_float(w & 0xffff0000u); }
;     __device__ __forceinline__ void operator()(const f32x4 (&acc)[2][2][4][2], const Unit& u, int wr, int wc, int fr, int fq) const {
;     ...
;                 for (int bj = 0; bj < 2; ++bj) { const size_t off = row * DM + col0 + bj * HALF;
;                     f32x4 v0 = acc[ai][bj][m][0] + *(const f32x4*)(base + off), v1 = acc[ai][bj][m][1] + *(const f32x4*)(base + off + 4);
;                     u32x4 w; w.x = cvt_pk_bf16(v0[0], v0[1]); w.y = cvt_pk_bf16(v0[2], v0[3]); w.z = cvt_pk_bf16(v1[0], v1[1]); w.w = cvt_pk_bf16(v1[2], v1[3]);
;                     *(u32x4*)(XN + off) = w;
;                     v0 = (f32x4){bf_lo(w.x), bf_hi(w.x), bf_lo(w.y), bf_hi(w.y)}; v1 = (f32x4){bf_lo(w.z), bf_hi(w.z), bf_lo(w.w), bf_hi(w.w)};
;                     ss += (v0[0] * v0[0] + v0[1] * v0[1]) + (v0[2] * v0[2] + v0[3] * v0[3]) + (v1[0] * v1[0] + v1[1] * v1[1]) + (v1[2] * v1[2] + v1[3] * v1[3]); }
	v_pk_add_f32 v[86:87], v[86:87], v[220:221]
	v_pk_add_f32 v[88:89], v[88:89], v[222:223]
	v_pk_add_f32 v[82:83], v[82:83], v[224:225]
	v_pk_add_f32 v[84:85], v[84:85], v[226:227]
	v_cvt_pk_bf16_f32 v220, v86, v87
	v_cvt_pk_bf16_f32 v221, v88, v89
	v_cvt_pk_bf16_f32 v222, v82, v83
	v_cvt_pk_bf16_f32 v223, v84, v85
	global_store_dwordx4 v[158:159], v[220:223], off offset:256
	v_lshlrev_b32_e32 v86, 16, v220
	v_lshlrev_b32_e32 v87, 16, v221
	v_and_b32_e32 v88, 0xffff0000, v220
	v_and_b32_e32 v89, 0xffff0000, v221
	v_mul_f32_e32 v88, v88, v88
	v_mul_f32_e32 v89, v89, v89
	v_lshlrev_b32_e32 v82, 16, v222
	v_and_b32_e32 v83, 0xffff0000, v222
	v_fmac_f32_e32 v88, v86, v86
	v_fmac_f32_e32 v89, v87, v87
	v_add_f32_e32 v88, v88, v89
	v_mul_f32_e32 v89, v83, v83
	v_lshlrev_b32_e32 v84, 16, v223
	v_and_b32_e32 v85, 0xffff0000, v223
	v_fmac_f32_e32 v89, v82, v82
	v_add_f32_e32 v88, v89, v88
	v_mul_f32_e32 v89, v85, v85
	v_fmac_f32_e32 v89, v84, v84
	v_add_f32_e32 v88, v89, v88
	v_add_f32_e32 v94, v94, v88
	s_mov_b32 s40, 0x140000
	v_lshl_add_u64 v[246:247], v[162:163], 0, s[40:41]
	global_load_dwordx4 v[212:215], v[246:247], off
	global_load_dwordx4 v[216:219], v[246:247], off offset:16
	global_load_dwordx4 v[220:223], v[246:247], off offset:512
	global_load_dwordx4 v[224:227], v[246:247], off offset:528
	s_mov_b32 s40, 0x30000
	v_lshl_add_u64 v[158:159], v[244:245], 0, s[40:41]
	s_waitcnt vmcnt(20)
	v_pk_add_f32 v[78:79], v[78:79], v[228:229]
	v_pk_add_f32 v[80:81], v[80:81], v[230:231]
	v_pk_add_f32 v[74:75], v[74:75], v[232:233]
	v_pk_add_f32 v[76:77], v[76:77], v[234:235]
	v_cvt_pk_bf16_f32 v228, v78, v79
	v_cvt_pk_bf16_f32 v229, v80, v81
	v_cvt_pk_bf16_f32 v230, v74, v75
	v_cvt_pk_bf16_f32 v231, v76, v77
	global_store_dwordx4 v[158:159], v[228:231], off
	v_lshlrev_b32_e32 v78, 16, v228
	v_lshlrev_b32_e32 v79, 16, v229
	v_and_b32_e32 v80, 0xffff0000, v228
	v_and_b32_e32 v81, 0xffff0000, v229
	v_mul_f32_e32 v80, v80, v80
	v_mul_f32_e32 v81, v81, v81
	v_lshlrev_b32_e32 v74, 16, v230
	v_and_b32_e32 v75, 0xffff0000, v230
	v_fmac_f32_e32 v80, v78, v78
	v_fmac_f32_e32 v81, v79, v79
	v_add_f32_e32 v80, v80, v81
	v_mul_f32_e32 v81, v75, v75
	v_lshlrev_b32_e32 v76, 16, v231
	v_and_b32_e32 v77, 0xffff0000, v231
	v_fmac_f32_e32 v81, v74, v74
	v_add_f32_e32 v80, v81, v80
	v_mul_f32_e32 v81, v77, v77
	v_fmac_f32_e32 v81, v76, v76
	v_add_f32_e32 v78, v81, v80
	s_waitcnt vmcnt(19)
	v_pk_add_f32 v[70:71], v[70:71], v[236:237]
	v_pk_add_f32 v[72:73], v[72:73], v[238:239]
	v_pk_add_f32 v[66:67], v[66:67], v[240:241]
	v_pk_add_f32 v[68:69], v[68:69], v[242:243]
	v_cvt_pk_bf16_f32 v236, v70, v71
	v_cvt_pk_bf16_f32 v237, v72, v73
	v_cvt_pk_bf16_f32 v238, v66, v67
	v_cvt_pk_bf16_f32 v239, v68, v69
	global_store_dwordx4 v[158:159], v[236:239], off offset:256
	v_lshlrev_b32_e32 v70, 16, v236
	v_lshlrev_b32_e32 v71, 16, v237
	v_and_b32_e32 v72, 0xffff0000, v236
	v_and_b32_e32 v73, 0xffff0000, v237
	v_mul_f32_e32 v72, v72, v72
	v_mul_f32_e32 v73, v73, v73
	v_lshlrev_b32_e32 v66, 16, v238
	v_and_b32_e32 v67, 0xffff0000, v238
	v_fmac_f32_e32 v72, v70, v70
	v_fmac_f32_e32 v73, v71, v71
	v_add_f32_e32 v72, v72, v73
	v_mul_f32_e32 v73, v67, v67
	v_lshlrev_b32_e32 v68, 16, v239
	v_and_b32_e32 v69, 0xffff0000, v239
	v_fmac_f32_e32 v73, v66, v66
	v_add_f32_e32 v72, v73, v72
	v_mul_f32_e32 v73, v69, v69
	v_fmac_f32_e32 v73, v68, v68
	v_add_f32_e32 v72, v73, v72
	v_add_f32_e32 v78, v78, v72
	s_mov_b32 s40, 0x160000
	v_lshl_add_u64 v[246:247], v[162:163], 0, s[40:41]
	global_load_dwordx4 v[228:231], v[246:247], off
	global_load_dwordx4 v[232:235], v[246:247], off offset:16
	global_load_dwordx4 v[236:239], v[246:247], off offset:512
	global_load_dwordx4 v[240:243], v[246:247], off offset:528
	s_mov_b32 s40, 0x80000
	v_lshl_add_u64 v[158:159], v[244:245], 0, s[40:41]
	s_waitcnt vmcnt(20)
	v_pk_add_f32 v[62:63], v[62:63], v[164:165]
	v_pk_add_f32 v[64:65], v[64:65], v[166:167]
	v_pk_add_f32 v[58:59], v[58:59], v[168:169]
	v_pk_add_f32 v[60:61], v[60:61], v[170:171]
	v_cvt_pk_bf16_f32 v164, v62, v63
	v_cvt_pk_bf16_f32 v165, v64, v65
	v_cvt_pk_bf16_f32 v166, v58, v59
	v_cvt_pk_bf16_f32 v167, v60, v61
	global_store_dwordx4 v[158:159], v[164:167], off
	v_lshlrev_b32_e32 v62, 16, v164
	v_lshlrev_b32_e32 v63, 16, v165
	v_and_b32_e32 v64, 0xffff0000, v164
	v_and_b32_e32 v65, 0xffff0000, v165
	v_mul_f32_e32 v64, v64, v64
	v_mul_f32_e32 v65, v65, v65
	v_lshlrev_b32_e32 v58, 16, v166
	v_and_b32_e32 v59, 0xffff0000, v166
	v_fmac_f32_e32 v64, v62, v62
	v_fmac_f32_e32 v65, v63, v63
	v_add_f32_e32 v64, v64, v65
	v_mul_f32_e32 v65, v59, v59
	v_lshlrev_b32_e32 v60, 16, v167
	v_and_b32_e32 v61, 0xffff0000, v167
	v_fmac_f32_e32 v65, v58, v58
	v_add_f32_e32 v64, v65, v64
	v_mul_f32_e32 v65, v61, v61
	v_fmac_f32_e32 v65, v60, v60
	v_add_f32_e32 v62, v65, v64
	s_waitcnt vmcnt(19)
	v_pk_add_f32 v[54:55], v[54:55], v[172:173]
	v_pk_add_f32 v[56:57], v[56:57], v[174:175]
	v_pk_add_f32 v[50:51], v[50:51], v[176:177]
	v_pk_add_f32 v[52:53], v[52:53], v[178:179]
	v_cvt_pk_bf16_f32 v172, v54, v55
	v_cvt_pk_bf16_f32 v173, v56, v57
	v_cvt_pk_bf16_f32 v174, v50, v51
	v_cvt_pk_bf16_f32 v175, v52, v53
	global_store_dwordx4 v[158:159], v[172:175], off offset:256
	v_lshlrev_b32_e32 v54, 16, v172
	v_lshlrev_b32_e32 v55, 16, v173
	v_and_b32_e32 v56, 0xffff0000, v172
	v_and_b32_e32 v57, 0xffff0000, v173
	v_mul_f32_e32 v56, v56, v56
	v_mul_f32_e32 v57, v57, v57
	v_lshlrev_b32_e32 v50, 16, v174
	v_and_b32_e32 v51, 0xffff0000, v174
	v_fmac_f32_e32 v56, v54, v54
	v_fmac_f32_e32 v57, v55, v55
	v_add_f32_e32 v56, v56, v57
	v_mul_f32_e32 v57, v51, v51
	v_lshlrev_b32_e32 v52, 16, v175
	v_and_b32_e32 v53, 0xffff0000, v175
	v_fmac_f32_e32 v57, v50, v50
	v_add_f32_e32 v56, v57, v56
	v_mul_f32_e32 v57, v53, v53
	v_fmac_f32_e32 v57, v52, v52
	v_add_f32_e32 v56, v57, v56
	v_add_f32_e32 v62, v62, v56
	s_mov_b32 s40, 0x90000
	v_lshl_add_u64 v[158:159], v[244:245], 0, s[40:41]
	s_waitcnt vmcnt(16)
; __device__ __forceinline__ unsigned cvt_pk_bf16(float lo, float hi) { const f32x2c_t v = {lo, hi}; const bf16x2c_t b = __builtin_convertvector(v, bf16x2c_t); return __builtin_bit_cast(unsigned, b); }
; __device__ __forceinline__ float bf_lo(unsigned w) { return __uint_as_float(w << 16); }
; __device__ __forceinline__ float bf_hi(unsigned w) { return __uint_as_float(w & 0xffff0000u); }
;     __device__ __forceinline__ void operator()(const f32x4 (&acc)[2][2][4][2], const Unit& u, int wr, int wc, int fr, int fq) const {
;     ...
;                 for (int bj = 0; bj < 2; ++bj) { const size_t off = row * DM + col0 + bj * HALF;
;                     f32x4 v0 = acc[ai][bj][m][0] + *(const f32x4*)(base + off), v1 = acc[ai][bj][m][1] + *(const f32x4*)(base + off + 4);
;                     u32x4 w; w.x = cvt_pk_bf16(v0[0], v0[1]); w.y = cvt_pk_bf16(v0[2], v0[3]); w.z = cvt_pk_bf16(v1[0], v1[1]); w.w = cvt_pk_bf16(v1[2], v1[3]);
;                     *(u32x4*)(XN + off) = w;
;                     v0 = (f32x4){bf_lo(w.x), bf_hi(w.x), bf_lo(w.y), bf_hi(w.y)}; v1 = (f32x4){bf_lo(w.z), bf_hi(w.z), bf_lo(w.w), bf_hi(w.w)};
;                     ss += (v0[0] * v0[0] + v0[1] * v0[1]) + (v0[2] * v0[2] + v0[3] * v0[3]) + (v1[0] * v1[0] + v1[1] * v1[1]) + (v1[2] * v1[2] + v1[3] * v1[3]); }
	v_pk_add_f32 v[46:47], v[46:47], v[180:181]
	v_pk_add_f32 v[48:49], v[48:49], v[182:183]
	v_pk_add_f32 v[42:43], v[42:43], v[184:185]
	v_pk_add_f32 v[44:45], v[44:45], v[186:187]
	v_cvt_pk_bf16_f32 v180, v46, v47
	v_cvt_pk_bf16_f32 v181, v48, v49
	v_cvt_pk_bf16_f32 v182, v42, v43
	v_cvt_pk_bf16_f32 v183, v44, v45
	global_store_dwordx4 v[158:159], v[180:183], off
	v_lshlrev_b32_e32 v46, 16, v180
	v_lshlrev_b32_e32 v47, 16, v181
	v_and_b32_e32 v48, 0xffff0000, v180
	v_and_b32_e32 v49, 0xffff0000, v181
	v_mul_f32_e32 v48, v48, v48
	v_mul_f32_e32 v49, v49, v49
	v_lshlrev_b32_e32 v42, 16, v182
	v_and_b32_e32 v43, 0xffff0000, v182
	v_fmac_f32_e32 v48, v46, v46
	v_fmac_f32_e32 v49, v47, v47
	v_add_f32_e32 v48, v48, v49
	v_mul_f32_e32 v49, v43, v43
	v_lshlrev_b32_e32 v44, 16, v183
	v_and_b32_e32 v45, 0xffff0000, v183
	v_fmac_f32_e32 v49, v42, v42
	v_add_f32_e32 v48, v49, v48
	v_mul_f32_e32 v49, v45, v45
	v_fmac_f32_e32 v49, v44, v44
	v_add_f32_e32 v46, v49, v48
	s_waitcnt vmcnt(15)
	v_pk_add_f32 v[38:39], v[38:39], v[204:205]
	v_pk_add_f32 v[40:41], v[40:41], v[206:207]
	v_pk_add_f32 v[34:35], v[34:35], v[208:209]
	v_pk_add_f32 v[36:37], v[36:37], v[210:211]
	v_cvt_pk_bf16_f32 v204, v38, v39
	v_cvt_pk_bf16_f32 v205, v40, v41
	v_cvt_pk_bf16_f32 v206, v34, v35
	v_cvt_pk_bf16_f32 v207, v36, v37
	global_store_dwordx4 v[158:159], v[204:207], off offset:256
	v_lshlrev_b32_e32 v38, 16, v204
	v_lshlrev_b32_e32 v39, 16, v205
	v_and_b32_e32 v40, 0xffff0000, v204
	v_and_b32_e32 v41, 0xffff0000, v205
	v_mul_f32_e32 v40, v40, v40
	v_mul_f32_e32 v41, v41, v41
	v_lshlrev_b32_e32 v34, 16, v206
	v_and_b32_e32 v35, 0xffff0000, v206
	v_fmac_f32_e32 v40, v38, v38
	v_fmac_f32_e32 v41, v39, v39
	v_add_f32_e32 v40, v40, v41
	v_mul_f32_e32 v41, v35, v35
	v_lshlrev_b32_e32 v36, 16, v207
	v_and_b32_e32 v37, 0xffff0000, v207
	v_fmac_f32_e32 v41, v34, v34
	v_add_f32_e32 v40, v41, v40
	v_mul_f32_e32 v41, v37, v37
	v_fmac_f32_e32 v41, v36, v36
	v_add_f32_e32 v40, v41, v40
	v_add_f32_e32 v46, v46, v40
	s_mov_b32 s40, 0xa0000
	v_lshl_add_u64 v[158:159], v[244:245], 0, s[40:41]
	s_waitcnt vmcnt(12)
	v_pk_add_f32 v[30:31], v[30:31], v[212:213]
	v_pk_add_f32 v[32:33], v[32:33], v[214:215]
	v_pk_add_f32 v[26:27], v[26:27], v[216:217]
	v_pk_add_f32 v[28:29], v[28:29], v[218:219]
	v_cvt_pk_bf16_f32 v212, v30, v31
	v_cvt_pk_bf16_f32 v213, v32, v33
	v_cvt_pk_bf16_f32 v214, v26, v27
	v_cvt_pk_bf16_f32 v215, v28, v29
	global_store_dwordx4 v[158:159], v[212:215], off
	v_lshlrev_b32_e32 v30, 16, v212
	v_lshlrev_b32_e32 v31, 16, v213
	v_and_b32_e32 v32, 0xffff0000, v212
	v_and_b32_e32 v33, 0xffff0000, v213
	v_mul_f32_e32 v32, v32, v32
	v_mul_f32_e32 v33, v33, v33
	v_lshlrev_b32_e32 v26, 16, v214
	v_and_b32_e32 v27, 0xffff0000, v214
	v_fmac_f32_e32 v32, v30, v30
	v_fmac_f32_e32 v33, v31, v31
	v_add_f32_e32 v32, v32, v33
	v_mul_f32_e32 v33, v27, v27
	v_lshlrev_b32_e32 v28, 16, v215
	v_and_b32_e32 v29, 0xffff0000, v215
	v_fmac_f32_e32 v33, v26, v26
	v_add_f32_e32 v32, v33, v32
	v_mul_f32_e32 v33, v29, v29
	v_fmac_f32_e32 v33, v28, v28
	v_add_f32_e32 v30, v33, v32
	s_waitcnt vmcnt(11)
	v_pk_add_f32 v[22:23], v[22:23], v[220:221]
	v_pk_add_f32 v[24:25], v[24:25], v[222:223]
	v_pk_add_f32 v[18:19], v[18:19], v[224:225]
	v_pk_add_f32 v[20:21], v[20:21], v[226:227]
	v_cvt_pk_bf16_f32 v220, v22, v23
	v_cvt_pk_bf16_f32 v221, v24, v25
	v_cvt_pk_bf16_f32 v222, v18, v19
	v_cvt_pk_bf16_f32 v223, v20, v21
	global_store_dwordx4 v[158:159], v[220:223], off offset:256
	v_lshlrev_b32_e32 v22, 16, v220
	v_lshlrev_b32_e32 v23, 16, v221
	v_and_b32_e32 v24, 0xffff0000, v220
	v_and_b32_e32 v25, 0xffff0000, v221
	v_mul_f32_e32 v24, v24, v24
	v_mul_f32_e32 v25, v25, v25
	v_lshlrev_b32_e32 v18, 16, v222
	v_and_b32_e32 v19, 0xffff0000, v222
	v_fmac_f32_e32 v24, v22, v22
	v_fmac_f32_e32 v25, v23, v23
	v_add_f32_e32 v24, v24, v25
	v_mul_f32_e32 v25, v19, v19
	v_lshlrev_b32_e32 v20, 16, v223
	v_and_b32_e32 v21, 0xffff0000, v223
	v_fmac_f32_e32 v25, v18, v18
	v_add_f32_e32 v24, v25, v24
	v_mul_f32_e32 v25, v21, v21
	v_fmac_f32_e32 v25, v20, v20
	v_add_f32_e32 v24, v25, v24
	v_add_f32_e32 v30, v30, v24
	s_mov_b32 s40, 0xb0000
	v_lshl_add_u64 v[158:159], v[244:245], 0, s[40:41]
	s_waitcnt vmcnt(8)
; __device__ __forceinline__ unsigned cvt_pk_bf16(float lo, float hi) { const f32x2c_t v = {lo, hi}; const bf16x2c_t b = __builtin_convertvector(v, bf16x2c_t); return __builtin_bit_cast(unsigned, b); }
; __device__ __forceinline__ float bf_lo(unsigned w) { return __uint_as_float(w << 16); }
; __device__ __forceinline__ float bf_hi(unsigned w) { return __uint_as_float(w & 0xffff0000u); }
; #define PG8_BAR __builtin_amdgcn_s_barrier()
;     __device__ __forceinline__ void operator()(const f32x4 (&acc)[2][2][4][2], const Unit& u, int wr, int wc, int fr, int fq) const {
;     ...
;                 for (int bj = 0; bj < 2; ++bj) { const size_t off = row * DM + col0 + bj * HALF;
;                     f32x4 v0 = acc[ai][bj][m][0] + *(const f32x4*)(base + off), v1 = acc[ai][bj][m][1] + *(const f32x4*)(base + off + 4);
;                     u32x4 w; w.x = cvt_pk_bf16(v0[0], v0[1]); w.y = cvt_pk_bf16(v0[2], v0[3]); w.z = cvt_pk_bf16(v1[0], v1[1]); w.w = cvt_pk_bf16(v1[2], v1[3]);
;                     *(u32x4*)(XN + off) = w;
;                     v0 = (f32x4){bf_lo(w.x), bf_hi(w.x), bf_lo(w.y), bf_hi(w.y)}; v1 = (f32x4){bf_lo(w.z), bf_hi(w.z), bf_lo(w.w), bf_hi(w.w)};
;                     ss += (v0[0] * v0[0] + v0[1] * v0[1]) + (v0[2] * v0[2] + v0[3] * v0[3]) + (v1[0] * v1[0] + v1[1] * v1[1]) + (v1[2] * v1[2] + v1[3] * v1[3]); }
;                 ss += __shfl_xor(ss, 16); ss += __shfl_xor(ss, 32);
;                 if (fq == 0) SS[row * 32 + u.pn * 4 + wc] = ss; }
; template <class Epi, class Sched, bool ALIGN_EPI = false, bool SP2 = false>
; __device__ __forceinline__ void gemm_phase(PG8_LAS unsigned char* lds, const Gemm g, const Sched& S, const Epi& E) {
;     ...
;         if (!has_next) break;
;     ...
;         if constexpr (ALIGN_EPI) { if (wr == 1) PG8_BAR; }
	v_pk_add_f32 v[14:15], v[14:15], v[228:229]
	v_pk_add_f32 v[16:17], v[16:17], v[230:231]
	v_pk_add_f32 v[10:11], v[10:11], v[232:233]
	v_pk_add_f32 v[12:13], v[12:13], v[234:235]
	v_cvt_pk_bf16_f32 v228, v14, v15
	v_cvt_pk_bf16_f32 v229, v16, v17
	v_cvt_pk_bf16_f32 v230, v10, v11
	v_cvt_pk_bf16_f32 v231, v12, v13
	global_store_dwordx4 v[158:159], v[228:231], off
	v_lshlrev_b32_e32 v14, 16, v228
	v_lshlrev_b32_e32 v15, 16, v229
	v_and_b32_e32 v16, 0xffff0000, v228
	v_and_b32_e32 v17, 0xffff0000, v229
	v_mul_f32_e32 v16, v16, v16
	v_mul_f32_e32 v17, v17, v17
	v_lshlrev_b32_e32 v10, 16, v230
	v_and_b32_e32 v11, 0xffff0000, v230
	v_fmac_f32_e32 v16, v14, v14
	v_fmac_f32_e32 v17, v15, v15
	v_add_f32_e32 v16, v16, v17
	v_mul_f32_e32 v17, v11, v11
	v_lshlrev_b32_e32 v12, 16, v231
	v_and_b32_e32 v13, 0xffff0000, v231
	v_fmac_f32_e32 v17, v10, v10
	v_add_f32_e32 v16, v17, v16
	v_mul_f32_e32 v17, v13, v13
	v_fmac_f32_e32 v17, v12, v12
	v_add_f32_e32 v14, v17, v16
	s_waitcnt vmcnt(7)
	v_pk_add_f32 v[6:7], v[6:7], v[236:237]
	v_pk_add_f32 v[8:9], v[8:9], v[238:239]
	v_pk_add_f32 v[2:3], v[2:3], v[240:241]
	v_pk_add_f32 v[4:5], v[4:5], v[242:243]
	v_cvt_pk_bf16_f32 v236, v6, v7
	v_cvt_pk_bf16_f32 v237, v8, v9
	v_cvt_pk_bf16_f32 v238, v2, v3
	v_cvt_pk_bf16_f32 v239, v4, v5
	global_store_dwordx4 v[158:159], v[236:239], off offset:256
	v_lshlrev_b32_e32 v6, 16, v236
	v_lshlrev_b32_e32 v7, 16, v237
	v_and_b32_e32 v8, 0xffff0000, v236
	v_and_b32_e32 v9, 0xffff0000, v237
	v_mul_f32_e32 v8, v8, v8
	v_mul_f32_e32 v9, v9, v9
	v_lshlrev_b32_e32 v2, 16, v238
	v_and_b32_e32 v3, 0xffff0000, v238
	v_fmac_f32_e32 v8, v6, v6
	v_fmac_f32_e32 v9, v7, v7
	v_add_f32_e32 v8, v8, v9
	v_mul_f32_e32 v9, v3, v3
	v_lshlrev_b32_e32 v4, 16, v239
	v_and_b32_e32 v5, 0xffff0000, v239
	v_fmac_f32_e32 v9, v2, v2
	v_add_f32_e32 v8, v9, v8
	v_mul_f32_e32 v9, v5, v5
	v_fmac_f32_e32 v9, v4, v4
	v_add_f32_e32 v8, v9, v8
	v_add_f32_e32 v14, v14, v8
	v_xor_b32_e32 v203, 16, v192
	v_xor_b32_e32 v157, 32, v192
	v_lshlrev_b32_e32 v203, 2, v203
	v_lshlrev_b32_e32 v157, 2, v157
	ds_bpermute_b32 v127, v203, v126
	ds_bpermute_b32 v111, v203, v110
	ds_bpermute_b32 v95, v203, v94
	ds_bpermute_b32 v79, v203, v78
	ds_bpermute_b32 v63, v203, v62
	ds_bpermute_b32 v47, v203, v46
	ds_bpermute_b32 v31, v203, v30
	ds_bpermute_b32 v15, v203, v14
	s_waitcnt lgkmcnt(0)
	v_add_f32_e32 v126, v126, v127
	v_add_f32_e32 v110, v110, v111
	v_add_f32_e32 v94, v94, v95
	v_add_f32_e32 v78, v78, v79
	v_add_f32_e32 v62, v62, v63
	v_add_f32_e32 v46, v46, v47
	v_add_f32_e32 v30, v30, v31
	v_add_f32_e32 v14, v14, v15
	ds_bpermute_b32 v127, v157, v126
	ds_bpermute_b32 v111, v157, v110
	ds_bpermute_b32 v95, v157, v94
	ds_bpermute_b32 v79, v157, v78
	ds_bpermute_b32 v63, v157, v62
	ds_bpermute_b32 v47, v157, v46
	ds_bpermute_b32 v31, v157, v30
	ds_bpermute_b32 v15, v157, v14
	s_waitcnt lgkmcnt(0)
	v_add_f32_e32 v126, v126, v127
	v_add_f32_e32 v110, v110, v111
	v_add_f32_e32 v94, v94, v95
	v_add_f32_e32 v78, v78, v79
	v_add_f32_e32 v62, v62, v63
	v_add_f32_e32 v46, v46, v47
	v_add_f32_e32 v30, v30, v31
	v_add_f32_e32 v14, v14, v15
	s_lshl_b32 s40, s54, 4
	s_lshl_b32 s41, s60, 2
	s_add_i32 s40, s40, s41
	s_addk_i32 s40, 0x1000
	v_lshl_add_u32 v246, v156, 7, s40
	v_add_u32_e32 v247, 0x4000, v246
	s_and_saveexec_b64 s[40:41], s[42:43]
	global_store_dword v246, v126, s[10:11] offset:-4096
	global_store_dword v246, v110, s[10:11] offset:-2048
	global_store_dword v246, v94, s[10:11]
	global_store_dword v246, v78, s[10:11] offset:2048
	global_store_dword v247, v62, s[10:11] offset:-4096
	global_store_dword v247, v46, s[10:11] offset:-2048
	global_store_dword v247, v30, s[10:11]
	global_store_dword v247, v14, s[10:11] offset:2048
	s_or_b64 exec, exec, s[40:41]
	s_andn2_b64 vcc, exec, s[44:45]
	s_mov_b64 s[40:41], -1
	s_cbranch_vccnz .LBB0_90
	s_andn2_b64 vcc, exec, s[0:1]
	s_cbranch_vccnz .LBB0_89
	s_nop 0
	s_branch .LBB0_89

; #define PG8_STAGE(bufoff, gbase, voff) do { _Pragma("unroll") for (int _i = 0; _i < 2; ++_i) \
;         __builtin_amdgcn_global_load_lds((const unsigned*)((const char*)(gbase) + (voff)[_i]), (PG8_LAS unsigned*)(lds + (bufoff) + ldsw + _i * 8192), 16, 0, 0); } while (0)
; #define PG8_LDA(dst, b, h) do { _Pragma("unroll") for (int m = 0; m < 4; ++m) _Pragma("unroll") for (int k = 0; k < 2; ++k) dst[m][k] = *(const PG8_LAS bf16x8*)(lds + PG8_SA(b, h) + aoff + m * 2048 + k * 1024); } while (0)
; #define PG8_LDB(dst, b, h) do { _Pragma("unroll") for (int n = 0; n < 2; ++n) _Pragma("unroll") for (int k = 0; k < 2; ++k) dst[n][k] = *(const PG8_LAS bf16x8*)(lds + PG8_SB(b, h) + boff + n * 2048 + k * 1024); } while (0)
; template <class Epi, class Sched, bool ALIGN_EPI = false, bool SP2 = false>
; __device__ __forceinline__ void gemm_phase(PG8_LAS unsigned char* lds, const Gemm g, const Sched& S, const Epi& E) {
;     ...
;         for (int t = 0; t < nt; t += 2) {
;             const bool last = (t == nt - 2);
;             const char* a1 = cA + (size_t)(t + 1) * kstep;
;             const char* a2 = last ? nA : cA + (size_t)(t + 2) * kstep; const char* b2 = last ? nB : cB + (size_t)(t + 2) * kstep;
;             const char* a3 = a2 + kstep; const char* b3 = b2 + kstep;
;             if (last && has_next) S.a_ready(nxt);
;             if constexpr (SP2) {
;             PG8_LDB(B0, 0, 0); PG8_LDB(B1, 0, 1); PG8_SCHED; PG8_LDA(At, 0, 0); PG8_STAGE(PG8_SA(1, 1), a1 + hstep, voffA);
;             PG8_WAIT_V(8); PG8_WAIT_L(0); PG8_BAR; PG8_MMA(0, 0, At, B0); PG8_MMA(0, 1, At, B1); PG8_BAR; PG8_SCHED;
;             PG8_LDA(At, 0, 1); PG8_STAGE(PG8_SB(0, 0), b2, voffB); PG8_STAGE(PG8_SB(0, 1), b2 + hstep, voffB); PG8_STAGE(PG8_SA(0, 0), a2, voffA);
;             PG8_WAIT_V(8); PG8_WAIT_L(0); PG8_BAR; PG8_MMA(1, 0, At, B0); PG8_MMA(1, 1, At, B1); PG8_BAR; PG8_SCHED;
;             PG8_LDB(B0, 1, 0); PG8_LDB(B1, 1, 1); PG8_SCHED; PG8_LDA(At, 1, 0); PG8_STAGE(PG8_SA(0, 1), a2 + hstep, voffA);
;             PG8_WAIT_V(8); PG8_WAIT_L(0); PG8_BAR; PG8_MMA(0, 0, At, B0); PG8_MMA(0, 1, At, B1); PG8_BAR; PG8_SCHED;
;             PG8_LDA(At, 1, 1); PG8_STAGE(PG8_SB(1, 0), b3, voffB); PG8_STAGE(PG8_SB(1, 1), b3 + hstep, voffB); PG8_STAGE(PG8_SA(1, 0), a3, voffA);
;             PG8_WAIT_V(8); PG8_WAIT_L(0); PG8_BAR; PG8_MMA(1, 0, At, B0); PG8_MMA(1, 1, At, B1); PG8_BAR; PG8_SCHED;
.LBB0_136:
	s_add_u32 s18, s58, 0xfffe0080
	s_addc_u32 s19, s59, -1
	s_add_i32 s46, 0, 0x10000
	s_cmp_eq_u32 s79, 4
	s_cselect_b32 s63, s37, s19
	s_cselect_b32 s62, s73, s18
	s_cselect_b32 s19, s11, s78
	s_cselect_b32 s18, s84, s85
	s_add_i32 s76, 0, 0x14000
	v_add_u32_e32 v172, s46, v1
	v_add_u32_e32 v203, s76, v1
	ds_read_b128 v[160:163], v172
	ds_read_b128 v[164:167], v172 offset:1024
	ds_read_b128 v[168:171], v172 offset:2048
	ds_read_b128 v[172:175], v172 offset:3072
	ds_read_b128 v[176:179], v203
	ds_read_b128 v[180:183], v203 offset:1024
	ds_read_b128 v[184:187], v203 offset:2048
	ds_read_b128 v[204:207], v203 offset:3072
	v_lshl_add_u64 v[240:241], s[58:59], 0, v[156:157]
	s_add_i32 m0, s5, 0xc000
	ds_read_b128 v[208:211], v143
	ds_read_b128 v[212:215], v143 offset:1024
	ds_read_b128 v[216:219], v143 offset:2048
	ds_read_b128 v[220:223], v143 offset:3072
	ds_read_b128 v[224:227], v143 offset:4096
	ds_read_b128 v[228:231], v143 offset:5120
	ds_read_b128 v[232:235], v143 offset:6144
	ds_read_b128 v[236:239], v143 offset:7168
	global_load_lds_dwordx4 v[240:241], off
	v_lshl_add_u64 v[240:241], s[58:59], 0, v[158:159]
	s_add_i32 m0, s5, 0xe000
	s_nop 0
	global_load_lds_dwordx4 v[240:241], off
	s_nop 0
	s_waitcnt vmcnt(8)
	s_waitcnt lgkmcnt(0)
	s_setprio 1
	s_barrier
	v_mfma_f32_16x16x32_bf16 v[126:129], v[160:163], v[208:211], v[126:129]
	v_mfma_f32_16x16x32_bf16 v[122:125], v[168:171], v[208:211], v[122:125]
	v_mfma_f32_16x16x32_bf16 v[110:113], v[160:163], v[216:219], v[110:113]
	v_mfma_f32_16x16x32_bf16 v[106:109], v[168:171], v[216:219], v[106:109]
	v_mfma_f32_16x16x32_bf16 v[94:97], v[160:163], v[224:227], v[94:97]
	v_mfma_f32_16x16x32_bf16 v[90:93], v[168:171], v[224:227], v[90:93]
	v_mfma_f32_16x16x32_bf16 v[78:81], v[160:163], v[232:235], v[78:81]
	v_mfma_f32_16x16x32_bf16 v[74:77], v[168:171], v[232:235], v[74:77]
	s_setprio 0
	s_setprio 1
	v_mfma_f32_16x16x32_bf16 v[126:129], v[164:167], v[212:215], v[126:129]
	v_mfma_f32_16x16x32_bf16 v[122:125], v[172:175], v[212:215], v[122:125]
	v_mfma_f32_16x16x32_bf16 v[110:113], v[164:167], v[220:223], v[110:113]
	v_mfma_f32_16x16x32_bf16 v[106:109], v[172:175], v[220:223], v[106:109]
	v_mfma_f32_16x16x32_bf16 v[94:97], v[164:167], v[228:231], v[94:97]
	v_mfma_f32_16x16x32_bf16 v[90:93], v[172:175], v[228:231], v[90:93]
	v_mfma_f32_16x16x32_bf16 v[78:81], v[164:167], v[236:239], v[78:81]
	v_mfma_f32_16x16x32_bf16 v[74:77], v[172:175], v[236:239], v[74:77]
	s_setprio 0
	s_setprio 1
	v_mfma_f32_16x16x32_bf16 v[118:121], v[176:179], v[208:211], v[118:121]
	v_mfma_f32_16x16x32_bf16 v[114:117], v[184:187], v[208:211], v[114:117]
	v_mfma_f32_16x16x32_bf16 v[102:105], v[176:179], v[216:219], v[102:105]
	v_mfma_f32_16x16x32_bf16 v[98:101], v[184:187], v[216:219], v[98:101]
	v_mfma_f32_16x16x32_bf16 v[86:89], v[176:179], v[224:227], v[86:89]
	v_mfma_f32_16x16x32_bf16 v[82:85], v[184:187], v[224:227], v[82:85]
	v_mfma_f32_16x16x32_bf16 v[70:73], v[176:179], v[232:235], v[70:73]
	v_mfma_f32_16x16x32_bf16 v[66:69], v[184:187], v[232:235], v[66:69]
	s_setprio 0
	s_setprio 1
	v_mfma_f32_16x16x32_bf16 v[118:121], v[180:183], v[212:215], v[118:121]
	v_mfma_f32_16x16x32_bf16 v[114:117], v[204:207], v[212:215], v[114:117]
	v_mfma_f32_16x16x32_bf16 v[102:105], v[180:183], v[220:223], v[102:105]
	v_mfma_f32_16x16x32_bf16 v[98:101], v[204:207], v[220:223], v[98:101]
	v_mfma_f32_16x16x32_bf16 v[86:89], v[180:183], v[228:231], v[86:89]
	v_mfma_f32_16x16x32_bf16 v[82:85], v[204:207], v[228:231], v[82:85]
	v_mfma_f32_16x16x32_bf16 v[70:73], v[180:183], v[236:239], v[70:73]
	v_mfma_f32_16x16x32_bf16 v[66:69], v[204:207], v[236:239], v[66:69]
	s_setprio 0
	s_barrier
	s_add_i32 s46, s46, s4
	v_lshl_add_u64 v[240:241], s[18:19], 0, v[148:149]
	s_mov_b32 m0, s46
	ds_read_b128 v[208:211], v143 offset:16384
	ds_read_b128 v[212:215], v143 offset:17408
	ds_read_b128 v[216:219], v143 offset:18432
	ds_read_b128 v[220:223], v143 offset:19456
	ds_read_b128 v[224:227], v143 offset:20480
	ds_read_b128 v[228:231], v143 offset:21504
	ds_read_b128 v[232:235], v143 offset:22528
	ds_read_b128 v[236:239], v143 offset:23552
	global_load_lds_dwordx4 v[240:241], off
	s_add_i32 m0, s46, 0x2000
	s_add_u32 s46, s18, 0x20000
	v_lshl_add_u64 v[242:243], s[18:19], 0, v[144:145]
	s_addc_u32 s47, s19, 0
	s_add_i32 s76, s76, s4
	global_load_lds_dwordx4 v[242:243], off
	v_lshl_add_u64 v[244:245], s[46:47], 0, v[148:149]
	s_mov_b32 m0, s76
	v_lshl_add_u64 v[246:247], s[62:63], 0, v[146:147]
	global_load_lds_dwordx4 v[244:245], off
	v_lshl_add_u64 v[244:245], s[46:47], 0, v[144:145]
	s_add_i32 m0, s76, 0x2000
	s_nop 0
	global_load_lds_dwordx4 v[244:245], off
	v_lshl_add_u64 v[244:245], s[62:63], 0, v[150:151]
	s_mov_b32 m0, s5
	s_nop 0
	global_load_lds_dwordx4 v[244:245], off
	s_mov_b32 m0, s28
	s_nop 0
	global_load_lds_dwordx4 v[246:247], off
	s_waitcnt vmcnt(8)
	s_waitcnt lgkmcnt(0)
	s_setprio 1
	s_barrier
; #define PG8_STAGE(bufoff, gbase, voff) do { _Pragma("unroll") for (int _i = 0; _i < 2; ++_i) \
;         __builtin_amdgcn_global_load_lds((const unsigned*)((const char*)(gbase) + (voff)[_i]), (PG8_LAS unsigned*)(lds + (bufoff) + ldsw + _i * 8192), 16, 0, 0); } while (0)
; #define PG8_LDA(dst, b, h) do { _Pragma("unroll") for (int m = 0; m < 4; ++m) _Pragma("unroll") for (int k = 0; k < 2; ++k) dst[m][k] = *(const PG8_LAS bf16x8*)(lds + PG8_SA(b, h) + aoff + m * 2048 + k * 1024); } while (0)
; #define PG8_LDB(dst, b, h) do { _Pragma("unroll") for (int n = 0; n < 2; ++n) _Pragma("unroll") for (int k = 0; k < 2; ++k) dst[n][k] = *(const PG8_LAS bf16x8*)(lds + PG8_SB(b, h) + boff + n * 2048 + k * 1024); } while (0)
; #define PG8_MMA(ai, bj, At, Bt) do { __builtin_amdgcn_s_setprio(1); _Pragma("unroll") for (int m = 0; m < 4; ++m) _Pragma("unroll") for (int n = 0; n < 2; ++n) _Pragma("unroll") for (int k = 0; k < 2; ++k) \
;         acc[ai][bj][m][n] = __builtin_amdgcn_mfma_f32_16x16x32_bf16(Bt[n][k], At[m][k], acc[ai][bj][m][n], 0, 0, 0); __builtin_amdgcn_s_setprio(0); } while (0)
; #define PG8_WAIT_V(n) asm volatile("s_waitcnt vmcnt(" #n ")" ::: "memory")
; #define PG8_WAIT_L(n) asm volatile("s_waitcnt lgkmcnt(" #n ")" ::: "memory")
; #define PG8_BAR __builtin_amdgcn_s_barrier()
; #define PG8_SCHED __builtin_amdgcn_sched_barrier(0)
; template <class Epi, class Sched, bool ALIGN_EPI = false, bool SP2 = false>
; __device__ __forceinline__ void gemm_phase(PG8_LAS unsigned char* lds, const Gemm g, const Sched& S, const Epi& E) {
;     ...
;             PG8_WAIT_V(8); PG8_WAIT_L(0); PG8_BAR; PG8_MMA(1, 0, At, B0); PG8_MMA(1, 1, At, B1); PG8_BAR; PG8_SCHED;
;             PG8_LDB(B0, 1, 0); PG8_LDB(B1, 1, 1); PG8_SCHED; PG8_LDA(At, 1, 0); PG8_STAGE(PG8_SA(0, 1), a2 + hstep, voffA);
;             PG8_WAIT_V(8); PG8_WAIT_L(0); PG8_BAR; PG8_MMA(0, 0, At, B0); PG8_MMA(0, 1, At, B1); PG8_BAR; PG8_SCHED;
;             PG8_LDA(At, 1, 1); PG8_STAGE(PG8_SB(1, 0), b3, voffB); PG8_STAGE(PG8_SB(1, 1), b3 + hstep, voffB); PG8_STAGE(PG8_SA(1, 0), a3, voffA);
;             PG8_WAIT_V(8); PG8_WAIT_L(0); PG8_BAR; PG8_MMA(1, 0, At, B0); PG8_MMA(1, 1, At, B1); PG8_BAR; PG8_SCHED;
	v_mfma_f32_16x16x32_bf16 v[62:65], v[160:163], v[208:211], v[62:65]
	v_mfma_f32_16x16x32_bf16 v[58:61], v[168:171], v[208:211], v[58:61]
	v_mfma_f32_16x16x32_bf16 v[46:49], v[160:163], v[216:219], v[46:49]
	v_mfma_f32_16x16x32_bf16 v[42:45], v[168:171], v[216:219], v[42:45]
	v_mfma_f32_16x16x32_bf16 v[30:33], v[160:163], v[224:227], v[30:33]
	v_mfma_f32_16x16x32_bf16 v[26:29], v[168:171], v[224:227], v[26:29]
	v_mfma_f32_16x16x32_bf16 v[14:17], v[160:163], v[232:235], v[14:17]
	v_mfma_f32_16x16x32_bf16 v[10:13], v[168:171], v[232:235], v[10:13]
	v_mfma_f32_16x16x32_bf16 v[62:65], v[164:167], v[212:215], v[62:65]
	v_mfma_f32_16x16x32_bf16 v[58:61], v[172:175], v[212:215], v[58:61]
	v_mfma_f32_16x16x32_bf16 v[46:49], v[164:167], v[220:223], v[46:49]
	v_mfma_f32_16x16x32_bf16 v[42:45], v[172:175], v[220:223], v[42:45]
	v_mfma_f32_16x16x32_bf16 v[30:33], v[164:167], v[228:231], v[30:33]
	v_mfma_f32_16x16x32_bf16 v[26:29], v[172:175], v[228:231], v[26:29]
	v_mfma_f32_16x16x32_bf16 v[14:17], v[164:167], v[236:239], v[14:17]
	v_mfma_f32_16x16x32_bf16 v[10:13], v[172:175], v[236:239], v[10:13]
	v_mfma_f32_16x16x32_bf16 v[54:57], v[176:179], v[208:211], v[54:57]
	v_mfma_f32_16x16x32_bf16 v[50:53], v[184:187], v[208:211], v[50:53]
	v_mfma_f32_16x16x32_bf16 v[38:41], v[176:179], v[216:219], v[38:41]
	v_mfma_f32_16x16x32_bf16 v[34:37], v[184:187], v[216:219], v[34:37]
	v_mfma_f32_16x16x32_bf16 v[22:25], v[176:179], v[224:227], v[22:25]
	v_mfma_f32_16x16x32_bf16 v[18:21], v[184:187], v[224:227], v[18:21]
	v_mfma_f32_16x16x32_bf16 v[6:9], v[176:179], v[232:235], v[6:9]
	v_mfma_f32_16x16x32_bf16 v[2:5], v[184:187], v[232:235], v[2:5]
	v_mfma_f32_16x16x32_bf16 v[54:57], v[180:183], v[212:215], v[54:57]
	v_mfma_f32_16x16x32_bf16 v[50:53], v[204:207], v[212:215], v[50:53]
	v_mfma_f32_16x16x32_bf16 v[38:41], v[180:183], v[220:223], v[38:41]
	v_mfma_f32_16x16x32_bf16 v[34:37], v[204:207], v[220:223], v[34:37]
	v_mfma_f32_16x16x32_bf16 v[22:25], v[180:183], v[228:231], v[22:25]
	v_mfma_f32_16x16x32_bf16 v[18:21], v[204:207], v[228:231], v[18:21]
	v_mfma_f32_16x16x32_bf16 v[6:9], v[180:183], v[236:239], v[6:9]
	v_mfma_f32_16x16x32_bf16 v[2:5], v[204:207], v[236:239], v[2:5]
	s_setprio 0
	s_barrier
	s_add_i32 s76, 0, 0x18000
	s_add_i32 s77, 0, 0x1c000
	v_add_u32_e32 v172, s76, v1
	v_add_u32_e32 v203, s77, v1
	ds_read_b128 v[160:163], v172
	ds_read_b128 v[164:167], v172 offset:1024
	ds_read_b128 v[168:171], v172 offset:2048
	ds_read_b128 v[172:175], v172 offset:3072
	ds_read_b128 v[176:179], v203
	ds_read_b128 v[180:183], v203 offset:1024
	ds_read_b128 v[184:187], v203 offset:2048
	ds_read_b128 v[204:207], v203 offset:3072
	s_add_u32 s46, s62, 0x20000
	s_addc_u32 s47, s63, 0
	s_mov_b32 m0, s30
	v_lshl_add_u64 v[248:249], s[46:47], 0, v[150:151]
	ds_read_b128 v[208:211], v143 offset:32768
	ds_read_b128 v[212:215], v143 offset:33792
	ds_read_b128 v[216:219], v143 offset:34816
	ds_read_b128 v[220:223], v143 offset:35840
	ds_read_b128 v[224:227], v143 offset:36864
	ds_read_b128 v[228:231], v143 offset:37888
	ds_read_b128 v[232:235], v143 offset:38912
	ds_read_b128 v[236:239], v143 offset:39936
	global_load_lds_dwordx4 v[248:249], off
	v_lshl_add_u64 v[248:249], s[46:47], 0, v[146:147]
	s_mov_b32 m0, s34
	s_nop 0
	global_load_lds_dwordx4 v[248:249], off
	s_waitcnt vmcnt(8)
	s_waitcnt lgkmcnt(0)
	s_setprio 1
	s_barrier
	v_mfma_f32_16x16x32_bf16 v[126:129], v[160:163], v[208:211], v[126:129]
	v_mfma_f32_16x16x32_bf16 v[122:125], v[168:171], v[208:211], v[122:125]
	v_mfma_f32_16x16x32_bf16 v[110:113], v[160:163], v[216:219], v[110:113]
	v_mfma_f32_16x16x32_bf16 v[106:109], v[168:171], v[216:219], v[106:109]
	v_mfma_f32_16x16x32_bf16 v[94:97], v[160:163], v[224:227], v[94:97]
	v_mfma_f32_16x16x32_bf16 v[90:93], v[168:171], v[224:227], v[90:93]
	v_mfma_f32_16x16x32_bf16 v[78:81], v[160:163], v[232:235], v[78:81]
	v_mfma_f32_16x16x32_bf16 v[74:77], v[168:171], v[232:235], v[74:77]
	s_setprio 0
	s_setprio 1
	v_mfma_f32_16x16x32_bf16 v[126:129], v[164:167], v[212:215], v[126:129]
	v_mfma_f32_16x16x32_bf16 v[122:125], v[172:175], v[212:215], v[122:125]
	v_mfma_f32_16x16x32_bf16 v[110:113], v[164:167], v[220:223], v[110:113]
	v_mfma_f32_16x16x32_bf16 v[106:109], v[172:175], v[220:223], v[106:109]
	v_mfma_f32_16x16x32_bf16 v[94:97], v[164:167], v[228:231], v[94:97]
	v_mfma_f32_16x16x32_bf16 v[90:93], v[172:175], v[228:231], v[90:93]
	v_mfma_f32_16x16x32_bf16 v[78:81], v[164:167], v[236:239], v[78:81]
	v_mfma_f32_16x16x32_bf16 v[74:77], v[172:175], v[236:239], v[74:77]
	s_setprio 0
	s_setprio 1
	v_mfma_f32_16x16x32_bf16 v[118:121], v[176:179], v[208:211], v[118:121]
	v_mfma_f32_16x16x32_bf16 v[114:117], v[184:187], v[208:211], v[114:117]
	v_mfma_f32_16x16x32_bf16 v[102:105], v[176:179], v[216:219], v[102:105]
	v_mfma_f32_16x16x32_bf16 v[98:101], v[184:187], v[216:219], v[98:101]
	v_mfma_f32_16x16x32_bf16 v[86:89], v[176:179], v[224:227], v[86:89]
	v_mfma_f32_16x16x32_bf16 v[82:85], v[184:187], v[224:227], v[82:85]
	v_mfma_f32_16x16x32_bf16 v[70:73], v[176:179], v[232:235], v[70:73]
	v_mfma_f32_16x16x32_bf16 v[66:69], v[184:187], v[232:235], v[66:69]
	s_setprio 0
	s_setprio 1
	v_mfma_f32_16x16x32_bf16 v[118:121], v[180:183], v[212:215], v[118:121]
	v_mfma_f32_16x16x32_bf16 v[114:117], v[204:207], v[212:215], v[114:117]
	v_mfma_f32_16x16x32_bf16 v[102:105], v[180:183], v[220:223], v[102:105]
	v_mfma_f32_16x16x32_bf16 v[98:101], v[204:207], v[220:223], v[98:101]
	v_mfma_f32_16x16x32_bf16 v[86:89], v[180:183], v[228:231], v[86:89]
	v_mfma_f32_16x16x32_bf16 v[82:85], v[204:207], v[228:231], v[82:85]
	v_mfma_f32_16x16x32_bf16 v[70:73], v[180:183], v[236:239], v[70:73]
	v_mfma_f32_16x16x32_bf16 v[66:69], v[204:207], v[236:239], v[66:69]
	s_setprio 0
	s_barrier
; #define PG8_STAGE(bufoff, gbase, voff) do { _Pragma("unroll") for (int _i = 0; _i < 2; ++_i) \
;         __builtin_amdgcn_global_load_lds((const unsigned*)((const char*)(gbase) + (voff)[_i]), (PG8_LAS unsigned*)(lds + (bufoff) + ldsw + _i * 8192), 16, 0, 0); } while (0)
; #define PG8_LDA(dst, b, h) do { _Pragma("unroll") for (int m = 0; m < 4; ++m) _Pragma("unroll") for (int k = 0; k < 2; ++k) dst[m][k] = *(const PG8_LAS bf16x8*)(lds + PG8_SA(b, h) + aoff + m * 2048 + k * 1024); } while (0)
; #define PG8_LDB(dst, b, h) do { _Pragma("unroll") for (int n = 0; n < 2; ++n) _Pragma("unroll") for (int k = 0; k < 2; ++k) dst[n][k] = *(const PG8_LAS bf16x8*)(lds + PG8_SB(b, h) + boff + n * 2048 + k * 1024); } while (0)
; #define PG8_WAIT_V(n) asm volatile("s_waitcnt vmcnt(" #n ")" ::: "memory")
;     __device__ __forceinline__ void operator()(const f32x4 (&acc)[2][2][4][2], const Unit& u, int wr, int wc, int fr, int fq) const {
;         const int row0 = u.pm * BM + wr * 64 + fr, col0 = u.pn * BM + wc * 32 + 8 * fq;
;         const int tidn = (wr * 4 + wc) * 64 + fq * 16 + fr;
;         const u32x4* gp = (const u32x4*)G8 + (size_t)(u.pm * 16 + gsel + u.pn) * 8 * 512 + tidn;
;         u32x4* mp = M1 + (size_t)(u.pm * 8 + u.pn) * 16 * 512 + tidn;
;         constexpr float K255 = 1.0f / 255.0f;
; #pragma unroll
;         for (int ai = 0; ai < 2; ++ai)
; #pragma unroll
;             for (int m = 0; m < 4; ++m) { const size_t row = (size_t)(row0 + ai * HALF + m * 16);
;                 const u32x4 gw = gp[(ai * 4 + m) * 512];
; template <class Epi, class Sched, bool ALIGN_EPI = false, bool SP2 = false>
; __device__ __forceinline__ void gemm_phase(PG8_LAS unsigned char* lds, const Gemm g, const Sched& S, const Epi& E) {
;     ...
;             PG8_WAIT_V(8); PG8_WAIT_L(0); PG8_BAR; PG8_MMA(1, 0, At, B0); PG8_MMA(1, 1, At, B1); PG8_BAR; PG8_SCHED;
;             PG8_LDB(B0, 1, 0); PG8_LDB(B1, 1, 1); PG8_SCHED; PG8_LDA(At, 1, 0); PG8_STAGE(PG8_SA(0, 1), a2 + hstep, voffA);
;             PG8_WAIT_V(8); PG8_WAIT_L(0); PG8_BAR; PG8_MMA(0, 0, At, B0); PG8_MMA(0, 1, At, B1); PG8_BAR; PG8_SCHED;
;             PG8_LDA(At, 1, 1); PG8_STAGE(PG8_SB(1, 0), b3, voffB); PG8_STAGE(PG8_SB(1, 1), b3 + hstep, voffB); PG8_STAGE(PG8_SA(1, 0), a3, voffA);
;             PG8_WAIT_V(8); PG8_WAIT_L(0); PG8_BAR; PG8_MMA(1, 0, At, B0); PG8_MMA(1, 1, At, B1); PG8_BAR; PG8_SCHED;
	s_add_i32 s46, s76, s4
	v_lshl_add_u64 v[240:241], v[240:241], 0, s[68:69]
	s_mov_b32 m0, s46
	ds_read_b128 v[208:211], v143 offset:49152
	ds_read_b128 v[212:215], v143 offset:50176
	ds_read_b128 v[216:219], v143 offset:51200
	ds_read_b128 v[220:223], v143 offset:52224
	ds_read_b128 v[224:227], v143 offset:53248
	ds_read_b128 v[228:231], v143 offset:54272
	ds_read_b128 v[232:235], v143 offset:55296
	ds_read_b128 v[236:239], v143 offset:56320
	global_load_lds_dwordx4 v[240:241], off
	s_add_i32 m0, s46, 0x2000
	s_add_u32 s18, s18, 0x20080
	v_lshl_add_u64 v[240:241], v[242:243], 0, s[68:69]
	s_addc_u32 s19, s19, 0
	s_add_i32 s46, s77, s4
	global_load_lds_dwordx4 v[240:241], off
	v_lshl_add_u64 v[240:241], s[18:19], 0, v[148:149]
	s_mov_b32 m0, s46
	s_nop 0
	global_load_lds_dwordx4 v[240:241], off
	v_lshl_add_u64 v[240:241], s[18:19], 0, v[144:145]
	s_add_i32 m0, s46, 0x2000
	s_nop 0
	global_load_lds_dwordx4 v[240:241], off
	v_lshl_add_u64 v[240:241], v[244:245], 0, s[68:69]
	s_mov_b32 m0, s54
	s_nop 0
	global_load_lds_dwordx4 v[240:241], off
	v_lshl_add_u64 v[240:241], v[246:247], 0, s[68:69]
	s_mov_b32 m0, s57
	s_nop 0
	global_load_lds_dwordx4 v[240:241], off
	s_nop 0
	s_waitcnt vmcnt(8)
	s_waitcnt lgkmcnt(0)
	s_setprio 1
	s_barrier
	v_mfma_f32_16x16x32_bf16 v[62:65], v[160:163], v[208:211], v[62:65]
	v_mfma_f32_16x16x32_bf16 v[58:61], v[168:171], v[208:211], v[58:61]
	v_mfma_f32_16x16x32_bf16 v[46:49], v[160:163], v[216:219], v[46:49]
	v_mfma_f32_16x16x32_bf16 v[42:45], v[168:171], v[216:219], v[42:45]
	v_mfma_f32_16x16x32_bf16 v[30:33], v[160:163], v[224:227], v[30:33]
	v_mfma_f32_16x16x32_bf16 v[26:29], v[168:171], v[224:227], v[26:29]
	v_mfma_f32_16x16x32_bf16 v[14:17], v[160:163], v[232:235], v[14:17]
	v_mfma_f32_16x16x32_bf16 v[10:13], v[168:171], v[232:235], v[10:13]
	v_mfma_f32_16x16x32_bf16 v[62:65], v[164:167], v[212:215], v[62:65]
	v_mfma_f32_16x16x32_bf16 v[58:61], v[172:175], v[212:215], v[58:61]
	v_mfma_f32_16x16x32_bf16 v[46:49], v[164:167], v[220:223], v[46:49]
	v_mfma_f32_16x16x32_bf16 v[42:45], v[172:175], v[220:223], v[42:45]
	v_mfma_f32_16x16x32_bf16 v[30:33], v[164:167], v[228:231], v[30:33]
	v_mfma_f32_16x16x32_bf16 v[26:29], v[172:175], v[228:231], v[26:29]
	v_mfma_f32_16x16x32_bf16 v[14:17], v[164:167], v[236:239], v[14:17]
	v_mfma_f32_16x16x32_bf16 v[10:13], v[172:175], v[236:239], v[10:13]
	v_mfma_f32_16x16x32_bf16 v[54:57], v[176:179], v[208:211], v[54:57]
	v_mfma_f32_16x16x32_bf16 v[50:53], v[184:187], v[208:211], v[50:53]
	v_mfma_f32_16x16x32_bf16 v[38:41], v[176:179], v[216:219], v[38:41]
	v_mfma_f32_16x16x32_bf16 v[34:37], v[184:187], v[216:219], v[34:37]
	v_mfma_f32_16x16x32_bf16 v[22:25], v[176:179], v[224:227], v[22:25]
	v_mfma_f32_16x16x32_bf16 v[18:21], v[184:187], v[224:227], v[18:21]
	v_mfma_f32_16x16x32_bf16 v[6:9], v[176:179], v[232:235], v[6:9]
	v_mfma_f32_16x16x32_bf16 v[2:5], v[184:187], v[232:235], v[2:5]
	v_mfma_f32_16x16x32_bf16 v[54:57], v[180:183], v[212:215], v[54:57]
	v_mfma_f32_16x16x32_bf16 v[50:53], v[204:207], v[212:215], v[50:53]
	v_mfma_f32_16x16x32_bf16 v[38:41], v[180:183], v[220:223], v[38:41]
	v_mfma_f32_16x16x32_bf16 v[34:37], v[204:207], v[220:223], v[34:37]
	v_mfma_f32_16x16x32_bf16 v[22:25], v[180:183], v[228:231], v[22:25]
	v_mfma_f32_16x16x32_bf16 v[18:21], v[204:207], v[228:231], v[18:21]
	v_mfma_f32_16x16x32_bf16 v[6:9], v[180:183], v[236:239], v[6:9]
	v_mfma_f32_16x16x32_bf16 v[2:5], v[204:207], v[236:239], v[2:5]
	s_setprio 0
	s_barrier
	s_add_i32 s79, s79, 2
	s_add_u32 s58, s58, 0x100
	s_addc_u32 s59, s59, 0
	s_add_u32 s85, s85, 0x100
	s_addc_u32 s78, s78, 0
	s_cmp_gt_u32 s79, 5
	s_cbranch_scc0 .LBB0_136
	s_mov_b32 s32, 1
	s_lshl_b32 s11, s67, 4
	s_add_i32 s18, s11, s86
	s_ashr_i32 s19, s18, 31
	s_lshl_b64 s[46:47], s[18:19], 16
	v_lshl_add_u64 v[162:163], v[152:153], 0, s[46:47]
	s_lshl_b32 s11, s67, 3
	s_sub_i32 s18, s18, s11
	s_ashr_i32 s19, s18, 31
	s_lshl_b64 s[18:19], s[18:19], 17
	v_lshl_add_u64 v[160:161], v[154:155], 0, s[18:19]
	s_mov_b32 s47, 0
	global_load_dwordx4 v[168:171], v[162:163], off
	s_mov_b32 s46, 0x2000
	v_lshl_add_u64 v[164:165], v[162:163], 0, s[46:47]
	global_load_dwordx4 v[172:175], v[164:165], off
	s_mov_b32 s46, 0x4000
	v_lshl_add_u64 v[164:165], v[162:163], 0, s[46:47]
	global_load_dwordx4 v[176:179], v[164:165], off
	s_mov_b32 s46, 0x6000
	v_lshl_add_u64 v[164:165], v[162:163], 0, s[46:47]
	global_load_dwordx4 v[180:183], v[164:165], off
	s_mov_b32 s46, 0x8000
	v_lshl_add_u64 v[164:165], v[162:163], 0, s[46:47]
	global_load_dwordx4 v[184:187], v[164:165], off
	s_mov_b32 s46, 0xa000
	v_lshl_add_u64 v[164:165], v[162:163], 0, s[46:47]
	global_load_dwordx4 v[204:207], v[164:165], off
	s_mov_b32 s46, 0xc000
	v_lshl_add_u64 v[164:165], v[162:163], 0, s[46:47]
	global_load_dwordx4 v[208:211], v[164:165], off
	s_mov_b32 s46, 0xe000
	v_lshl_add_u64 v[164:165], v[162:163], 0, s[46:47]
	global_load_dwordx4 v[212:215], v[164:165], off
	s_andn2_b64 vcc, s[8:9], s[42:43]
	s_cbranch_vccz .Lg0_nobar
	s_barrier
; __device__ __forceinline__ unsigned cvt_pk_bf16(float lo, float hi) { const f32x2c_t v = {lo, hi}; const bf16x2c_t b = __builtin_convertvector(v, bf16x2c_t); return __builtin_bit_cast(unsigned, b); }
; __device__ __forceinline__ float bf_lo(unsigned w) { return __uint_as_float(w << 16); }
; __device__ __forceinline__ float bf_hi(unsigned w) { return __uint_as_float(w & 0xffff0000u); }
;     __device__ __forceinline__ void operator()(const f32x4 (&acc)[2][2][4][2], const Unit& u, int wr, int wc, int fr, int fq) const {
;     ...
;             for (int m = 0; m < 4; ++m) { const size_t row = (size_t)(row0 + ai * HALF + m * 16);
;                 const u32x4 gw = gp[(ai * 4 + m) * 512];
;                 u32x4 pw[2];
;                 if (SECOND) { pw[0] = mp[((ai * 4 + m) * 2 + 0) * 512]; pw[1] = mp[((ai * 4 + m) * 2 + 1) * 512]; }
; #pragma unroll
;                 for (int bj = 0; bj < 2; ++bj) { const unsigned gx = bj ? gw.z : gw.x, gy = bj ? gw.w : gw.y;
;                     const f32x4 g0 = (f32x4){(float)(gx & 255u), (float)((gx >> 8) & 255u), (float)((gx >> 16) & 255u), (float)(gx >> 24)} * K255,
;                                 g1 = (f32x4){(float)(gy & 255u), (float)((gy >> 8) & 255u), (float)((gy >> 16) & 255u), (float)(gy >> 24)} * K255;
;                     f32x4 v0 = acc[ai][bj][m][0] * g0, v1 = acc[ai][bj][m][1] * g1;
;                     if (SECOND) { const u32x4 p = pw[bj];
;                         v0 = v0 + (f32x4){bf_lo(p.x), bf_hi(p.x), bf_lo(p.y), bf_hi(p.y)}; v1 = v1 + (f32x4){bf_lo(p.z), bf_hi(p.z), bf_lo(p.w), bf_hi(p.w)}; }
;                     u32x4 w; w.x = cvt_pk_bf16(v0[0], v0[1]); w.y = cvt_pk_bf16(v0[2], v0[3]); w.z = cvt_pk_bf16(v1[0], v1[1]); w.w = cvt_pk_bf16(v1[2], v1[3]);
;                     if (SECOND) *(u32x4*)(MG + row * DM + col0 + bj * HALF) = w; else mp[((ai * 4 + m) * 2 + bj) * 512] = w; }
.Lg0_nobar:
	s_waitcnt vmcnt(7)
	v_cvt_f32_ubyte0_e32 v216, v168
	v_cvt_f32_ubyte1_e32 v217, v168
	v_cvt_f32_ubyte2_e32 v218, v168
	v_cvt_f32_ubyte3_e32 v219, v168
	v_cvt_f32_ubyte0_e32 v220, v169
	v_cvt_f32_ubyte1_e32 v221, v169
	v_cvt_f32_ubyte2_e32 v222, v169
	v_cvt_f32_ubyte3_e32 v223, v169
	v_pk_mul_f32 v[216:217], v[216:217], s[26:27] op_sel_hi:[1,0]
	v_pk_mul_f32 v[218:219], v[218:219], s[26:27] op_sel_hi:[1,0]
	v_pk_mul_f32 v[220:221], v[220:221], s[26:27] op_sel_hi:[1,0]
	v_pk_mul_f32 v[222:223], v[222:223], s[26:27] op_sel_hi:[1,0]
	v_pk_mul_f32 v[126:127], v[126:127], v[216:217]
	v_pk_mul_f32 v[128:129], v[128:129], v[218:219]
	v_pk_mul_f32 v[122:123], v[122:123], v[220:221]
	v_pk_mul_f32 v[124:125], v[124:125], v[222:223]
	v_cvt_pk_bf16_f32 v224, v126, v127
	v_cvt_pk_bf16_f32 v225, v128, v129
	v_cvt_pk_bf16_f32 v226, v122, v123
	v_cvt_pk_bf16_f32 v227, v124, v125
	global_store_dwordx4 v[160:161], v[224:227], off
	v_cvt_f32_ubyte0_e32 v216, v170
	v_cvt_f32_ubyte1_e32 v217, v170
	v_cvt_f32_ubyte2_e32 v218, v170
	v_cvt_f32_ubyte3_e32 v219, v170
	v_cvt_f32_ubyte0_e32 v220, v171
	v_cvt_f32_ubyte1_e32 v221, v171
	v_cvt_f32_ubyte2_e32 v222, v171
	v_cvt_f32_ubyte3_e32 v223, v171
	v_pk_mul_f32 v[216:217], v[216:217], s[26:27] op_sel_hi:[1,0]
	v_pk_mul_f32 v[218:219], v[218:219], s[26:27] op_sel_hi:[1,0]
	v_pk_mul_f32 v[220:221], v[220:221], s[26:27] op_sel_hi:[1,0]
	v_pk_mul_f32 v[222:223], v[222:223], s[26:27] op_sel_hi:[1,0]
	v_pk_mul_f32 v[118:119], v[118:119], v[216:217]
	v_pk_mul_f32 v[120:121], v[120:121], v[218:219]
	v_pk_mul_f32 v[114:115], v[114:115], v[220:221]
	v_pk_mul_f32 v[116:117], v[116:117], v[222:223]
	v_cvt_pk_bf16_f32 v228, v118, v119
	v_cvt_pk_bf16_f32 v229, v120, v121
	v_cvt_pk_bf16_f32 v230, v114, v115
	v_cvt_pk_bf16_f32 v231, v116, v117
	s_mov_b32 s46, 0x2000
	v_lshl_add_u64 v[166:167], v[160:161], 0, s[46:47]
	global_store_dwordx4 v[166:167], v[228:231], off
	s_waitcnt vmcnt(8)
	v_cvt_f32_ubyte0_e32 v216, v172
	v_cvt_f32_ubyte1_e32 v217, v172
	v_cvt_f32_ubyte2_e32 v218, v172
	v_cvt_f32_ubyte3_e32 v219, v172
	v_cvt_f32_ubyte0_e32 v220, v173
	v_cvt_f32_ubyte1_e32 v221, v173
	v_cvt_f32_ubyte2_e32 v222, v173
	v_cvt_f32_ubyte3_e32 v223, v173
	v_pk_mul_f32 v[216:217], v[216:217], s[26:27] op_sel_hi:[1,0]
	v_pk_mul_f32 v[218:219], v[218:219], s[26:27] op_sel_hi:[1,0]
	v_pk_mul_f32 v[220:221], v[220:221], s[26:27] op_sel_hi:[1,0]
	v_pk_mul_f32 v[222:223], v[222:223], s[26:27] op_sel_hi:[1,0]
	v_pk_mul_f32 v[110:111], v[110:111], v[216:217]
	v_pk_mul_f32 v[112:113], v[112:113], v[218:219]
	v_pk_mul_f32 v[106:107], v[106:107], v[220:221]
	v_pk_mul_f32 v[108:109], v[108:109], v[222:223]
	v_cvt_pk_bf16_f32 v224, v110, v111
	v_cvt_pk_bf16_f32 v225, v112, v113
	v_cvt_pk_bf16_f32 v226, v106, v107
	v_cvt_pk_bf16_f32 v227, v108, v109
	s_mov_b32 s46, 0x4000
	v_lshl_add_u64 v[166:167], v[160:161], 0, s[46:47]
	global_store_dwordx4 v[166:167], v[224:227], off
	v_cvt_f32_ubyte0_e32 v216, v174
	v_cvt_f32_ubyte1_e32 v217, v174
	v_cvt_f32_ubyte2_e32 v218, v174
	v_cvt_f32_ubyte3_e32 v219, v174
	v_cvt_f32_ubyte0_e32 v220, v175
	v_cvt_f32_ubyte1_e32 v221, v175
	v_cvt_f32_ubyte2_e32 v222, v175
	v_cvt_f32_ubyte3_e32 v223, v175
	v_pk_mul_f32 v[216:217], v[216:217], s[26:27] op_sel_hi:[1,0]
	v_pk_mul_f32 v[218:219], v[218:219], s[26:27] op_sel_hi:[1,0]
	v_pk_mul_f32 v[220:221], v[220:221], s[26:27] op_sel_hi:[1,0]
	v_pk_mul_f32 v[222:223], v[222:223], s[26:27] op_sel_hi:[1,0]
	v_pk_mul_f32 v[102:103], v[102:103], v[216:217]
	v_pk_mul_f32 v[104:105], v[104:105], v[218:219]
	v_pk_mul_f32 v[98:99], v[98:99], v[220:221]
	v_pk_mul_f32 v[100:101], v[100:101], v[222:223]
	v_cvt_pk_bf16_f32 v228, v102, v103
	v_cvt_pk_bf16_f32 v229, v104, v105
	v_cvt_pk_bf16_f32 v230, v98, v99
	v_cvt_pk_bf16_f32 v231, v100, v101
	s_mov_b32 s46, 0x6000
	v_lshl_add_u64 v[166:167], v[160:161], 0, s[46:47]
	global_store_dwordx4 v[166:167], v[228:231], off
	s_waitcnt vmcnt(9)
	v_cvt_f32_ubyte0_e32 v216, v176
	v_cvt_f32_ubyte1_e32 v217, v176
	v_cvt_f32_ubyte2_e32 v218, v176
	v_cvt_f32_ubyte3_e32 v219, v176
	v_cvt_f32_ubyte0_e32 v220, v177
	v_cvt_f32_ubyte1_e32 v221, v177
	v_cvt_f32_ubyte2_e32 v222, v177
	v_cvt_f32_ubyte3_e32 v223, v177
	v_pk_mul_f32 v[216:217], v[216:217], s[26:27] op_sel_hi:[1,0]
	v_pk_mul_f32 v[218:219], v[218:219], s[26:27] op_sel_hi:[1,0]
	v_pk_mul_f32 v[220:221], v[220:221], s[26:27] op_sel_hi:[1,0]
	v_pk_mul_f32 v[222:223], v[222:223], s[26:27] op_sel_hi:[1,0]
	v_pk_mul_f32 v[94:95], v[94:95], v[216:217]
	v_pk_mul_f32 v[96:97], v[96:97], v[218:219]
	v_pk_mul_f32 v[90:91], v[90:91], v[220:221]
	v_pk_mul_f32 v[92:93], v[92:93], v[222:223]
	v_cvt_pk_bf16_f32 v224, v94, v95
	v_cvt_pk_bf16_f32 v225, v96, v97
	v_cvt_pk_bf16_f32 v226, v90, v91
	v_cvt_pk_bf16_f32 v227, v92, v93
	s_mov_b32 s46, 0x8000
	v_lshl_add_u64 v[166:167], v[160:161], 0, s[46:47]
	global_store_dwordx4 v[166:167], v[224:227], off
	v_cvt_f32_ubyte0_e32 v216, v178
	v_cvt_f32_ubyte1_e32 v217, v178
	v_cvt_f32_ubyte2_e32 v218, v178
	v_cvt_f32_ubyte3_e32 v219, v178
	v_cvt_f32_ubyte0_e32 v220, v179
	v_cvt_f32_ubyte1_e32 v221, v179
	v_cvt_f32_ubyte2_e32 v222, v179
	v_cvt_f32_ubyte3_e32 v223, v179
	v_pk_mul_f32 v[216:217], v[216:217], s[26:27] op_sel_hi:[1,0]
	v_pk_mul_f32 v[218:219], v[218:219], s[26:27] op_sel_hi:[1,0]
	v_pk_mul_f32 v[220:221], v[220:221], s[26:27] op_sel_hi:[1,0]
	v_pk_mul_f32 v[222:223], v[222:223], s[26:27] op_sel_hi:[1,0]
	v_pk_mul_f32 v[86:87], v[86:87], v[216:217]
	v_pk_mul_f32 v[88:89], v[88:89], v[218:219]
	v_pk_mul_f32 v[82:83], v[82:83], v[220:221]
	v_pk_mul_f32 v[84:85], v[84:85], v[222:223]
	v_cvt_pk_bf16_f32 v228, v86, v87
	v_cvt_pk_bf16_f32 v229, v88, v89
	v_cvt_pk_bf16_f32 v230, v82, v83
	v_cvt_pk_bf16_f32 v231, v84, v85
	s_mov_b32 s46, 0xa000
	v_lshl_add_u64 v[166:167], v[160:161], 0, s[46:47]
	global_store_dwordx4 v[166:167], v[228:231], off
	s_waitcnt vmcnt(10)
; __device__ __forceinline__ unsigned cvt_pk_bf16(float lo, float hi) { const f32x2c_t v = {lo, hi}; const bf16x2c_t b = __builtin_convertvector(v, bf16x2c_t); return __builtin_bit_cast(unsigned, b); }
; __device__ __forceinline__ float bf_lo(unsigned w) { return __uint_as_float(w << 16); }
; __device__ __forceinline__ float bf_hi(unsigned w) { return __uint_as_float(w & 0xffff0000u); }
;     __device__ __forceinline__ void operator()(const f32x4 (&acc)[2][2][4][2], const Unit& u, int wr, int wc, int fr, int fq) const {
;     ...
;             for (int m = 0; m < 4; ++m) { const size_t row = (size_t)(row0 + ai * HALF + m * 16);
;                 const u32x4 gw = gp[(ai * 4 + m) * 512];
;                 u32x4 pw[2];
;                 if (SECOND) { pw[0] = mp[((ai * 4 + m) * 2 + 0) * 512]; pw[1] = mp[((ai * 4 + m) * 2 + 1) * 512]; }
; #pragma unroll
;                 for (int bj = 0; bj < 2; ++bj) { const unsigned gx = bj ? gw.z : gw.x, gy = bj ? gw.w : gw.y;
;                     const f32x4 g0 = (f32x4){(float)(gx & 255u), (float)((gx >> 8) & 255u), (float)((gx >> 16) & 255u), (float)(gx >> 24)} * K255,
;                                 g1 = (f32x4){(float)(gy & 255u), (float)((gy >> 8) & 255u), (float)((gy >> 16) & 255u), (float)(gy >> 24)} * K255;
;                     f32x4 v0 = acc[ai][bj][m][0] * g0, v1 = acc[ai][bj][m][1] * g1;
;                     if (SECOND) { const u32x4 p = pw[bj];
;                         v0 = v0 + (f32x4){bf_lo(p.x), bf_hi(p.x), bf_lo(p.y), bf_hi(p.y)}; v1 = v1 + (f32x4){bf_lo(p.z), bf_hi(p.z), bf_lo(p.w), bf_hi(p.w)}; }
;                     u32x4 w; w.x = cvt_pk_bf16(v0[0], v0[1]); w.y = cvt_pk_bf16(v0[2], v0[3]); w.z = cvt_pk_bf16(v1[0], v1[1]); w.w = cvt_pk_bf16(v1[2], v1[3]);
;                     if (SECOND) *(u32x4*)(MG + row * DM + col0 + bj * HALF) = w; else mp[((ai * 4 + m) * 2 + bj) * 512] = w; }
	v_cvt_f32_ubyte0_e32 v216, v180
	v_cvt_f32_ubyte1_e32 v217, v180
	v_cvt_f32_ubyte2_e32 v218, v180
	v_cvt_f32_ubyte3_e32 v219, v180
	v_cvt_f32_ubyte0_e32 v220, v181
	v_cvt_f32_ubyte1_e32 v221, v181
	v_cvt_f32_ubyte2_e32 v222, v181
	v_cvt_f32_ubyte3_e32 v223, v181
	v_pk_mul_f32 v[216:217], v[216:217], s[26:27] op_sel_hi:[1,0]
	v_pk_mul_f32 v[218:219], v[218:219], s[26:27] op_sel_hi:[1,0]
	v_pk_mul_f32 v[220:221], v[220:221], s[26:27] op_sel_hi:[1,0]
	v_pk_mul_f32 v[222:223], v[222:223], s[26:27] op_sel_hi:[1,0]
	v_pk_mul_f32 v[78:79], v[78:79], v[216:217]
	v_pk_mul_f32 v[80:81], v[80:81], v[218:219]
	v_pk_mul_f32 v[74:75], v[74:75], v[220:221]
	v_pk_mul_f32 v[76:77], v[76:77], v[222:223]
	v_cvt_pk_bf16_f32 v224, v78, v79
	v_cvt_pk_bf16_f32 v225, v80, v81
	v_cvt_pk_bf16_f32 v226, v74, v75
	v_cvt_pk_bf16_f32 v227, v76, v77
	s_mov_b32 s46, 0xc000
	v_lshl_add_u64 v[166:167], v[160:161], 0, s[46:47]
	global_store_dwordx4 v[166:167], v[224:227], off
	v_cvt_f32_ubyte0_e32 v216, v182
	v_cvt_f32_ubyte1_e32 v217, v182
	v_cvt_f32_ubyte2_e32 v218, v182
	v_cvt_f32_ubyte3_e32 v219, v182
	v_cvt_f32_ubyte0_e32 v220, v183
	v_cvt_f32_ubyte1_e32 v221, v183
	v_cvt_f32_ubyte2_e32 v222, v183
	v_cvt_f32_ubyte3_e32 v223, v183
	v_pk_mul_f32 v[216:217], v[216:217], s[26:27] op_sel_hi:[1,0]
	v_pk_mul_f32 v[218:219], v[218:219], s[26:27] op_sel_hi:[1,0]
	v_pk_mul_f32 v[220:221], v[220:221], s[26:27] op_sel_hi:[1,0]
	v_pk_mul_f32 v[222:223], v[222:223], s[26:27] op_sel_hi:[1,0]
	v_pk_mul_f32 v[70:71], v[70:71], v[216:217]
	v_pk_mul_f32 v[72:73], v[72:73], v[218:219]
	v_pk_mul_f32 v[66:67], v[66:67], v[220:221]
	v_pk_mul_f32 v[68:69], v[68:69], v[222:223]
	v_cvt_pk_bf16_f32 v228, v70, v71
	v_cvt_pk_bf16_f32 v229, v72, v73
	v_cvt_pk_bf16_f32 v230, v66, v67
	v_cvt_pk_bf16_f32 v231, v68, v69
	s_mov_b32 s46, 0xe000
	v_lshl_add_u64 v[166:167], v[160:161], 0, s[46:47]
	global_store_dwordx4 v[166:167], v[228:231], off
	s_waitcnt vmcnt(11)
	v_cvt_f32_ubyte0_e32 v216, v184
	v_cvt_f32_ubyte1_e32 v217, v184
	v_cvt_f32_ubyte2_e32 v218, v184
	v_cvt_f32_ubyte3_e32 v219, v184
	v_cvt_f32_ubyte0_e32 v220, v185
	v_cvt_f32_ubyte1_e32 v221, v185
	v_cvt_f32_ubyte2_e32 v222, v185
	v_cvt_f32_ubyte3_e32 v223, v185
	v_pk_mul_f32 v[216:217], v[216:217], s[26:27] op_sel_hi:[1,0]
	v_pk_mul_f32 v[218:219], v[218:219], s[26:27] op_sel_hi:[1,0]
	v_pk_mul_f32 v[220:221], v[220:221], s[26:27] op_sel_hi:[1,0]
	v_pk_mul_f32 v[222:223], v[222:223], s[26:27] op_sel_hi:[1,0]
	v_pk_mul_f32 v[62:63], v[62:63], v[216:217]
	v_pk_mul_f32 v[64:65], v[64:65], v[218:219]
	v_pk_mul_f32 v[58:59], v[58:59], v[220:221]
	v_pk_mul_f32 v[60:61], v[60:61], v[222:223]
	v_cvt_pk_bf16_f32 v224, v62, v63
	v_cvt_pk_bf16_f32 v225, v64, v65
	v_cvt_pk_bf16_f32 v226, v58, v59
	v_cvt_pk_bf16_f32 v227, v60, v61
	s_mov_b32 s46, 0x10000
	v_lshl_add_u64 v[166:167], v[160:161], 0, s[46:47]
	global_store_dwordx4 v[166:167], v[224:227], off
	v_cvt_f32_ubyte0_e32 v216, v186
	v_cvt_f32_ubyte1_e32 v217, v186
	v_cvt_f32_ubyte2_e32 v218, v186
	v_cvt_f32_ubyte3_e32 v219, v186
	v_cvt_f32_ubyte0_e32 v220, v187
	v_cvt_f32_ubyte1_e32 v221, v187
	v_cvt_f32_ubyte2_e32 v222, v187
	v_cvt_f32_ubyte3_e32 v223, v187
	v_pk_mul_f32 v[216:217], v[216:217], s[26:27] op_sel_hi:[1,0]
	v_pk_mul_f32 v[218:219], v[218:219], s[26:27] op_sel_hi:[1,0]
	v_pk_mul_f32 v[220:221], v[220:221], s[26:27] op_sel_hi:[1,0]
	v_pk_mul_f32 v[222:223], v[222:223], s[26:27] op_sel_hi:[1,0]
	v_pk_mul_f32 v[54:55], v[54:55], v[216:217]
	v_pk_mul_f32 v[56:57], v[56:57], v[218:219]
	v_pk_mul_f32 v[50:51], v[50:51], v[220:221]
	v_pk_mul_f32 v[52:53], v[52:53], v[222:223]
	v_cvt_pk_bf16_f32 v228, v54, v55
	v_cvt_pk_bf16_f32 v229, v56, v57
	v_cvt_pk_bf16_f32 v230, v50, v51
	v_cvt_pk_bf16_f32 v231, v52, v53
	s_mov_b32 s46, 0x12000
	v_lshl_add_u64 v[166:167], v[160:161], 0, s[46:47]
	global_store_dwordx4 v[166:167], v[228:231], off
	s_waitcnt vmcnt(12)
	v_cvt_f32_ubyte0_e32 v216, v204
	v_cvt_f32_ubyte1_e32 v217, v204
	v_cvt_f32_ubyte2_e32 v218, v204
	v_cvt_f32_ubyte3_e32 v219, v204
	v_cvt_f32_ubyte0_e32 v220, v205
	v_cvt_f32_ubyte1_e32 v221, v205
	v_cvt_f32_ubyte2_e32 v222, v205
	v_cvt_f32_ubyte3_e32 v223, v205
	v_pk_mul_f32 v[216:217], v[216:217], s[26:27] op_sel_hi:[1,0]
	v_pk_mul_f32 v[218:219], v[218:219], s[26:27] op_sel_hi:[1,0]
	v_pk_mul_f32 v[220:221], v[220:221], s[26:27] op_sel_hi:[1,0]
	v_pk_mul_f32 v[222:223], v[222:223], s[26:27] op_sel_hi:[1,0]
	v_pk_mul_f32 v[46:47], v[46:47], v[216:217]
	v_pk_mul_f32 v[48:49], v[48:49], v[218:219]
	v_pk_mul_f32 v[42:43], v[42:43], v[220:221]
	v_pk_mul_f32 v[44:45], v[44:45], v[222:223]
	v_cvt_pk_bf16_f32 v224, v46, v47
	v_cvt_pk_bf16_f32 v225, v48, v49
	v_cvt_pk_bf16_f32 v226, v42, v43
	v_cvt_pk_bf16_f32 v227, v44, v45
	s_mov_b32 s46, 0x14000
	v_lshl_add_u64 v[166:167], v[160:161], 0, s[46:47]
	global_store_dwordx4 v[166:167], v[224:227], off
	v_cvt_f32_ubyte0_e32 v216, v206
	v_cvt_f32_ubyte1_e32 v217, v206
	v_cvt_f32_ubyte2_e32 v218, v206
	v_cvt_f32_ubyte3_e32 v219, v206
	v_cvt_f32_ubyte0_e32 v220, v207
	v_cvt_f32_ubyte1_e32 v221, v207
	v_cvt_f32_ubyte2_e32 v222, v207
	v_cvt_f32_ubyte3_e32 v223, v207
	v_pk_mul_f32 v[216:217], v[216:217], s[26:27] op_sel_hi:[1,0]
	v_pk_mul_f32 v[218:219], v[218:219], s[26:27] op_sel_hi:[1,0]
	v_pk_mul_f32 v[220:221], v[220:221], s[26:27] op_sel_hi:[1,0]
	v_pk_mul_f32 v[222:223], v[222:223], s[26:27] op_sel_hi:[1,0]
	v_pk_mul_f32 v[38:39], v[38:39], v[216:217]
	v_pk_mul_f32 v[40:41], v[40:41], v[218:219]
	v_pk_mul_f32 v[34:35], v[34:35], v[220:221]
	v_pk_mul_f32 v[36:37], v[36:37], v[222:223]
	v_cvt_pk_bf16_f32 v228, v38, v39
	v_cvt_pk_bf16_f32 v229, v40, v41
	v_cvt_pk_bf16_f32 v230, v34, v35
	v_cvt_pk_bf16_f32 v231, v36, v37
	s_mov_b32 s46, 0x16000
	v_lshl_add_u64 v[166:167], v[160:161], 0, s[46:47]
	global_store_dwordx4 v[166:167], v[228:231], off
	s_waitcnt vmcnt(13)
; __device__ __forceinline__ unsigned cvt_pk_bf16(float lo, float hi) { const f32x2c_t v = {lo, hi}; const bf16x2c_t b = __builtin_convertvector(v, bf16x2c_t); return __builtin_bit_cast(unsigned, b); }
; __device__ __forceinline__ float bf_lo(unsigned w) { return __uint_as_float(w << 16); }
;     __device__ __forceinline__ void operator()(const f32x4 (&acc)[2][2][4][2], const Unit& u, int wr, int wc, int fr, int fq) const {
;     ...
;             for (int m = 0; m < 4; ++m) { const size_t row = (size_t)(row0 + ai * HALF + m * 16);
;                 const u32x4 gw = gp[(ai * 4 + m) * 512];
;                 u32x4 pw[2];
;                 if (SECOND) { pw[0] = mp[((ai * 4 + m) * 2 + 0) * 512]; pw[1] = mp[((ai * 4 + m) * 2 + 1) * 512]; }
; #pragma unroll
;                 for (int bj = 0; bj < 2; ++bj) { const unsigned gx = bj ? gw.z : gw.x, gy = bj ? gw.w : gw.y;
;                     const f32x4 g0 = (f32x4){(float)(gx & 255u), (float)((gx >> 8) & 255u), (float)((gx >> 16) & 255u), (float)(gx >> 24)} * K255,
;                                 g1 = (f32x4){(float)(gy & 255u), (float)((gy >> 8) & 255u), (float)((gy >> 16) & 255u), (float)(gy >> 24)} * K255;
;                     f32x4 v0 = acc[ai][bj][m][0] * g0, v1 = acc[ai][bj][m][1] * g1;
;                     if (SECOND) { const u32x4 p = pw[bj];
;                         v0 = v0 + (f32x4){bf_lo(p.x), bf_hi(p.x), bf_lo(p.y), bf_hi(p.y)}; v1 = v1 + (f32x4){bf_lo(p.z), bf_hi(p.z), bf_lo(p.w), bf_hi(p.w)}; }
;                     u32x4 w; w.x = cvt_pk_bf16(v0[0], v0[1]); w.y = cvt_pk_bf16(v0[2], v0[3]); w.z = cvt_pk_bf16(v1[0], v1[1]); w.w = cvt_pk_bf16(v1[2], v1[3]);
;                     if (SECOND) *(u32x4*)(MG + row * DM + col0 + bj * HALF) = w; else mp[((ai * 4 + m) * 2 + bj) * 512] = w; }
; template <class Epi, class Sched, bool ALIGN_EPI = false, bool SP2 = false>
; __device__ __forceinline__ void gemm_phase(PG8_LAS unsigned char* lds, const Gemm g, const Sched& S, const Epi& E) {
;     ...
;         if (!has_next) break;
; #pragma unroll
;         for (int a = 0; a < 2; ++a)
; #pragma unroll
;             for (int b = 0; b < 2; ++b)
; #pragma unroll
;                 for (int m = 0; m < 4; ++m)
; #pragma unroll
;                     for (int n = 0; n < 2; ++n) acc[a][b][m][n] = (f32x4){0.f, 0.f, 0.f, 0.f};
;         cur = nxt; cA = nA; cB = nB; ++ui;
;         if constexpr (ALIGN_EPI) { if (wr == 1) PG8_BAR; }
	v_cvt_f32_ubyte0_e32 v216, v208
	v_cvt_f32_ubyte1_e32 v217, v208
	v_cvt_f32_ubyte2_e32 v218, v208
	v_cvt_f32_ubyte3_e32 v219, v208
	v_cvt_f32_ubyte0_e32 v220, v209
	v_cvt_f32_ubyte1_e32 v221, v209
	v_cvt_f32_ubyte2_e32 v222, v209
	v_cvt_f32_ubyte3_e32 v223, v209
	v_pk_mul_f32 v[216:217], v[216:217], s[26:27] op_sel_hi:[1,0]
	v_pk_mul_f32 v[218:219], v[218:219], s[26:27] op_sel_hi:[1,0]
	v_pk_mul_f32 v[220:221], v[220:221], s[26:27] op_sel_hi:[1,0]
	v_pk_mul_f32 v[222:223], v[222:223], s[26:27] op_sel_hi:[1,0]
	v_pk_mul_f32 v[30:31], v[30:31], v[216:217]
	v_pk_mul_f32 v[32:33], v[32:33], v[218:219]
	v_pk_mul_f32 v[26:27], v[26:27], v[220:221]
	v_pk_mul_f32 v[28:29], v[28:29], v[222:223]
	v_cvt_pk_bf16_f32 v224, v30, v31
	v_cvt_pk_bf16_f32 v225, v32, v33
	v_cvt_pk_bf16_f32 v226, v26, v27
	v_cvt_pk_bf16_f32 v227, v28, v29
	s_mov_b32 s46, 0x18000
	v_lshl_add_u64 v[166:167], v[160:161], 0, s[46:47]
	global_store_dwordx4 v[166:167], v[224:227], off
	v_cvt_f32_ubyte0_e32 v216, v210
	v_cvt_f32_ubyte1_e32 v217, v210
	v_cvt_f32_ubyte2_e32 v218, v210
	v_cvt_f32_ubyte3_e32 v219, v210
	v_cvt_f32_ubyte0_e32 v220, v211
	v_cvt_f32_ubyte1_e32 v221, v211
	v_cvt_f32_ubyte2_e32 v222, v211
	v_cvt_f32_ubyte3_e32 v223, v211
	v_pk_mul_f32 v[216:217], v[216:217], s[26:27] op_sel_hi:[1,0]
	v_pk_mul_f32 v[218:219], v[218:219], s[26:27] op_sel_hi:[1,0]
	v_pk_mul_f32 v[220:221], v[220:221], s[26:27] op_sel_hi:[1,0]
	v_pk_mul_f32 v[222:223], v[222:223], s[26:27] op_sel_hi:[1,0]
	v_pk_mul_f32 v[22:23], v[22:23], v[216:217]
	v_pk_mul_f32 v[24:25], v[24:25], v[218:219]
	v_pk_mul_f32 v[18:19], v[18:19], v[220:221]
	v_pk_mul_f32 v[20:21], v[20:21], v[222:223]
	v_cvt_pk_bf16_f32 v228, v22, v23
	v_cvt_pk_bf16_f32 v229, v24, v25
	v_cvt_pk_bf16_f32 v230, v18, v19
	v_cvt_pk_bf16_f32 v231, v20, v21
	s_mov_b32 s46, 0x1a000
	v_lshl_add_u64 v[166:167], v[160:161], 0, s[46:47]
	global_store_dwordx4 v[166:167], v[228:231], off
	s_waitcnt vmcnt(14)
	v_cvt_f32_ubyte0_e32 v216, v212
	v_cvt_f32_ubyte1_e32 v217, v212
	v_cvt_f32_ubyte2_e32 v218, v212
	v_cvt_f32_ubyte3_e32 v219, v212
	v_cvt_f32_ubyte0_e32 v220, v213
	v_cvt_f32_ubyte1_e32 v221, v213
	v_cvt_f32_ubyte2_e32 v222, v213
	v_cvt_f32_ubyte3_e32 v223, v213
	v_pk_mul_f32 v[216:217], v[216:217], s[26:27] op_sel_hi:[1,0]
	v_pk_mul_f32 v[218:219], v[218:219], s[26:27] op_sel_hi:[1,0]
	v_pk_mul_f32 v[220:221], v[220:221], s[26:27] op_sel_hi:[1,0]
	v_pk_mul_f32 v[222:223], v[222:223], s[26:27] op_sel_hi:[1,0]
	v_pk_mul_f32 v[14:15], v[14:15], v[216:217]
	v_pk_mul_f32 v[16:17], v[16:17], v[218:219]
	v_pk_mul_f32 v[10:11], v[10:11], v[220:221]
	v_pk_mul_f32 v[12:13], v[12:13], v[222:223]
	v_cvt_pk_bf16_f32 v224, v14, v15
	v_cvt_pk_bf16_f32 v225, v16, v17
	v_cvt_pk_bf16_f32 v226, v10, v11
	v_cvt_pk_bf16_f32 v227, v12, v13
	s_mov_b32 s46, 0x1c000
	v_lshl_add_u64 v[166:167], v[160:161], 0, s[46:47]
	global_store_dwordx4 v[166:167], v[224:227], off
	v_cvt_f32_ubyte0_e32 v216, v214
	v_cvt_f32_ubyte1_e32 v217, v214
	v_cvt_f32_ubyte2_e32 v218, v214
	v_cvt_f32_ubyte3_e32 v219, v214
	v_cvt_f32_ubyte0_e32 v220, v215
	v_cvt_f32_ubyte1_e32 v221, v215
	v_cvt_f32_ubyte2_e32 v222, v215
	v_cvt_f32_ubyte3_e32 v223, v215
	v_pk_mul_f32 v[216:217], v[216:217], s[26:27] op_sel_hi:[1,0]
	v_pk_mul_f32 v[218:219], v[218:219], s[26:27] op_sel_hi:[1,0]
	v_pk_mul_f32 v[220:221], v[220:221], s[26:27] op_sel_hi:[1,0]
	v_pk_mul_f32 v[222:223], v[222:223], s[26:27] op_sel_hi:[1,0]
	v_pk_mul_f32 v[6:7], v[6:7], v[216:217]
	v_pk_mul_f32 v[8:9], v[8:9], v[218:219]
	v_pk_mul_f32 v[2:3], v[2:3], v[220:221]
	v_pk_mul_f32 v[4:5], v[4:5], v[222:223]
	v_cvt_pk_bf16_f32 v228, v6, v7
	v_cvt_pk_bf16_f32 v229, v8, v9
	v_cvt_pk_bf16_f32 v230, v2, v3
	v_cvt_pk_bf16_f32 v231, v4, v5
	s_mov_b32 s46, 0x1e000
	v_lshl_add_u64 v[166:167], v[160:161], 0, s[46:47]
	global_store_dwordx4 v[166:167], v[228:231], off
	s_mov_b64 s[18:19], -1
	s_andn2_b64 vcc, exec, s[42:43]
	s_cbranch_vccnz .LBB0_128
	s_andn2_b64 vcc, exec, s[0:1]
	s_cbranch_vccnz .LBB0_127
	s_nop 0
	s_branch .LBB0_127

; #define PG8_STAGE(bufoff, gbase, voff) do { _Pragma("unroll") for (int _i = 0; _i < 2; ++_i) \
;         __builtin_amdgcn_global_load_lds((const unsigned*)((const char*)(gbase) + (voff)[_i]), (PG8_LAS unsigned*)(lds + (bufoff) + ldsw + _i * 8192), 16, 0, 0); } while (0)
; #define PG8_LDA(dst, b, h) do { _Pragma("unroll") for (int m = 0; m < 4; ++m) _Pragma("unroll") for (int k = 0; k < 2; ++k) dst[m][k] = *(const PG8_LAS bf16x8*)(lds + PG8_SA(b, h) + aoff + m * 2048 + k * 1024); } while (0)
; #define PG8_LDB(dst, b, h) do { _Pragma("unroll") for (int n = 0; n < 2; ++n) _Pragma("unroll") for (int k = 0; k < 2; ++k) dst[n][k] = *(const PG8_LAS bf16x8*)(lds + PG8_SB(b, h) + boff + n * 2048 + k * 1024); } while (0)
; template <class Epi, class Sched, bool ALIGN_EPI = false, bool SP2 = false>
; __device__ __forceinline__ void gemm_phase(PG8_LAS unsigned char* lds, const Gemm g, const Sched& S, const Epi& E) {
;     ...
;         for (int t = 0; t < nt; t += 2) {
;             const bool last = (t == nt - 2);
;             const char* a1 = cA + (size_t)(t + 1) * kstep;
;             const char* a2 = last ? nA : cA + (size_t)(t + 2) * kstep; const char* b2 = last ? nB : cB + (size_t)(t + 2) * kstep;
;             const char* a3 = a2 + kstep; const char* b3 = b2 + kstep;
;             if (last && has_next) S.a_ready(nxt);
;             if constexpr (SP2) {
;             PG8_LDB(B0, 0, 0); PG8_LDB(B1, 0, 1); PG8_SCHED; PG8_LDA(At, 0, 0); PG8_STAGE(PG8_SA(1, 1), a1 + hstep, voffA);
;             PG8_WAIT_V(8); PG8_WAIT_L(0); PG8_BAR; PG8_MMA(0, 0, At, B0); PG8_MMA(0, 1, At, B1); PG8_BAR; PG8_SCHED;
;             PG8_LDA(At, 0, 1); PG8_STAGE(PG8_SB(0, 0), b2, voffB); PG8_STAGE(PG8_SB(0, 1), b2 + hstep, voffB); PG8_STAGE(PG8_SA(0, 0), a2, voffA);
;             PG8_WAIT_V(8); PG8_WAIT_L(0); PG8_BAR; PG8_MMA(1, 0, At, B0); PG8_MMA(1, 1, At, B1); PG8_BAR; PG8_SCHED;
;             PG8_LDB(B0, 1, 0); PG8_LDB(B1, 1, 1); PG8_SCHED; PG8_LDA(At, 1, 0); PG8_STAGE(PG8_SA(0, 1), a2 + hstep, voffA);
;             PG8_WAIT_V(8); PG8_WAIT_L(0); PG8_BAR; PG8_MMA(0, 0, At, B0); PG8_MMA(0, 1, At, B1); PG8_BAR; PG8_SCHED;
;             PG8_LDA(At, 1, 1); PG8_STAGE(PG8_SB(1, 0), b3, voffB); PG8_STAGE(PG8_SB(1, 1), b3 + hstep, voffB); PG8_STAGE(PG8_SA(1, 0), a3, voffA);
;             PG8_WAIT_V(8); PG8_WAIT_L(0); PG8_BAR; PG8_MMA(1, 0, At, B0); PG8_MMA(1, 1, At, B1); PG8_BAR; PG8_SCHED;
.LBB0_160:
	s_add_u32 s42, s36, 0x100
	s_addc_u32 s43, s37, 0
	s_add_i32 s47, 0, 0x10000
	s_cmp_eq_u32 s46, 20
	s_cselect_b32 s45, s1, s43
	s_cselect_b32 s44, s0, s42
	s_cselect_b32 s19, s7, s73
	s_cselect_b32 s18, s6, s60
	s_add_i32 s76, 0, 0x14000
	v_add_u32_e32 v174, s47, v143
	v_add_u32_e32 v186, s76, v143
	ds_read_b128 v[160:163], v174
	ds_read_b128 v[164:167], v174 offset:1024
	ds_read_b128 v[170:173], v174 offset:2048
	ds_read_b128 v[174:177], v174 offset:3072
	ds_read_b128 v[178:181], v186
	ds_read_b128 v[182:185], v186 offset:1024
	ds_read_b128 v[204:207], v186 offset:2048
	ds_read_b128 v[208:211], v186 offset:3072
	v_lshl_add_u64 v[186:187], s[36:37], 0, v[156:157]
	s_add_i32 m0, s54, 0xc000
	ds_read_b128 v[212:215], v169
	ds_read_b128 v[216:219], v169 offset:1024
	ds_read_b128 v[220:223], v169 offset:2048
	ds_read_b128 v[224:227], v169 offset:3072
	ds_read_b128 v[228:231], v169 offset:4096
	ds_read_b128 v[232:235], v169 offset:5120
	ds_read_b128 v[236:239], v169 offset:6144
	ds_read_b128 v[240:243], v169 offset:7168
	global_load_lds_dwordx4 v[186:187], off
	v_lshl_add_u64 v[186:187], s[36:37], 0, v[158:159]
	s_add_i32 m0, s54, 0xe000
	s_nop 0
	global_load_lds_dwordx4 v[186:187], off
	s_nop 0
	s_waitcnt vmcnt(8)
	s_waitcnt lgkmcnt(0)
	s_setprio 1
	s_barrier
	v_mfma_f32_16x16x32_bf16 v[126:129], v[160:163], v[212:215], v[126:129]
	v_mfma_f32_16x16x32_bf16 v[122:125], v[170:173], v[212:215], v[122:125]
	v_mfma_f32_16x16x32_bf16 v[110:113], v[160:163], v[220:223], v[110:113]
	v_mfma_f32_16x16x32_bf16 v[106:109], v[170:173], v[220:223], v[106:109]
	v_mfma_f32_16x16x32_bf16 v[94:97], v[160:163], v[228:231], v[94:97]
	v_mfma_f32_16x16x32_bf16 v[90:93], v[170:173], v[228:231], v[90:93]
	v_mfma_f32_16x16x32_bf16 v[78:81], v[160:163], v[236:239], v[78:81]
	v_mfma_f32_16x16x32_bf16 v[74:77], v[170:173], v[236:239], v[74:77]
	s_setprio 0
	s_setprio 1
	v_mfma_f32_16x16x32_bf16 v[126:129], v[164:167], v[216:219], v[126:129]
	v_mfma_f32_16x16x32_bf16 v[122:125], v[174:177], v[216:219], v[122:125]
	v_mfma_f32_16x16x32_bf16 v[110:113], v[164:167], v[224:227], v[110:113]
	v_mfma_f32_16x16x32_bf16 v[106:109], v[174:177], v[224:227], v[106:109]
	v_mfma_f32_16x16x32_bf16 v[94:97], v[164:167], v[232:235], v[94:97]
	v_mfma_f32_16x16x32_bf16 v[90:93], v[174:177], v[232:235], v[90:93]
	v_mfma_f32_16x16x32_bf16 v[78:81], v[164:167], v[240:243], v[78:81]
	v_mfma_f32_16x16x32_bf16 v[74:77], v[174:177], v[240:243], v[74:77]
	s_setprio 0
	s_setprio 1
	v_mfma_f32_16x16x32_bf16 v[118:121], v[178:181], v[212:215], v[118:121]
	v_mfma_f32_16x16x32_bf16 v[114:117], v[204:207], v[212:215], v[114:117]
	v_mfma_f32_16x16x32_bf16 v[102:105], v[178:181], v[220:223], v[102:105]
	v_mfma_f32_16x16x32_bf16 v[98:101], v[204:207], v[220:223], v[98:101]
	v_mfma_f32_16x16x32_bf16 v[86:89], v[178:181], v[228:231], v[86:89]
	v_mfma_f32_16x16x32_bf16 v[82:85], v[204:207], v[228:231], v[82:85]
	v_mfma_f32_16x16x32_bf16 v[70:73], v[178:181], v[236:239], v[70:73]
	v_mfma_f32_16x16x32_bf16 v[66:69], v[204:207], v[236:239], v[66:69]
	s_setprio 0
	s_setprio 1
	v_mfma_f32_16x16x32_bf16 v[118:121], v[182:185], v[216:219], v[118:121]
	v_mfma_f32_16x16x32_bf16 v[114:117], v[208:211], v[216:219], v[114:117]
	v_mfma_f32_16x16x32_bf16 v[102:105], v[182:185], v[224:227], v[102:105]
	v_mfma_f32_16x16x32_bf16 v[98:101], v[208:211], v[224:227], v[98:101]
	v_mfma_f32_16x16x32_bf16 v[86:89], v[182:185], v[232:235], v[86:89]
	v_mfma_f32_16x16x32_bf16 v[82:85], v[208:211], v[232:235], v[82:85]
	v_mfma_f32_16x16x32_bf16 v[70:73], v[182:185], v[240:243], v[70:73]
	v_mfma_f32_16x16x32_bf16 v[66:69], v[208:211], v[240:243], v[66:69]
	s_setprio 0
	s_barrier
	s_add_i32 s36, s47, s4
	v_lshl_add_u64 v[186:187], s[18:19], 0, v[148:149]
	s_mov_b32 m0, s36
	ds_read_b128 v[212:215], v169 offset:16384
	ds_read_b128 v[216:219], v169 offset:17408
	ds_read_b128 v[220:223], v169 offset:18432
	ds_read_b128 v[224:227], v169 offset:19456
	ds_read_b128 v[228:231], v169 offset:20480
	ds_read_b128 v[232:235], v169 offset:21504
	ds_read_b128 v[236:239], v169 offset:22528
	ds_read_b128 v[240:243], v169 offset:23552
	global_load_lds_dwordx4 v[186:187], off
	s_add_i32 m0, s36, 0x2000
	s_add_u32 s36, s18, 0x60000
	v_lshl_add_u64 v[244:245], s[18:19], 0, v[144:145]
	s_addc_u32 s37, s19, 0
	s_add_i32 s47, s76, s4
	global_load_lds_dwordx4 v[244:245], off
	v_lshl_add_u64 v[246:247], s[36:37], 0, v[148:149]
	s_mov_b32 m0, s47
	v_lshl_add_u64 v[248:249], s[44:45], 0, v[146:147]
	global_load_lds_dwordx4 v[246:247], off
	v_lshl_add_u64 v[246:247], s[36:37], 0, v[144:145]
	s_add_i32 m0, s47, 0x2000
	s_nop 0
	global_load_lds_dwordx4 v[246:247], off
	v_lshl_add_u64 v[246:247], s[44:45], 0, v[150:151]
	s_mov_b32 m0, s54
	s_nop 0
	global_load_lds_dwordx4 v[246:247], off
	s_mov_b32 m0, s57
	s_nop 0
	global_load_lds_dwordx4 v[248:249], off
	s_waitcnt vmcnt(8)
	s_waitcnt lgkmcnt(0)
	s_setprio 1
	s_barrier
; #define PG8_STAGE(bufoff, gbase, voff) do { _Pragma("unroll") for (int _i = 0; _i < 2; ++_i) \
;         __builtin_amdgcn_global_load_lds((const unsigned*)((const char*)(gbase) + (voff)[_i]), (PG8_LAS unsigned*)(lds + (bufoff) + ldsw + _i * 8192), 16, 0, 0); } while (0)
; #define PG8_LDA(dst, b, h) do { _Pragma("unroll") for (int m = 0; m < 4; ++m) _Pragma("unroll") for (int k = 0; k < 2; ++k) dst[m][k] = *(const PG8_LAS bf16x8*)(lds + PG8_SA(b, h) + aoff + m * 2048 + k * 1024); } while (0)
; #define PG8_LDB(dst, b, h) do { _Pragma("unroll") for (int n = 0; n < 2; ++n) _Pragma("unroll") for (int k = 0; k < 2; ++k) dst[n][k] = *(const PG8_LAS bf16x8*)(lds + PG8_SB(b, h) + boff + n * 2048 + k * 1024); } while (0)
; #define PG8_MMA(ai, bj, At, Bt) do { __builtin_amdgcn_s_setprio(1); _Pragma("unroll") for (int m = 0; m < 4; ++m) _Pragma("unroll") for (int n = 0; n < 2; ++n) _Pragma("unroll") for (int k = 0; k < 2; ++k) \
;         acc[ai][bj][m][n] = __builtin_amdgcn_mfma_f32_16x16x32_bf16(Bt[n][k], At[m][k], acc[ai][bj][m][n], 0, 0, 0); __builtin_amdgcn_s_setprio(0); } while (0)
; #define PG8_BAR __builtin_amdgcn_s_barrier()
; template <class Epi, class Sched, bool ALIGN_EPI = false, bool SP2 = false>
; __device__ __forceinline__ void gemm_phase(PG8_LAS unsigned char* lds, const Gemm g, const Sched& S, const Epi& E) {
;     ...
;             if constexpr (SP2) {
;             PG8_LDB(B0, 0, 0); PG8_LDB(B1, 0, 1); PG8_SCHED; PG8_LDA(At, 0, 0); PG8_STAGE(PG8_SA(1, 1), a1 + hstep, voffA);
;             PG8_WAIT_V(8); PG8_WAIT_L(0); PG8_BAR; PG8_MMA(0, 0, At, B0); PG8_MMA(0, 1, At, B1); PG8_BAR; PG8_SCHED;
;             PG8_LDA(At, 0, 1); PG8_STAGE(PG8_SB(0, 0), b2, voffB); PG8_STAGE(PG8_SB(0, 1), b2 + hstep, voffB); PG8_STAGE(PG8_SA(0, 0), a2, voffA);
;             PG8_WAIT_V(8); PG8_WAIT_L(0); PG8_BAR; PG8_MMA(1, 0, At, B0); PG8_MMA(1, 1, At, B1); PG8_BAR; PG8_SCHED;
;             PG8_LDB(B0, 1, 0); PG8_LDB(B1, 1, 1); PG8_SCHED; PG8_LDA(At, 1, 0); PG8_STAGE(PG8_SA(0, 1), a2 + hstep, voffA);
;             PG8_WAIT_V(8); PG8_WAIT_L(0); PG8_BAR; PG8_MMA(0, 0, At, B0); PG8_MMA(0, 1, At, B1); PG8_BAR; PG8_SCHED;
;             PG8_LDA(At, 1, 1); PG8_STAGE(PG8_SB(1, 0), b3, voffB); PG8_STAGE(PG8_SB(1, 1), b3 + hstep, voffB); PG8_STAGE(PG8_SA(1, 0), a3, voffA);
;             PG8_WAIT_V(8); PG8_WAIT_L(0); PG8_BAR; PG8_MMA(1, 0, At, B0); PG8_MMA(1, 1, At, B1); PG8_BAR; PG8_SCHED;
	v_mfma_f32_16x16x32_bf16 v[62:65], v[160:163], v[212:215], v[62:65]
	v_mfma_f32_16x16x32_bf16 v[58:61], v[170:173], v[212:215], v[58:61]
	v_mfma_f32_16x16x32_bf16 v[46:49], v[160:163], v[220:223], v[46:49]
	v_mfma_f32_16x16x32_bf16 v[42:45], v[170:173], v[220:223], v[42:45]
	v_mfma_f32_16x16x32_bf16 v[30:33], v[160:163], v[228:231], v[30:33]
	v_mfma_f32_16x16x32_bf16 v[26:29], v[170:173], v[228:231], v[26:29]
	v_mfma_f32_16x16x32_bf16 v[14:17], v[160:163], v[236:239], v[14:17]
	v_mfma_f32_16x16x32_bf16 v[10:13], v[170:173], v[236:239], v[10:13]
	v_mfma_f32_16x16x32_bf16 v[62:65], v[164:167], v[216:219], v[62:65]
	v_mfma_f32_16x16x32_bf16 v[58:61], v[174:177], v[216:219], v[58:61]
	v_mfma_f32_16x16x32_bf16 v[46:49], v[164:167], v[224:227], v[46:49]
	v_mfma_f32_16x16x32_bf16 v[42:45], v[174:177], v[224:227], v[42:45]
	v_mfma_f32_16x16x32_bf16 v[30:33], v[164:167], v[232:235], v[30:33]
	v_mfma_f32_16x16x32_bf16 v[26:29], v[174:177], v[232:235], v[26:29]
	v_mfma_f32_16x16x32_bf16 v[14:17], v[164:167], v[240:243], v[14:17]
	v_mfma_f32_16x16x32_bf16 v[10:13], v[174:177], v[240:243], v[10:13]
	v_mfma_f32_16x16x32_bf16 v[54:57], v[178:181], v[212:215], v[54:57]
	v_mfma_f32_16x16x32_bf16 v[50:53], v[204:207], v[212:215], v[50:53]
	v_mfma_f32_16x16x32_bf16 v[38:41], v[178:181], v[220:223], v[38:41]
	v_mfma_f32_16x16x32_bf16 v[34:37], v[204:207], v[220:223], v[34:37]
	v_mfma_f32_16x16x32_bf16 v[22:25], v[178:181], v[228:231], v[22:25]
	v_mfma_f32_16x16x32_bf16 v[18:21], v[204:207], v[228:231], v[18:21]
	v_mfma_f32_16x16x32_bf16 v[6:9], v[178:181], v[236:239], v[6:9]
	v_mfma_f32_16x16x32_bf16 v[2:5], v[204:207], v[236:239], v[2:5]
	v_mfma_f32_16x16x32_bf16 v[54:57], v[182:185], v[216:219], v[54:57]
	v_mfma_f32_16x16x32_bf16 v[50:53], v[208:211], v[216:219], v[50:53]
	v_mfma_f32_16x16x32_bf16 v[38:41], v[182:185], v[224:227], v[38:41]
	v_mfma_f32_16x16x32_bf16 v[34:37], v[208:211], v[224:227], v[34:37]
	v_mfma_f32_16x16x32_bf16 v[22:25], v[182:185], v[232:235], v[22:25]
	v_mfma_f32_16x16x32_bf16 v[18:21], v[208:211], v[232:235], v[18:21]
	v_mfma_f32_16x16x32_bf16 v[6:9], v[182:185], v[240:243], v[6:9]
	v_mfma_f32_16x16x32_bf16 v[2:5], v[208:211], v[240:243], v[2:5]
	s_setprio 0
	s_barrier
	s_add_i32 s47, 0, 0x18000
	s_add_i32 s76, 0, 0x1c000
	v_add_u32_e32 v174, s47, v143
	v_add_u32_e32 v203, s76, v143
	ds_read_b128 v[160:163], v174
	ds_read_b128 v[164:167], v174 offset:1024
	ds_read_b128 v[170:173], v174 offset:2048
	ds_read_b128 v[174:177], v174 offset:3072
	ds_read_b128 v[178:181], v203
	ds_read_b128 v[182:185], v203 offset:1024
	ds_read_b128 v[204:207], v203 offset:2048
	ds_read_b128 v[208:211], v203 offset:3072
	s_add_u32 s36, s44, 0x60000
	s_addc_u32 s37, s45, 0
	s_mov_b32 m0, s58
	v_lshl_add_u64 v[250:251], s[36:37], 0, v[150:151]
	ds_read_b128 v[212:215], v169 offset:32768
	ds_read_b128 v[216:219], v169 offset:33792
	ds_read_b128 v[220:223], v169 offset:34816
	ds_read_b128 v[224:227], v169 offset:35840
	ds_read_b128 v[228:231], v169 offset:36864
	ds_read_b128 v[232:235], v169 offset:37888
	ds_read_b128 v[236:239], v169 offset:38912
	ds_read_b128 v[240:243], v169 offset:39936
	global_load_lds_dwordx4 v[250:251], off
	v_lshl_add_u64 v[250:251], s[36:37], 0, v[146:147]
	s_mov_b32 m0, s59
	s_nop 0
	global_load_lds_dwordx4 v[250:251], off
	s_waitcnt vmcnt(8)
	s_waitcnt lgkmcnt(0)
	s_setprio 1
	s_barrier
	v_mfma_f32_16x16x32_bf16 v[126:129], v[160:163], v[212:215], v[126:129]
	v_mfma_f32_16x16x32_bf16 v[122:125], v[170:173], v[212:215], v[122:125]
	v_mfma_f32_16x16x32_bf16 v[110:113], v[160:163], v[220:223], v[110:113]
	v_mfma_f32_16x16x32_bf16 v[106:109], v[170:173], v[220:223], v[106:109]
	v_mfma_f32_16x16x32_bf16 v[94:97], v[160:163], v[228:231], v[94:97]
	v_mfma_f32_16x16x32_bf16 v[90:93], v[170:173], v[228:231], v[90:93]
	v_mfma_f32_16x16x32_bf16 v[78:81], v[160:163], v[236:239], v[78:81]
	v_mfma_f32_16x16x32_bf16 v[74:77], v[170:173], v[236:239], v[74:77]
	s_setprio 0
	s_setprio 1
	v_mfma_f32_16x16x32_bf16 v[126:129], v[164:167], v[216:219], v[126:129]
	v_mfma_f32_16x16x32_bf16 v[122:125], v[174:177], v[216:219], v[122:125]
	v_mfma_f32_16x16x32_bf16 v[110:113], v[164:167], v[224:227], v[110:113]
	v_mfma_f32_16x16x32_bf16 v[106:109], v[174:177], v[224:227], v[106:109]
	v_mfma_f32_16x16x32_bf16 v[94:97], v[164:167], v[232:235], v[94:97]
	v_mfma_f32_16x16x32_bf16 v[90:93], v[174:177], v[232:235], v[90:93]
	v_mfma_f32_16x16x32_bf16 v[78:81], v[164:167], v[240:243], v[78:81]
	v_mfma_f32_16x16x32_bf16 v[74:77], v[174:177], v[240:243], v[74:77]
	s_setprio 0
	s_setprio 1
	v_mfma_f32_16x16x32_bf16 v[118:121], v[178:181], v[212:215], v[118:121]
	v_mfma_f32_16x16x32_bf16 v[114:117], v[204:207], v[212:215], v[114:117]
	v_mfma_f32_16x16x32_bf16 v[102:105], v[178:181], v[220:223], v[102:105]
	v_mfma_f32_16x16x32_bf16 v[98:101], v[204:207], v[220:223], v[98:101]
	v_mfma_f32_16x16x32_bf16 v[86:89], v[178:181], v[228:231], v[86:89]
	v_mfma_f32_16x16x32_bf16 v[82:85], v[204:207], v[228:231], v[82:85]
	v_mfma_f32_16x16x32_bf16 v[70:73], v[178:181], v[236:239], v[70:73]
	v_mfma_f32_16x16x32_bf16 v[66:69], v[204:207], v[236:239], v[66:69]
	s_setprio 0
	s_setprio 1
	v_mfma_f32_16x16x32_bf16 v[118:121], v[182:185], v[216:219], v[118:121]
	v_mfma_f32_16x16x32_bf16 v[114:117], v[208:211], v[216:219], v[114:117]
	v_mfma_f32_16x16x32_bf16 v[102:105], v[182:185], v[224:227], v[102:105]
	v_mfma_f32_16x16x32_bf16 v[98:101], v[208:211], v[224:227], v[98:101]
	v_mfma_f32_16x16x32_bf16 v[86:89], v[182:185], v[232:235], v[86:89]
	v_mfma_f32_16x16x32_bf16 v[82:85], v[208:211], v[232:235], v[82:85]
	v_mfma_f32_16x16x32_bf16 v[70:73], v[182:185], v[240:243], v[70:73]
	v_mfma_f32_16x16x32_bf16 v[66:69], v[208:211], v[240:243], v[66:69]
	s_setprio 0
	s_barrier
; #define PG8_STAGE(bufoff, gbase, voff) do { _Pragma("unroll") for (int _i = 0; _i < 2; ++_i) \
;         __builtin_amdgcn_global_load_lds((const unsigned*)((const char*)(gbase) + (voff)[_i]), (PG8_LAS unsigned*)(lds + (bufoff) + ldsw + _i * 8192), 16, 0, 0); } while (0)
; #define PG8_LDA(dst, b, h) do { _Pragma("unroll") for (int m = 0; m < 4; ++m) _Pragma("unroll") for (int k = 0; k < 2; ++k) dst[m][k] = *(const PG8_LAS bf16x8*)(lds + PG8_SA(b, h) + aoff + m * 2048 + k * 1024); } while (0)
; #define PG8_WAIT_V(n) asm volatile("s_waitcnt vmcnt(" #n ")" ::: "memory")
; #define PG8_WAIT_L(n) asm volatile("s_waitcnt lgkmcnt(" #n ")" ::: "memory")
;     __device__ __forceinline__ void operator()(const f32x4 (&acc)[2][2][4][2], const Unit& u, int wr, int wc, int fr, int fq) const {
;         const int row0 = u.pm * BM + wr * 64 + fr, col0 = u.pn * BM + wc * 32 + 8 * fq;
;         const int tidn = (wr * 4 + wc) * 64 + fq * 16 + fr;
;         const u32x4* gp = (const u32x4*)G8 + (size_t)(u.pm * 16 + gsel + u.pn) * 8 * 512 + tidn;
;         u32x4* mp = M1 + (size_t)(u.pm * 8 + u.pn) * 16 * 512 + tidn;
;         constexpr float K255 = 1.0f / 255.0f;
; #pragma unroll
;         for (int ai = 0; ai < 2; ++ai)
; #pragma unroll
;             for (int m = 0; m < 4; ++m) { const size_t row = (size_t)(row0 + ai * HALF + m * 16);
;                 const u32x4 gw = gp[(ai * 4 + m) * 512];
;                 u32x4 pw[2];
;                 if (SECOND) { pw[0] = mp[((ai * 4 + m) * 2 + 0) * 512]; pw[1] = mp[((ai * 4 + m) * 2 + 1) * 512]; }
; template <class Epi, class Sched, bool ALIGN_EPI = false, bool SP2 = false>
; __device__ __forceinline__ void gemm_phase(PG8_LAS unsigned char* lds, const Gemm g, const Sched& S, const Epi& E) {
;     ...
;             PG8_WAIT_V(8); PG8_WAIT_L(0); PG8_BAR; PG8_MMA(1, 0, At, B0); PG8_MMA(1, 1, At, B1); PG8_BAR; PG8_SCHED;
;             PG8_LDB(B0, 1, 0); PG8_LDB(B1, 1, 1); PG8_SCHED; PG8_LDA(At, 1, 0); PG8_STAGE(PG8_SA(0, 1), a2 + hstep, voffA);
;             PG8_WAIT_V(8); PG8_WAIT_L(0); PG8_BAR; PG8_MMA(0, 0, At, B0); PG8_MMA(0, 1, At, B1); PG8_BAR; PG8_SCHED;
;             PG8_LDA(At, 1, 1); PG8_STAGE(PG8_SB(1, 0), b3, voffB); PG8_STAGE(PG8_SB(1, 1), b3 + hstep, voffB); PG8_STAGE(PG8_SA(1, 0), a3, voffA);
;             PG8_WAIT_V(8); PG8_WAIT_L(0); PG8_BAR; PG8_MMA(1, 0, At, B0); PG8_MMA(1, 1, At, B1); PG8_BAR; PG8_SCHED;
	s_add_i32 s36, s47, s4
	v_lshl_add_u64 v[186:187], v[186:187], 0, s[68:69]
	s_mov_b32 m0, s36
	ds_read_b128 v[212:215], v169 offset:49152
	ds_read_b128 v[216:219], v169 offset:50176
	ds_read_b128 v[220:223], v169 offset:51200
	ds_read_b128 v[224:227], v169 offset:52224
	ds_read_b128 v[228:231], v169 offset:53248
	ds_read_b128 v[232:235], v169 offset:54272
	ds_read_b128 v[236:239], v169 offset:55296
	ds_read_b128 v[240:243], v169 offset:56320
	global_load_lds_dwordx4 v[186:187], off
	s_add_i32 m0, s36, 0x2000
	s_add_u32 s18, s18, 0x60080
	v_lshl_add_u64 v[186:187], v[244:245], 0, s[68:69]
	s_addc_u32 s19, s19, 0
	s_add_i32 s36, s76, s4
	global_load_lds_dwordx4 v[186:187], off
	v_lshl_add_u64 v[186:187], s[18:19], 0, v[148:149]
	s_mov_b32 m0, s36
	s_nop 0
	global_load_lds_dwordx4 v[186:187], off
	v_lshl_add_u64 v[186:187], s[18:19], 0, v[144:145]
	s_add_i32 m0, s36, 0x2000
	s_nop 0
	global_load_lds_dwordx4 v[186:187], off
	v_lshl_add_u64 v[186:187], v[246:247], 0, s[68:69]
	s_mov_b32 m0, s62
	s_nop 0
	global_load_lds_dwordx4 v[186:187], off
	v_lshl_add_u64 v[186:187], v[248:249], 0, s[68:69]
	s_mov_b32 m0, s63
	s_nop 0
	global_load_lds_dwordx4 v[186:187], off
	s_nop 0
	s_waitcnt vmcnt(8)
	s_waitcnt lgkmcnt(0)
	s_setprio 1
	s_barrier
	v_mfma_f32_16x16x32_bf16 v[62:65], v[160:163], v[212:215], v[62:65]
	v_mfma_f32_16x16x32_bf16 v[58:61], v[170:173], v[212:215], v[58:61]
	v_mfma_f32_16x16x32_bf16 v[46:49], v[160:163], v[220:223], v[46:49]
	v_mfma_f32_16x16x32_bf16 v[42:45], v[170:173], v[220:223], v[42:45]
	v_mfma_f32_16x16x32_bf16 v[30:33], v[160:163], v[228:231], v[30:33]
	v_mfma_f32_16x16x32_bf16 v[26:29], v[170:173], v[228:231], v[26:29]
	v_mfma_f32_16x16x32_bf16 v[14:17], v[160:163], v[236:239], v[14:17]
	v_mfma_f32_16x16x32_bf16 v[10:13], v[170:173], v[236:239], v[10:13]
	v_mfma_f32_16x16x32_bf16 v[62:65], v[164:167], v[216:219], v[62:65]
	v_mfma_f32_16x16x32_bf16 v[58:61], v[174:177], v[216:219], v[58:61]
	v_mfma_f32_16x16x32_bf16 v[46:49], v[164:167], v[224:227], v[46:49]
	v_mfma_f32_16x16x32_bf16 v[42:45], v[174:177], v[224:227], v[42:45]
	v_mfma_f32_16x16x32_bf16 v[30:33], v[164:167], v[232:235], v[30:33]
	v_mfma_f32_16x16x32_bf16 v[26:29], v[174:177], v[232:235], v[26:29]
	v_mfma_f32_16x16x32_bf16 v[14:17], v[164:167], v[240:243], v[14:17]
	v_mfma_f32_16x16x32_bf16 v[10:13], v[174:177], v[240:243], v[10:13]
	v_mfma_f32_16x16x32_bf16 v[54:57], v[178:181], v[212:215], v[54:57]
	v_mfma_f32_16x16x32_bf16 v[50:53], v[204:207], v[212:215], v[50:53]
	v_mfma_f32_16x16x32_bf16 v[38:41], v[178:181], v[220:223], v[38:41]
	v_mfma_f32_16x16x32_bf16 v[34:37], v[204:207], v[220:223], v[34:37]
	v_mfma_f32_16x16x32_bf16 v[22:25], v[178:181], v[228:231], v[22:25]
	v_mfma_f32_16x16x32_bf16 v[18:21], v[204:207], v[228:231], v[18:21]
	v_mfma_f32_16x16x32_bf16 v[6:9], v[178:181], v[236:239], v[6:9]
	v_mfma_f32_16x16x32_bf16 v[2:5], v[204:207], v[236:239], v[2:5]
	v_mfma_f32_16x16x32_bf16 v[54:57], v[182:185], v[216:219], v[54:57]
	v_mfma_f32_16x16x32_bf16 v[50:53], v[208:211], v[216:219], v[50:53]
	v_mfma_f32_16x16x32_bf16 v[38:41], v[182:185], v[224:227], v[38:41]
	v_mfma_f32_16x16x32_bf16 v[34:37], v[208:211], v[224:227], v[34:37]
	v_mfma_f32_16x16x32_bf16 v[22:25], v[182:185], v[232:235], v[22:25]
	v_mfma_f32_16x16x32_bf16 v[18:21], v[208:211], v[232:235], v[18:21]
	v_mfma_f32_16x16x32_bf16 v[6:9], v[182:185], v[240:243], v[6:9]
	v_mfma_f32_16x16x32_bf16 v[2:5], v[208:211], v[240:243], v[2:5]
	s_setprio 0
	s_barrier
	s_add_i32 s46, s46, 2
	s_add_u32 s60, s60, 0x100
	s_addc_u32 s73, s73, 0
	s_cmp_gt_u32 s46, 21
	s_mov_b64 s[36:37], s[42:43]
	s_cbranch_scc0 .LBB0_160
	s_mov_b32 s32, 1
	s_and_b64 vcc, s[10:11], s[40:41]
	s_cbranch_vccz .LBB0_163
	s_barrier
.LBB0_163:
	s_lshl_b32 s18, s34, 4
	s_add_i32 s18, s28, s18
	s_add_i32 s18, s18, 8
	s_ashr_i32 s19, s18, 31
	s_lshl_b64 s[18:19], s[18:19], 16
	v_lshl_add_u64 v[160:161], v[152:153], 0, s[18:19]
	s_lshl_b32 s18, s34, 3
	s_add_i32 s18, s18, s28
	s_ashr_i32 s19, s18, 31
	s_lshl_b64 s[18:19], s[18:19], 17
	v_lshl_add_u64 v[162:163], v[154:155], 0, s[18:19]
	global_load_dwordx4 v[170:173], v[160:161], off
	global_load_dwordx4 v[174:177], v[162:163], off
	s_movk_i32 s18, 0x2000
	v_add_co_u32_e32 v178, vcc, s18, v162
	v_lshl_add_u32 v164, s34, 8, v1
	s_nop 0
	v_addc_co_u32_e32 v179, vcc, 0, v163, vcc
	global_load_dwordx4 v[178:181], v[178:179], off
	v_lshl_or_b32 v166, s28, 8, v168
	v_ashrrev_i32_e32 v165, 31, v164
	v_ashrrev_i32_e32 v167, 31, v166
	v_lshlrev_b64 v[182:183], 12, v[164:165]
	s_movk_i32 s28, 0x6000
	s_movk_i32 s19, 0x4000
	s_mov_b32 s34, 0xa000
	s_mov_b32 s37, 0xe000
	s_mov_b32 s36, 0xc000
	s_movk_i32 s81, 0x4000
	s_waitcnt vmcnt(0)
; __device__ __forceinline__ unsigned cvt_pk_bf16(float lo, float hi) { const f32x2c_t v = {lo, hi}; const bf16x2c_t b = __builtin_convertvector(v, bf16x2c_t); return __builtin_bit_cast(unsigned, b); }
; __device__ __forceinline__ float bf_lo(unsigned w) { return __uint_as_float(w << 16); }
; __device__ __forceinline__ float bf_hi(unsigned w) { return __uint_as_float(w & 0xffff0000u); }
;     __device__ __forceinline__ void operator()(const f32x4 (&acc)[2][2][4][2], const Unit& u, int wr, int wc, int fr, int fq) const {
;     ...
;             for (int m = 0; m < 4; ++m) { const size_t row = (size_t)(row0 + ai * HALF + m * 16);
;                 const u32x4 gw = gp[(ai * 4 + m) * 512];
;                 u32x4 pw[2];
;                 if (SECOND) { pw[0] = mp[((ai * 4 + m) * 2 + 0) * 512]; pw[1] = mp[((ai * 4 + m) * 2 + 1) * 512]; }
; #pragma unroll
;                 for (int bj = 0; bj < 2; ++bj) { const unsigned gx = bj ? gw.z : gw.x, gy = bj ? gw.w : gw.y;
;                     const f32x4 g0 = (f32x4){(float)(gx & 255u), (float)((gx >> 8) & 255u), (float)((gx >> 16) & 255u), (float)(gx >> 24)} * K255,
;                                 g1 = (f32x4){(float)(gy & 255u), (float)((gy >> 8) & 255u), (float)((gy >> 16) & 255u), (float)(gy >> 24)} * K255;
;                     f32x4 v0 = acc[ai][bj][m][0] * g0, v1 = acc[ai][bj][m][1] * g1;
;                     if (SECOND) { const u32x4 p = pw[bj];
;                         v0 = v0 + (f32x4){bf_lo(p.x), bf_hi(p.x), bf_lo(p.y), bf_hi(p.y)}; v1 = v1 + (f32x4){bf_lo(p.z), bf_hi(p.z), bf_lo(p.w), bf_hi(p.w)}; }
;                     u32x4 w; w.x = cvt_pk_bf16(v0[0], v0[1]); w.y = cvt_pk_bf16(v0[2], v0[3]); w.z = cvt_pk_bf16(v1[0], v1[1]); w.w = cvt_pk_bf16(v1[2], v1[3]);
;                     if (SECOND) *(u32x4*)(MG + row * DM + col0 + bj * HALF) = w; else mp[((ai * 4 + m) * 2 + bj) * 512] = w; }
	v_cvt_f32_ubyte3_e32 v185, v170
	v_cvt_f32_ubyte2_e32 v184, v170
	v_cvt_f32_ubyte1_e32 v207, v171
	v_cvt_f32_ubyte0_e32 v206, v171
	v_cvt_f32_ubyte1_e32 v187, v170
	v_cvt_f32_ubyte0_e32 v186, v170
	v_pk_mul_f32 v[184:185], v[184:185], s[26:27] op_sel_hi:[1,0]
	v_cvt_f32_ubyte3_e32 v205, v171
	v_cvt_f32_ubyte2_e32 v204, v171
	v_pk_mul_f32 v[170:171], v[206:207], s[26:27] op_sel_hi:[1,0]
	v_lshlrev_b32_e32 v206, 16, v174
	v_and_b32_e32 v207, 0xffff0000, v174
	v_lshlrev_b32_e32 v174, 16, v175
	v_and_b32_e32 v175, 0xffff0000, v175
	v_pk_mul_f32 v[186:187], v[186:187], s[26:27] op_sel_hi:[1,0]
	v_pk_mul_f32 v[204:205], v[204:205], s[26:27] op_sel_hi:[1,0]
	v_pk_fma_f32 v[128:129], v[128:129], v[184:185], v[174:175]
	v_lshlrev_b32_e32 v174, 16, v176
	v_and_b32_e32 v175, 0xffff0000, v176
	v_lshlrev_b32_e32 v176, 16, v177
	v_and_b32_e32 v177, 0xffff0000, v177
	v_pk_fma_f32 v[126:127], v[126:127], v[186:187], v[206:207]
	v_pk_fma_f32 v[124:125], v[124:125], v[204:205], v[176:177]
	v_pk_fma_f32 v[122:123], v[122:123], v[170:171], v[174:175]
	v_cvt_pk_bf16_f32 v126, v126, v127
	v_cvt_pk_bf16_f32 v127, v128, v129
	v_cvt_pk_bf16_f32 v128, v122, v123
	v_cvt_pk_bf16_f32 v129, v124, v125
	v_lshl_add_u64 v[122:123], s[12:13], 0, v[182:183]
	v_lshlrev_b64 v[124:125], 1, v[166:167]
	v_lshl_add_u64 v[122:123], v[122:123], 0, v[124:125]
	global_store_dwordx4 v[122:123], v[126:129], off
	v_cvt_f32_ubyte3_e32 v167, v173
	v_cvt_f32_ubyte2_e32 v166, v173
	v_cvt_f32_ubyte3_e32 v127, v172
	v_cvt_f32_ubyte2_e32 v126, v172
	v_cvt_f32_ubyte1_e32 v129, v172
	v_cvt_f32_ubyte0_e32 v128, v172
	v_pk_mul_f32 v[128:129], v[128:129], s[26:27] op_sel_hi:[1,0]
	v_pk_mul_f32 v[126:127], v[126:127], s[26:27] op_sel_hi:[1,0]
	v_cvt_f32_ubyte1_e32 v171, v173
	v_cvt_f32_ubyte0_e32 v170, v173
	v_lshlrev_b32_e32 v172, 16, v178
	v_and_b32_e32 v173, 0xffff0000, v178
	v_lshlrev_b32_e32 v174, 16, v179
	v_and_b32_e32 v175, 0xffff0000, v179
	v_pk_mul_f32 v[170:171], v[170:171], s[26:27] op_sel_hi:[1,0]
	v_pk_mul_f32 v[166:167], v[166:167], s[26:27] op_sel_hi:[1,0]
	v_pk_fma_f32 v[120:121], v[120:121], v[126:127], v[174:175]
	v_pk_fma_f32 v[118:119], v[118:119], v[128:129], v[172:173]
	v_lshlrev_b32_e32 v126, 16, v180
	v_and_b32_e32 v127, 0xffff0000, v180
	v_lshlrev_b32_e32 v128, 16, v181
	v_and_b32_e32 v129, 0xffff0000, v181
	v_pk_fma_f32 v[128:129], v[116:117], v[166:167], v[128:129]
	v_pk_fma_f32 v[116:117], v[114:115], v[170:171], v[126:127]
	v_cvt_pk_bf16_f32 v114, v118, v119
	v_cvt_pk_bf16_f32 v115, v120, v121
	v_cvt_pk_bf16_f32 v116, v116, v117
	v_cvt_pk_bf16_f32 v117, v128, v129
	global_store_dwordx4 v[122:123], v[114:117], off offset:256
	v_or_b32_e32 v166, 16, v164
	v_ashrrev_i32_e32 v167, 31, v166
	v_add_co_u32_e32 v114, vcc, s28, v162
	v_lshlrev_b64 v[166:167], 12, v[166:167]
	s_nop 0
	v_addc_co_u32_e32 v115, vcc, 0, v163, vcc
	v_add_co_u32_e32 v118, vcc, s19, v162
	global_load_dwordx4 v[114:117], v[114:115], off
	s_nop 0
	v_addc_co_u32_e32 v119, vcc, 0, v163, vcc
	v_add_co_u32_e32 v126, vcc, s18, v160
	global_load_dwordx4 v[118:121], v[118:119], off
	s_nop 0
	v_addc_co_u32_e32 v127, vcc, 0, v161, vcc
	global_load_dwordx4 v[126:129], v[126:127], off
	s_mov_b32 s18, 0x8000
	s_waitcnt vmcnt(0)
	v_cvt_f32_ubyte3_e32 v171, v126
	v_cvt_f32_ubyte2_e32 v170, v126
	v_cvt_f32_ubyte1_e32 v173, v126
	v_cvt_f32_ubyte0_e32 v172, v126
	v_cvt_f32_ubyte1_e32 v177, v127
	v_cvt_f32_ubyte0_e32 v176, v127
	v_pk_mul_f32 v[172:173], v[172:173], s[26:27] op_sel_hi:[1,0]
	v_pk_mul_f32 v[170:171], v[170:171], s[26:27] op_sel_hi:[1,0]
	v_cvt_f32_ubyte3_e32 v175, v127
	v_cvt_f32_ubyte2_e32 v174, v127
	v_pk_mul_f32 v[126:127], v[176:177], s[26:27] op_sel_hi:[1,0]
	v_lshlrev_b32_e32 v176, 16, v118
	v_and_b32_e32 v177, 0xffff0000, v118
	v_lshlrev_b32_e32 v118, 16, v119
	v_and_b32_e32 v119, 0xffff0000, v119
	v_pk_mul_f32 v[174:175], v[174:175], s[26:27] op_sel_hi:[1,0]
	v_pk_fma_f32 v[112:113], v[112:113], v[170:171], v[118:119]
	v_pk_fma_f32 v[110:111], v[110:111], v[172:173], v[176:177]
	v_lshlrev_b32_e32 v118, 16, v120
	v_and_b32_e32 v119, 0xffff0000, v120
	v_lshlrev_b32_e32 v120, 16, v121
	v_and_b32_e32 v121, 0xffff0000, v121
	v_pk_fma_f32 v[120:121], v[108:109], v[174:175], v[120:121]
	v_pk_fma_f32 v[108:109], v[106:107], v[126:127], v[118:119]
	v_cvt_pk_bf16_f32 v106, v110, v111
	v_lshl_add_u64 v[110:111], s[12:13], 0, v[166:167]
	v_cvt_pk_bf16_f32 v107, v112, v113
	v_cvt_pk_bf16_f32 v108, v108, v109
	v_cvt_pk_bf16_f32 v109, v120, v121
	v_lshl_add_u64 v[110:111], v[110:111], 0, v[124:125]
	global_store_dwordx4 v[110:111], v[106:109], off
	v_cvt_f32_ubyte3_e32 v113, v129
	v_cvt_f32_ubyte2_e32 v112, v129
	v_cvt_f32_ubyte3_e32 v107, v128
	v_cvt_f32_ubyte2_e32 v106, v128
	v_cvt_f32_ubyte1_e32 v109, v128
	v_cvt_f32_ubyte0_e32 v108, v128
	v_pk_mul_f32 v[108:109], v[108:109], s[26:27] op_sel_hi:[1,0]
	v_pk_mul_f32 v[106:107], v[106:107], s[26:27] op_sel_hi:[1,0]
	v_cvt_f32_ubyte1_e32 v119, v129
	v_cvt_f32_ubyte0_e32 v118, v129
	v_lshlrev_b32_e32 v120, 16, v114
	v_and_b32_e32 v121, 0xffff0000, v114
	v_lshlrev_b32_e32 v114, 16, v115
	v_and_b32_e32 v115, 0xffff0000, v115
	v_pk_mul_f32 v[118:119], v[118:119], s[26:27] op_sel_hi:[1,0]
	v_pk_mul_f32 v[112:113], v[112:113], s[26:27] op_sel_hi:[1,0]
	v_pk_fma_f32 v[104:105], v[104:105], v[106:107], v[114:115]
	v_pk_fma_f32 v[102:103], v[102:103], v[108:109], v[120:121]
	v_lshlrev_b32_e32 v106, 16, v116
	v_and_b32_e32 v107, 0xffff0000, v116
	v_lshlrev_b32_e32 v108, 16, v117
	v_and_b32_e32 v109, 0xffff0000, v117
	v_pk_fma_f32 v[108:109], v[100:101], v[112:113], v[108:109]
	v_pk_fma_f32 v[100:101], v[98:99], v[118:119], v[106:107]
	v_cvt_pk_bf16_f32 v98, v102, v103
	v_cvt_pk_bf16_f32 v99, v104, v105
	v_cvt_pk_bf16_f32 v100, v100, v101
	v_cvt_pk_bf16_f32 v101, v108, v109
	global_store_dwordx4 v[110:111], v[98:101], off offset:256
	v_or_b32_e32 v110, 32, v164
	v_ashrrev_i32_e32 v111, 31, v110
	v_add_co_u32_e32 v98, vcc, s34, v162
	v_lshlrev_b64 v[110:111], 12, v[110:111]
	s_nop 0
	v_addc_co_u32_e32 v99, vcc, 0, v163, vcc
	v_add_co_u32_e32 v102, vcc, s18, v162
	global_load_dwordx4 v[98:101], v[98:99], off
	s_nop 0
	v_addc_co_u32_e32 v103, vcc, 0, v163, vcc
	v_add_co_u32_e32 v106, vcc, s19, v160
	global_load_dwordx4 v[102:105], v[102:103], off
	s_nop 0
	v_addc_co_u32_e32 v107, vcc, 0, v161, vcc
	global_load_dwordx4 v[106:109], v[106:107], off
	s_waitcnt vmcnt(0)
; __device__ __forceinline__ unsigned cvt_pk_bf16(float lo, float hi) { const f32x2c_t v = {lo, hi}; const bf16x2c_t b = __builtin_convertvector(v, bf16x2c_t); return __builtin_bit_cast(unsigned, b); }
; __device__ __forceinline__ float bf_lo(unsigned w) { return __uint_as_float(w << 16); }
; __device__ __forceinline__ float bf_hi(unsigned w) { return __uint_as_float(w & 0xffff0000u); }
;     __device__ __forceinline__ void operator()(const f32x4 (&acc)[2][2][4][2], const Unit& u, int wr, int wc, int fr, int fq) const {
;     ...
;             for (int m = 0; m < 4; ++m) { const size_t row = (size_t)(row0 + ai * HALF + m * 16);
;                 const u32x4 gw = gp[(ai * 4 + m) * 512];
;                 u32x4 pw[2];
;                 if (SECOND) { pw[0] = mp[((ai * 4 + m) * 2 + 0) * 512]; pw[1] = mp[((ai * 4 + m) * 2 + 1) * 512]; }
; #pragma unroll
;                 for (int bj = 0; bj < 2; ++bj) { const unsigned gx = bj ? gw.z : gw.x, gy = bj ? gw.w : gw.y;
;                     const f32x4 g0 = (f32x4){(float)(gx & 255u), (float)((gx >> 8) & 255u), (float)((gx >> 16) & 255u), (float)(gx >> 24)} * K255,
;                                 g1 = (f32x4){(float)(gy & 255u), (float)((gy >> 8) & 255u), (float)((gy >> 16) & 255u), (float)(gy >> 24)} * K255;
;                     f32x4 v0 = acc[ai][bj][m][0] * g0, v1 = acc[ai][bj][m][1] * g1;
;                     if (SECOND) { const u32x4 p = pw[bj];
;                         v0 = v0 + (f32x4){bf_lo(p.x), bf_hi(p.x), bf_lo(p.y), bf_hi(p.y)}; v1 = v1 + (f32x4){bf_lo(p.z), bf_hi(p.z), bf_lo(p.w), bf_hi(p.w)}; }
;                     u32x4 w; w.x = cvt_pk_bf16(v0[0], v0[1]); w.y = cvt_pk_bf16(v0[2], v0[3]); w.z = cvt_pk_bf16(v1[0], v1[1]); w.w = cvt_pk_bf16(v1[2], v1[3]);
;                     if (SECOND) *(u32x4*)(MG + row * DM + col0 + bj * HALF) = w; else mp[((ai * 4 + m) * 2 + bj) * 512] = w; }
	v_cvt_f32_ubyte3_e32 v113, v106
	v_cvt_f32_ubyte2_e32 v112, v106
	v_cvt_f32_ubyte1_e32 v115, v106
	v_cvt_f32_ubyte0_e32 v114, v106
	v_cvt_f32_ubyte1_e32 v119, v107
	v_cvt_f32_ubyte0_e32 v118, v107
	v_pk_mul_f32 v[114:115], v[114:115], s[26:27] op_sel_hi:[1,0]
	v_pk_mul_f32 v[112:113], v[112:113], s[26:27] op_sel_hi:[1,0]
	v_cvt_f32_ubyte3_e32 v117, v107
	v_cvt_f32_ubyte2_e32 v116, v107
	v_pk_mul_f32 v[106:107], v[118:119], s[26:27] op_sel_hi:[1,0]
	v_lshlrev_b32_e32 v118, 16, v102
	v_and_b32_e32 v119, 0xffff0000, v102
	v_lshlrev_b32_e32 v102, 16, v103
	v_and_b32_e32 v103, 0xffff0000, v103
	v_pk_mul_f32 v[116:117], v[116:117], s[26:27] op_sel_hi:[1,0]
	v_pk_fma_f32 v[96:97], v[96:97], v[112:113], v[102:103]
	v_pk_fma_f32 v[94:95], v[94:95], v[114:115], v[118:119]
	v_lshlrev_b32_e32 v102, 16, v104
	v_and_b32_e32 v103, 0xffff0000, v104
	v_lshlrev_b32_e32 v104, 16, v105
	v_and_b32_e32 v105, 0xffff0000, v105
	v_pk_fma_f32 v[104:105], v[92:93], v[116:117], v[104:105]
	v_pk_fma_f32 v[92:93], v[90:91], v[106:107], v[102:103]
	v_cvt_pk_bf16_f32 v90, v94, v95
	v_lshl_add_u64 v[94:95], s[12:13], 0, v[110:111]
	v_cvt_pk_bf16_f32 v91, v96, v97
	v_cvt_pk_bf16_f32 v92, v92, v93
	v_cvt_pk_bf16_f32 v93, v104, v105
	v_lshl_add_u64 v[94:95], v[94:95], 0, v[124:125]
	global_store_dwordx4 v[94:95], v[90:93], off
	v_cvt_f32_ubyte3_e32 v97, v109
	v_cvt_f32_ubyte2_e32 v96, v109
	v_cvt_f32_ubyte3_e32 v91, v108
	v_cvt_f32_ubyte2_e32 v90, v108
	v_cvt_f32_ubyte1_e32 v93, v108
	v_cvt_f32_ubyte0_e32 v92, v108
	v_pk_mul_f32 v[92:93], v[92:93], s[26:27] op_sel_hi:[1,0]
	v_pk_mul_f32 v[90:91], v[90:91], s[26:27] op_sel_hi:[1,0]
	v_cvt_f32_ubyte1_e32 v103, v109
	v_cvt_f32_ubyte0_e32 v102, v109
	v_lshlrev_b32_e32 v104, 16, v98
	v_and_b32_e32 v105, 0xffff0000, v98
	v_lshlrev_b32_e32 v98, 16, v99
	v_and_b32_e32 v99, 0xffff0000, v99
	v_pk_mul_f32 v[102:103], v[102:103], s[26:27] op_sel_hi:[1,0]
	v_pk_mul_f32 v[96:97], v[96:97], s[26:27] op_sel_hi:[1,0]
	v_pk_fma_f32 v[88:89], v[88:89], v[90:91], v[98:99]
	v_pk_fma_f32 v[86:87], v[86:87], v[92:93], v[104:105]
	v_lshlrev_b32_e32 v90, 16, v100
	v_and_b32_e32 v91, 0xffff0000, v100
	v_lshlrev_b32_e32 v92, 16, v101
	v_and_b32_e32 v93, 0xffff0000, v101
	v_pk_fma_f32 v[92:93], v[84:85], v[96:97], v[92:93]
	v_pk_fma_f32 v[84:85], v[82:83], v[102:103], v[90:91]
	v_cvt_pk_bf16_f32 v82, v86, v87
	v_cvt_pk_bf16_f32 v83, v88, v89
	v_cvt_pk_bf16_f32 v84, v84, v85
	v_cvt_pk_bf16_f32 v85, v92, v93
	global_store_dwordx4 v[94:95], v[82:85], off offset:256
	v_or_b32_e32 v94, 48, v164
	v_ashrrev_i32_e32 v95, 31, v94
	v_add_co_u32_e32 v82, vcc, s37, v162
	v_lshlrev_b64 v[94:95], 12, v[94:95]
	s_nop 0
	v_addc_co_u32_e32 v83, vcc, 0, v163, vcc
	v_add_co_u32_e32 v86, vcc, s36, v162
	global_load_dwordx4 v[82:85], v[82:83], off
	s_nop 0
	v_addc_co_u32_e32 v87, vcc, 0, v163, vcc
	v_add_co_u32_e32 v90, vcc, s28, v160
	global_load_dwordx4 v[86:89], v[86:87], off
	s_nop 0
	v_addc_co_u32_e32 v91, vcc, 0, v161, vcc
	global_load_dwordx4 v[90:93], v[90:91], off
	s_waitcnt vmcnt(0)
	v_cvt_f32_ubyte3_e32 v97, v90
	v_cvt_f32_ubyte2_e32 v96, v90
	v_cvt_f32_ubyte1_e32 v99, v90
	v_cvt_f32_ubyte0_e32 v98, v90
	v_cvt_f32_ubyte1_e32 v103, v91
	v_cvt_f32_ubyte0_e32 v102, v91
	v_pk_mul_f32 v[98:99], v[98:99], s[26:27] op_sel_hi:[1,0]
	v_pk_mul_f32 v[96:97], v[96:97], s[26:27] op_sel_hi:[1,0]
	v_cvt_f32_ubyte3_e32 v101, v91
	v_cvt_f32_ubyte2_e32 v100, v91
	v_pk_mul_f32 v[90:91], v[102:103], s[26:27] op_sel_hi:[1,0]
	v_lshlrev_b32_e32 v102, 16, v86
	v_and_b32_e32 v103, 0xffff0000, v86
	v_lshlrev_b32_e32 v86, 16, v87
	v_and_b32_e32 v87, 0xffff0000, v87
	v_pk_mul_f32 v[100:101], v[100:101], s[26:27] op_sel_hi:[1,0]
	v_pk_fma_f32 v[80:81], v[80:81], v[96:97], v[86:87]
	v_pk_fma_f32 v[78:79], v[78:79], v[98:99], v[102:103]
	v_lshlrev_b32_e32 v86, 16, v88
	v_and_b32_e32 v87, 0xffff0000, v88
	v_lshlrev_b32_e32 v88, 16, v89
	v_and_b32_e32 v89, 0xffff0000, v89
	v_pk_fma_f32 v[88:89], v[76:77], v[100:101], v[88:89]
	v_pk_fma_f32 v[76:77], v[74:75], v[90:91], v[86:87]
	v_cvt_pk_bf16_f32 v74, v78, v79
	v_lshl_add_u64 v[78:79], s[12:13], 0, v[94:95]
	v_cvt_pk_bf16_f32 v75, v80, v81
	v_cvt_pk_bf16_f32 v76, v76, v77
	v_cvt_pk_bf16_f32 v77, v88, v89
	v_lshl_add_u64 v[78:79], v[78:79], 0, v[124:125]
	global_store_dwordx4 v[78:79], v[74:77], off
	v_cvt_f32_ubyte3_e32 v81, v93
	v_cvt_f32_ubyte2_e32 v80, v93
	v_cvt_f32_ubyte3_e32 v75, v92
	v_cvt_f32_ubyte2_e32 v74, v92
	v_cvt_f32_ubyte1_e32 v77, v92
	v_cvt_f32_ubyte0_e32 v76, v92
	v_pk_mul_f32 v[76:77], v[76:77], s[26:27] op_sel_hi:[1,0]
	v_pk_mul_f32 v[74:75], v[74:75], s[26:27] op_sel_hi:[1,0]
	v_cvt_f32_ubyte1_e32 v87, v93
	v_cvt_f32_ubyte0_e32 v86, v93
	v_lshlrev_b32_e32 v88, 16, v82
	v_and_b32_e32 v89, 0xffff0000, v82
	v_lshlrev_b32_e32 v82, 16, v83
	v_and_b32_e32 v83, 0xffff0000, v83
	v_pk_mul_f32 v[86:87], v[86:87], s[26:27] op_sel_hi:[1,0]
	v_pk_mul_f32 v[80:81], v[80:81], s[26:27] op_sel_hi:[1,0]
	v_pk_fma_f32 v[72:73], v[72:73], v[74:75], v[82:83]
	v_pk_fma_f32 v[70:71], v[70:71], v[76:77], v[88:89]
	v_lshlrev_b32_e32 v74, 16, v84
	v_and_b32_e32 v75, 0xffff0000, v84
	v_lshlrev_b32_e32 v76, 16, v85
	v_and_b32_e32 v77, 0xffff0000, v85
	v_pk_fma_f32 v[76:77], v[68:69], v[80:81], v[76:77]
	v_pk_fma_f32 v[68:69], v[66:67], v[86:87], v[74:75]
	v_cvt_pk_bf16_f32 v66, v70, v71
	v_cvt_pk_bf16_f32 v67, v72, v73
	v_cvt_pk_bf16_f32 v68, v68, v69
	v_cvt_pk_bf16_f32 v69, v76, v77
	global_store_dwordx4 v[78:79], v[66:69], off offset:256
	s_nop 1
	v_add_co_u32_e32 v66, vcc, s18, v160
	s_mov_b32 s18, 0x10000
	s_nop 0
	v_addc_co_u32_e32 v67, vcc, 0, v161, vcc
	v_add_co_u32_e32 v70, vcc, s18, v162
	global_load_dwordx4 v[66:69], v[66:67], off
	s_nop 0
	v_addc_co_u32_e32 v71, vcc, 0, v163, vcc
	global_load_dwordx4 v[70:73], v[70:71], off
	s_mov_b32 s18, 0x12000
	v_add_co_u32_e32 v74, vcc, s18, v162
	s_mov_b64 s[18:19], 0x80000
	s_nop 0
	v_addc_co_u32_e32 v75, vcc, 0, v163, vcc
	global_load_dwordx4 v[74:77], v[74:75], off
	s_waitcnt vmcnt(2)
; __device__ __forceinline__ unsigned cvt_pk_bf16(float lo, float hi) { const f32x2c_t v = {lo, hi}; const bf16x2c_t b = __builtin_convertvector(v, bf16x2c_t); return __builtin_bit_cast(unsigned, b); }
; __device__ __forceinline__ float bf_lo(unsigned w) { return __uint_as_float(w << 16); }
; __device__ __forceinline__ float bf_hi(unsigned w) { return __uint_as_float(w & 0xffff0000u); }
;     __device__ __forceinline__ void operator()(const f32x4 (&acc)[2][2][4][2], const Unit& u, int wr, int wc, int fr, int fq) const {
;     ...
;             for (int m = 0; m < 4; ++m) { const size_t row = (size_t)(row0 + ai * HALF + m * 16);
;                 const u32x4 gw = gp[(ai * 4 + m) * 512];
;                 u32x4 pw[2];
;                 if (SECOND) { pw[0] = mp[((ai * 4 + m) * 2 + 0) * 512]; pw[1] = mp[((ai * 4 + m) * 2 + 1) * 512]; }
; #pragma unroll
;                 for (int bj = 0; bj < 2; ++bj) { const unsigned gx = bj ? gw.z : gw.x, gy = bj ? gw.w : gw.y;
;                     const f32x4 g0 = (f32x4){(float)(gx & 255u), (float)((gx >> 8) & 255u), (float)((gx >> 16) & 255u), (float)(gx >> 24)} * K255,
;                                 g1 = (f32x4){(float)(gy & 255u), (float)((gy >> 8) & 255u), (float)((gy >> 16) & 255u), (float)(gy >> 24)} * K255;
;                     f32x4 v0 = acc[ai][bj][m][0] * g0, v1 = acc[ai][bj][m][1] * g1;
;                     if (SECOND) { const u32x4 p = pw[bj];
;                         v0 = v0 + (f32x4){bf_lo(p.x), bf_hi(p.x), bf_lo(p.y), bf_hi(p.y)}; v1 = v1 + (f32x4){bf_lo(p.z), bf_hi(p.z), bf_lo(p.w), bf_hi(p.w)}; }
;                     u32x4 w; w.x = cvt_pk_bf16(v0[0], v0[1]); w.y = cvt_pk_bf16(v0[2], v0[3]); w.z = cvt_pk_bf16(v1[0], v1[1]); w.w = cvt_pk_bf16(v1[2], v1[3]);
;                     if (SECOND) *(u32x4*)(MG + row * DM + col0 + bj * HALF) = w; else mp[((ai * 4 + m) * 2 + bj) * 512] = w; }
	v_cvt_f32_ubyte3_e32 v79, v66
	v_cvt_f32_ubyte2_e32 v78, v66
	v_cvt_f32_ubyte1_e32 v81, v66
	v_cvt_f32_ubyte0_e32 v80, v66
	v_cvt_f32_ubyte1_e32 v85, v67
	v_cvt_f32_ubyte0_e32 v84, v67
	v_pk_mul_f32 v[80:81], v[80:81], s[26:27] op_sel_hi:[1,0]
	v_pk_mul_f32 v[78:79], v[78:79], s[26:27] op_sel_hi:[1,0]
	v_cvt_f32_ubyte3_e32 v83, v67
	v_cvt_f32_ubyte2_e32 v82, v67
	v_pk_mul_f32 v[66:67], v[84:85], s[26:27] op_sel_hi:[1,0]
	s_waitcnt vmcnt(1)
	v_lshlrev_b32_e32 v84, 16, v70
	v_and_b32_e32 v85, 0xffff0000, v70
	v_lshlrev_b32_e32 v70, 16, v71
	v_and_b32_e32 v71, 0xffff0000, v71
	v_pk_mul_f32 v[82:83], v[82:83], s[26:27] op_sel_hi:[1,0]
	v_pk_fma_f32 v[64:65], v[64:65], v[78:79], v[70:71]
	v_pk_fma_f32 v[62:63], v[62:63], v[80:81], v[84:85]
	v_lshlrev_b32_e32 v70, 16, v72
	v_and_b32_e32 v71, 0xffff0000, v72
	v_lshlrev_b32_e32 v72, 16, v73
	v_and_b32_e32 v73, 0xffff0000, v73
	v_pk_fma_f32 v[72:73], v[60:61], v[82:83], v[72:73]
	v_pk_fma_f32 v[60:61], v[58:59], v[66:67], v[70:71]
	v_cvt_pk_bf16_f32 v58, v62, v63
	v_lshl_add_u64 v[62:63], v[122:123], 0, s[18:19]
	s_mov_b32 s18, 0x80000
	v_cvt_pk_bf16_f32 v59, v64, v65
	v_add_co_u32_e32 v64, vcc, s18, v122
	v_cvt_pk_bf16_f32 v60, v60, v61
	v_cvt_pk_bf16_f32 v61, v72, v73
	v_addc_co_u32_e32 v65, vcc, 0, v123, vcc
	global_store_dwordx4 v[64:65], v[58:61], off
	v_cvt_f32_ubyte3_e32 v65, v69
	v_cvt_f32_ubyte2_e32 v64, v69
	v_cvt_f32_ubyte3_e32 v59, v68
	v_cvt_f32_ubyte2_e32 v58, v68
	v_cvt_f32_ubyte1_e32 v61, v68
	v_cvt_f32_ubyte0_e32 v60, v68
	v_pk_mul_f32 v[60:61], v[60:61], s[26:27] op_sel_hi:[1,0]
	v_pk_mul_f32 v[58:59], v[58:59], s[26:27] op_sel_hi:[1,0]
	v_cvt_f32_ubyte1_e32 v67, v69
	v_cvt_f32_ubyte0_e32 v66, v69
	s_waitcnt vmcnt(1)
	v_lshlrev_b32_e32 v68, 16, v74
	v_and_b32_e32 v69, 0xffff0000, v74
	v_lshlrev_b32_e32 v70, 16, v75
	v_and_b32_e32 v71, 0xffff0000, v75
	v_pk_mul_f32 v[66:67], v[66:67], s[26:27] op_sel_hi:[1,0]
	v_pk_mul_f32 v[64:65], v[64:65], s[26:27] op_sel_hi:[1,0]
	v_pk_fma_f32 v[56:57], v[56:57], v[58:59], v[70:71]
	v_pk_fma_f32 v[54:55], v[54:55], v[60:61], v[68:69]
	v_lshlrev_b32_e32 v58, 16, v76
	v_and_b32_e32 v59, 0xffff0000, v76
	v_lshlrev_b32_e32 v60, 16, v77
	v_and_b32_e32 v61, 0xffff0000, v77
	v_pk_fma_f32 v[60:61], v[52:53], v[64:65], v[60:61]
	v_pk_fma_f32 v[52:53], v[50:51], v[66:67], v[58:59]
	v_cvt_pk_bf16_f32 v50, v54, v55
	v_cvt_pk_bf16_f32 v51, v56, v57
	v_cvt_pk_bf16_f32 v52, v52, v53
	v_cvt_pk_bf16_f32 v53, v60, v61
	s_mov_b32 s18, 0x16000
	global_store_dwordx4 v[62:63], v[50:53], off offset:256
	s_nop 1
	v_add_co_u32_e32 v50, vcc, s18, v162
	s_mov_b32 s18, 0x14000
	s_nop 0
	v_addc_co_u32_e32 v51, vcc, 0, v163, vcc
	v_add_co_u32_e32 v54, vcc, s18, v162
	global_load_dwordx4 v[50:53], v[50:51], off
	s_nop 0
	v_addc_co_u32_e32 v55, vcc, 0, v163, vcc
	v_add_co_u32_e32 v58, vcc, s34, v160
	global_load_dwordx4 v[54:57], v[54:55], off
	s_nop 0
	v_addc_co_u32_e32 v59, vcc, 0, v161, vcc
	global_load_dwordx4 v[58:61], v[58:59], off
	s_mov_b64 s[18:19], 0x90000
	s_waitcnt vmcnt(0)
	v_cvt_f32_ubyte3_e32 v63, v58
	v_cvt_f32_ubyte2_e32 v62, v58
	v_cvt_f32_ubyte1_e32 v65, v58
	v_cvt_f32_ubyte0_e32 v64, v58
	v_cvt_f32_ubyte1_e32 v69, v59
	v_cvt_f32_ubyte0_e32 v68, v59
	v_pk_mul_f32 v[64:65], v[64:65], s[26:27] op_sel_hi:[1,0]
	v_pk_mul_f32 v[62:63], v[62:63], s[26:27] op_sel_hi:[1,0]
	v_cvt_f32_ubyte3_e32 v67, v59
	v_cvt_f32_ubyte2_e32 v66, v59
	v_pk_mul_f32 v[58:59], v[68:69], s[26:27] op_sel_hi:[1,0]
	v_lshlrev_b32_e32 v68, 16, v54
	v_and_b32_e32 v69, 0xffff0000, v54
	v_lshlrev_b32_e32 v54, 16, v55
	v_and_b32_e32 v55, 0xffff0000, v55
	v_pk_mul_f32 v[66:67], v[66:67], s[26:27] op_sel_hi:[1,0]
	v_pk_fma_f32 v[48:49], v[48:49], v[62:63], v[54:55]
	v_pk_fma_f32 v[46:47], v[46:47], v[64:65], v[68:69]
	v_lshlrev_b32_e32 v54, 16, v56
	v_and_b32_e32 v55, 0xffff0000, v56
	v_lshlrev_b32_e32 v56, 16, v57
	v_and_b32_e32 v57, 0xffff0000, v57
	v_pk_fma_f32 v[56:57], v[44:45], v[66:67], v[56:57]
	v_pk_fma_f32 v[44:45], v[42:43], v[58:59], v[54:55]
	v_cvt_pk_bf16_f32 v42, v46, v47
	v_lshl_add_u64 v[46:47], v[122:123], 0, s[18:19]
	s_mov_b32 s18, 0x90000
	v_cvt_pk_bf16_f32 v43, v48, v49
	v_add_co_u32_e32 v48, vcc, s18, v122
	v_cvt_pk_bf16_f32 v44, v44, v45
	v_cvt_pk_bf16_f32 v45, v56, v57
	v_addc_co_u32_e32 v49, vcc, 0, v123, vcc
	global_store_dwordx4 v[48:49], v[42:45], off
	v_cvt_f32_ubyte3_e32 v49, v61
	v_cvt_f32_ubyte2_e32 v48, v61
	v_cvt_f32_ubyte3_e32 v43, v60
	v_cvt_f32_ubyte2_e32 v42, v60
	v_cvt_f32_ubyte1_e32 v45, v60
	v_cvt_f32_ubyte0_e32 v44, v60
	v_pk_mul_f32 v[44:45], v[44:45], s[26:27] op_sel_hi:[1,0]
	v_pk_mul_f32 v[42:43], v[42:43], s[26:27] op_sel_hi:[1,0]
	v_cvt_f32_ubyte1_e32 v55, v61
	v_cvt_f32_ubyte0_e32 v54, v61
	v_lshlrev_b32_e32 v56, 16, v50
	v_and_b32_e32 v57, 0xffff0000, v50
	v_lshlrev_b32_e32 v50, 16, v51
	v_and_b32_e32 v51, 0xffff0000, v51
	v_pk_mul_f32 v[54:55], v[54:55], s[26:27] op_sel_hi:[1,0]
	v_pk_mul_f32 v[48:49], v[48:49], s[26:27] op_sel_hi:[1,0]
	v_pk_fma_f32 v[40:41], v[40:41], v[42:43], v[50:51]
	v_pk_fma_f32 v[38:39], v[38:39], v[44:45], v[56:57]
	v_lshlrev_b32_e32 v42, 16, v52
	v_and_b32_e32 v43, 0xffff0000, v52
	v_lshlrev_b32_e32 v44, 16, v53
	v_and_b32_e32 v45, 0xffff0000, v53
	v_pk_fma_f32 v[44:45], v[36:37], v[48:49], v[44:45]
	v_pk_fma_f32 v[36:37], v[34:35], v[54:55], v[42:43]
	v_cvt_pk_bf16_f32 v34, v38, v39
	v_cvt_pk_bf16_f32 v35, v40, v41
	v_cvt_pk_bf16_f32 v36, v36, v37
	v_cvt_pk_bf16_f32 v37, v44, v45
	s_mov_b32 s18, 0x1a000
	global_store_dwordx4 v[46:47], v[34:37], off offset:256
	s_nop 1
	v_add_co_u32_e32 v34, vcc, s18, v162
	s_mov_b32 s18, 0x18000
	s_nop 0
	v_addc_co_u32_e32 v35, vcc, 0, v163, vcc
	v_add_co_u32_e32 v38, vcc, s18, v162
	global_load_dwordx4 v[34:37], v[34:35], off
	s_nop 0
	v_addc_co_u32_e32 v39, vcc, 0, v163, vcc
	v_add_co_u32_e32 v42, vcc, s36, v160
	global_load_dwordx4 v[38:41], v[38:39], off
	s_nop 0
	v_addc_co_u32_e32 v43, vcc, 0, v161, vcc
	global_load_dwordx4 v[42:45], v[42:43], off
	s_mov_b64 s[18:19], 0xa0000
	s_waitcnt vmcnt(0)
; __device__ __forceinline__ unsigned cvt_pk_bf16(float lo, float hi) { const f32x2c_t v = {lo, hi}; const bf16x2c_t b = __builtin_convertvector(v, bf16x2c_t); return __builtin_bit_cast(unsigned, b); }
; __device__ __forceinline__ float bf_lo(unsigned w) { return __uint_as_float(w << 16); }
;     __device__ __forceinline__ void operator()(const f32x4 (&acc)[2][2][4][2], const Unit& u, int wr, int wc, int fr, int fq) const {
;     ...
;             for (int m = 0; m < 4; ++m) { const size_t row = (size_t)(row0 + ai * HALF + m * 16);
;                 const u32x4 gw = gp[(ai * 4 + m) * 512];
;                 u32x4 pw[2];
;                 if (SECOND) { pw[0] = mp[((ai * 4 + m) * 2 + 0) * 512]; pw[1] = mp[((ai * 4 + m) * 2 + 1) * 512]; }
; #pragma unroll
;                 for (int bj = 0; bj < 2; ++bj) { const unsigned gx = bj ? gw.z : gw.x, gy = bj ? gw.w : gw.y;
;                     const f32x4 g0 = (f32x4){(float)(gx & 255u), (float)((gx >> 8) & 255u), (float)((gx >> 16) & 255u), (float)(gx >> 24)} * K255,
;                                 g1 = (f32x4){(float)(gy & 255u), (float)((gy >> 8) & 255u), (float)((gy >> 16) & 255u), (float)(gy >> 24)} * K255;
;                     f32x4 v0 = acc[ai][bj][m][0] * g0, v1 = acc[ai][bj][m][1] * g1;
;                     if (SECOND) { const u32x4 p = pw[bj];
;                         v0 = v0 + (f32x4){bf_lo(p.x), bf_hi(p.x), bf_lo(p.y), bf_hi(p.y)}; v1 = v1 + (f32x4){bf_lo(p.z), bf_hi(p.z), bf_lo(p.w), bf_hi(p.w)}; }
;                     u32x4 w; w.x = cvt_pk_bf16(v0[0], v0[1]); w.y = cvt_pk_bf16(v0[2], v0[3]); w.z = cvt_pk_bf16(v1[0], v1[1]); w.w = cvt_pk_bf16(v1[2], v1[3]);
;                     if (SECOND) *(u32x4*)(MG + row * DM + col0 + bj * HALF) = w; else mp[((ai * 4 + m) * 2 + bj) * 512] = w; }
; template <class Epi, class Sched, bool ALIGN_EPI = false, bool SP2 = false>
; __device__ __forceinline__ void gemm_phase(PG8_LAS unsigned char* lds, const Gemm g, const Sched& S, const Epi& E) {
;     ...
;         if (!has_next) break;
; #pragma unroll
;         for (int a = 0; a < 2; ++a)
; #pragma unroll
;             for (int b = 0; b < 2; ++b)
; #pragma unroll
;                 for (int m = 0; m < 4; ++m)
; #pragma unroll
;                     for (int n = 0; n < 2; ++n) acc[a][b][m][n] = (f32x4){0.f, 0.f, 0.f, 0.f};
;         cur = nxt; cA = nA; cB = nB; ++ui;
;         if constexpr (ALIGN_EPI) { if (wr == 1) PG8_BAR; }
	v_cvt_f32_ubyte3_e32 v47, v42
	v_cvt_f32_ubyte2_e32 v46, v42
	v_cvt_f32_ubyte1_e32 v49, v42
	v_cvt_f32_ubyte0_e32 v48, v42
	v_cvt_f32_ubyte1_e32 v53, v43
	v_cvt_f32_ubyte0_e32 v52, v43
	v_pk_mul_f32 v[48:49], v[48:49], s[26:27] op_sel_hi:[1,0]
	v_pk_mul_f32 v[46:47], v[46:47], s[26:27] op_sel_hi:[1,0]
	v_cvt_f32_ubyte3_e32 v51, v43
	v_cvt_f32_ubyte2_e32 v50, v43
	v_pk_mul_f32 v[42:43], v[52:53], s[26:27] op_sel_hi:[1,0]
	v_lshlrev_b32_e32 v52, 16, v38
	v_and_b32_e32 v53, 0xffff0000, v38
	v_lshlrev_b32_e32 v38, 16, v39
	v_and_b32_e32 v39, 0xffff0000, v39
	v_pk_mul_f32 v[50:51], v[50:51], s[26:27] op_sel_hi:[1,0]
	v_pk_fma_f32 v[32:33], v[32:33], v[46:47], v[38:39]
	v_pk_fma_f32 v[30:31], v[30:31], v[48:49], v[52:53]
	v_lshlrev_b32_e32 v38, 16, v40
	v_and_b32_e32 v39, 0xffff0000, v40
	v_lshlrev_b32_e32 v40, 16, v41
	v_and_b32_e32 v41, 0xffff0000, v41
	v_pk_fma_f32 v[40:41], v[28:29], v[50:51], v[40:41]
	v_pk_fma_f32 v[28:29], v[26:27], v[42:43], v[38:39]
	v_cvt_pk_bf16_f32 v26, v30, v31
	v_lshl_add_u64 v[30:31], v[122:123], 0, s[18:19]
	s_mov_b32 s18, 0xa0000
	v_cvt_pk_bf16_f32 v27, v32, v33
	v_add_co_u32_e32 v32, vcc, s18, v122
	v_cvt_pk_bf16_f32 v28, v28, v29
	v_cvt_pk_bf16_f32 v29, v40, v41
	v_addc_co_u32_e32 v33, vcc, 0, v123, vcc
	global_store_dwordx4 v[32:33], v[26:29], off
	v_cvt_f32_ubyte3_e32 v33, v45
	v_cvt_f32_ubyte2_e32 v32, v45
	v_cvt_f32_ubyte3_e32 v27, v44
	v_cvt_f32_ubyte2_e32 v26, v44
	v_cvt_f32_ubyte1_e32 v29, v44
	v_cvt_f32_ubyte0_e32 v28, v44
	v_pk_mul_f32 v[28:29], v[28:29], s[26:27] op_sel_hi:[1,0]
	v_pk_mul_f32 v[26:27], v[26:27], s[26:27] op_sel_hi:[1,0]
	v_cvt_f32_ubyte1_e32 v39, v45
	v_cvt_f32_ubyte0_e32 v38, v45
	v_lshlrev_b32_e32 v40, 16, v34
	v_and_b32_e32 v41, 0xffff0000, v34
	v_lshlrev_b32_e32 v34, 16, v35
	v_and_b32_e32 v35, 0xffff0000, v35
	v_pk_mul_f32 v[38:39], v[38:39], s[26:27] op_sel_hi:[1,0]
	v_pk_mul_f32 v[32:33], v[32:33], s[26:27] op_sel_hi:[1,0]
	v_pk_fma_f32 v[24:25], v[24:25], v[26:27], v[34:35]
	v_pk_fma_f32 v[22:23], v[22:23], v[28:29], v[40:41]
	v_lshlrev_b32_e32 v26, 16, v36
	v_and_b32_e32 v27, 0xffff0000, v36
	v_lshlrev_b32_e32 v28, 16, v37
	v_and_b32_e32 v29, 0xffff0000, v37
	v_pk_fma_f32 v[28:29], v[20:21], v[32:33], v[28:29]
	v_pk_fma_f32 v[20:21], v[18:19], v[38:39], v[26:27]
	v_cvt_pk_bf16_f32 v18, v22, v23
	v_cvt_pk_bf16_f32 v19, v24, v25
	v_cvt_pk_bf16_f32 v20, v20, v21
	v_cvt_pk_bf16_f32 v21, v28, v29
	s_mov_b32 s18, 0x1e000
	global_store_dwordx4 v[30:31], v[18:21], off offset:256
	s_nop 1
	v_add_co_u32_e32 v18, vcc, s18, v162
	s_mov_b32 s18, 0x1c000
	s_nop 0
	v_addc_co_u32_e32 v19, vcc, 0, v163, vcc
	v_add_co_u32_e32 v22, vcc, s18, v162
	global_load_dwordx4 v[18:21], v[18:19], off
	s_nop 0
	v_addc_co_u32_e32 v23, vcc, 0, v163, vcc
	v_add_co_u32_e32 v26, vcc, s37, v160
	global_load_dwordx4 v[22:25], v[22:23], off
	s_nop 0
	v_addc_co_u32_e32 v27, vcc, 0, v161, vcc
	global_load_dwordx4 v[26:29], v[26:27], off
	s_mov_b64 s[18:19], 0xb0000
	s_waitcnt vmcnt(0)
	v_cvt_f32_ubyte3_e32 v31, v26
	v_cvt_f32_ubyte2_e32 v30, v26
	v_cvt_f32_ubyte1_e32 v37, v27
	v_cvt_f32_ubyte0_e32 v36, v27
	v_cvt_f32_ubyte1_e32 v33, v26
	v_cvt_f32_ubyte0_e32 v32, v26
	v_pk_mul_f32 v[30:31], v[30:31], s[26:27] op_sel_hi:[1,0]
	v_cvt_f32_ubyte3_e32 v35, v27
	v_cvt_f32_ubyte2_e32 v34, v27
	v_pk_mul_f32 v[26:27], v[36:37], s[26:27] op_sel_hi:[1,0]
	v_lshlrev_b32_e32 v36, 16, v22
	v_and_b32_e32 v37, 0xffff0000, v22
	v_lshlrev_b32_e32 v22, 16, v23
	v_and_b32_e32 v23, 0xffff0000, v23
	v_pk_mul_f32 v[32:33], v[32:33], s[26:27] op_sel_hi:[1,0]
	v_pk_fma_f32 v[16:17], v[16:17], v[30:31], v[22:23]
	v_lshlrev_b32_e32 v22, 16, v24
	v_and_b32_e32 v23, 0xffff0000, v24
	v_pk_mul_f32 v[34:35], v[34:35], s[26:27] op_sel_hi:[1,0]
	v_pk_fma_f32 v[14:15], v[14:15], v[32:33], v[36:37]
	v_lshlrev_b32_e32 v24, 16, v25
	v_and_b32_e32 v25, 0xffff0000, v25
	v_pk_fma_f32 v[10:11], v[10:11], v[26:27], v[22:23]
	v_pk_fma_f32 v[24:25], v[12:13], v[34:35], v[24:25]
	v_cvt_pk_bf16_f32 v12, v14, v15
	v_cvt_pk_bf16_f32 v14, v10, v11
	v_lshl_add_u64 v[10:11], v[122:123], 0, s[18:19]
	s_mov_b32 s18, 0xb0000
	v_cvt_pk_bf16_f32 v13, v16, v17
	v_add_co_u32_e32 v16, vcc, s18, v122
	v_cvt_pk_bf16_f32 v15, v24, v25
	s_nop 0
	v_addc_co_u32_e32 v17, vcc, 0, v123, vcc
	global_store_dwordx4 v[16:17], v[12:15], off
	v_cvt_f32_ubyte3_e32 v17, v29
	v_cvt_f32_ubyte2_e32 v16, v29
	v_cvt_f32_ubyte3_e32 v13, v28
	v_cvt_f32_ubyte2_e32 v12, v28
	v_cvt_f32_ubyte1_e32 v15, v28
	v_cvt_f32_ubyte0_e32 v14, v28
	v_pk_mul_f32 v[14:15], v[14:15], s[26:27] op_sel_hi:[1,0]
	v_pk_mul_f32 v[12:13], v[12:13], s[26:27] op_sel_hi:[1,0]
	v_cvt_f32_ubyte1_e32 v23, v29
	v_cvt_f32_ubyte0_e32 v22, v29
	v_lshlrev_b32_e32 v24, 16, v18
	v_and_b32_e32 v25, 0xffff0000, v18
	v_lshlrev_b32_e32 v18, 16, v19
	v_and_b32_e32 v19, 0xffff0000, v19
	v_pk_mul_f32 v[22:23], v[22:23], s[26:27] op_sel_hi:[1,0]
	v_pk_mul_f32 v[16:17], v[16:17], s[26:27] op_sel_hi:[1,0]
	v_pk_fma_f32 v[8:9], v[8:9], v[12:13], v[18:19]
	v_pk_fma_f32 v[6:7], v[6:7], v[14:15], v[24:25]
	v_lshlrev_b32_e32 v12, 16, v20
	v_and_b32_e32 v13, 0xffff0000, v20
	v_lshlrev_b32_e32 v14, 16, v21
	v_and_b32_e32 v15, 0xffff0000, v21
	v_pk_fma_f32 v[14:15], v[4:5], v[16:17], v[14:15]
	v_pk_fma_f32 v[4:5], v[2:3], v[22:23], v[12:13]
	v_cvt_pk_bf16_f32 v2, v6, v7
	v_cvt_pk_bf16_f32 v3, v8, v9
	v_cvt_pk_bf16_f32 v4, v4, v5
	v_cvt_pk_bf16_f32 v5, v14, v15
	global_store_dwordx4 v[10:11], v[2:5], off offset:256
	s_mov_b64 s[18:19], -1
	s_and_b64 vcc, exec, s[40:41]
	s_cbranch_vccnz .LBB0_148
	s_andn2_b64 vcc, exec, s[8:9]
	s_cbranch_vccnz .LBB0_147
	s_nop 0
	s_branch .LBB0_147

; #define PG8_STAGE(bufoff, gbase, voff) do { _Pragma("unroll") for (int _i = 0; _i < 2; ++_i) \
;         __builtin_amdgcn_global_load_lds((const unsigned*)((const char*)(gbase) + (voff)[_i]), (PG8_LAS unsigned*)(lds + (bufoff) + ldsw + _i * 8192), 16, 0, 0); } while (0)
; #define PG8_LDA(dst, b, h) do { _Pragma("unroll") for (int m = 0; m < 4; ++m) _Pragma("unroll") for (int k = 0; k < 2; ++k) dst[m][k] = *(const PG8_LAS bf16x8*)(lds + PG8_SA(b, h) + aoff + m * 2048 + k * 1024); } while (0)
; #define PG8_LDB(dst, b, h) do { _Pragma("unroll") for (int n = 0; n < 2; ++n) _Pragma("unroll") for (int k = 0; k < 2; ++k) dst[n][k] = *(const PG8_LAS bf16x8*)(lds + PG8_SB(b, h) + boff + n * 2048 + k * 1024); } while (0)
; template <class Epi, class Sched, bool ALIGN_EPI = false, bool SP2 = false>
; __device__ __forceinline__ void gemm_phase(PG8_LAS unsigned char* lds, const Gemm g, const Sched& S, const Epi& E) {
;     ...
;         for (int t = 0; t < nt; t += 2) {
;             const bool last = (t == nt - 2);
;             const char* a1 = cA + (size_t)(t + 1) * kstep;
;             const char* a2 = last ? nA : cA + (size_t)(t + 2) * kstep; const char* b2 = last ? nB : cB + (size_t)(t + 2) * kstep;
;             const char* a3 = a2 + kstep; const char* b3 = b2 + kstep;
;             if (last && has_next) S.a_ready(nxt);
;             if constexpr (SP2) {
;             PG8_LDB(B0, 0, 0); PG8_LDB(B1, 0, 1); PG8_SCHED; PG8_LDA(At, 0, 0); PG8_STAGE(PG8_SA(1, 1), a1 + hstep, voffA);
;             PG8_WAIT_V(8); PG8_WAIT_L(0); PG8_BAR; PG8_MMA(0, 0, At, B0); PG8_MMA(0, 1, At, B1); PG8_BAR; PG8_SCHED;
;             PG8_LDA(At, 0, 1); PG8_STAGE(PG8_SB(0, 0), b2, voffB); PG8_STAGE(PG8_SB(0, 1), b2 + hstep, voffB); PG8_STAGE(PG8_SA(0, 0), a2, voffA);
;             PG8_WAIT_V(8); PG8_WAIT_L(0); PG8_BAR; PG8_MMA(1, 0, At, B0); PG8_MMA(1, 1, At, B1); PG8_BAR; PG8_SCHED;
;             PG8_LDB(B0, 1, 0); PG8_LDB(B1, 1, 1); PG8_SCHED; PG8_LDA(At, 1, 0); PG8_STAGE(PG8_SA(0, 1), a2 + hstep, voffA);
;             PG8_WAIT_V(8); PG8_WAIT_L(0); PG8_BAR; PG8_MMA(0, 0, At, B0); PG8_MMA(0, 1, At, B1); PG8_BAR; PG8_SCHED;
;             PG8_LDA(At, 1, 1); PG8_STAGE(PG8_SB(1, 0), b3, voffB); PG8_STAGE(PG8_SB(1, 1), b3 + hstep, voffB); PG8_STAGE(PG8_SA(1, 0), a3, voffA);
;             PG8_WAIT_V(8); PG8_WAIT_L(0); PG8_BAR; PG8_MMA(1, 0, At, B0); PG8_MMA(1, 1, At, B1); PG8_BAR; PG8_SCHED;
.LBB0_281:
	s_add_u32 s18, s36, 0xfff80080
	s_addc_u32 s19, s37, -1
	s_add_i32 s73, 0, 0x10000
	s_cmp_eq_u32 s67, 28
	s_cselect_b32 s43, s9, s19
	s_cselect_b32 s42, s59, s18
	v_add_u32_e32 v163, s73, v160
	s_cselect_b32 s19, s7, s63
	s_cselect_b32 s18, s60, s62
	s_add_i32 s76, 0, 0x14000
	ds_read_b128 v[156:159], v163
	ds_read_b128 v[164:167], v163 offset:1024
	ds_read_b128 v[168:171], v163 offset:2048
	ds_read_b128 v[172:175], v163 offset:3072
	v_add_u32_e32 v163, s76, v160
	ds_read_b128 v[176:179], v163
	ds_read_b128 v[180:183], v163 offset:1024
	ds_read_b128 v[184:187], v163 offset:2048
	ds_read_b128 v[204:207], v163 offset:3072
	v_lshl_add_u64 v[240:241], s[36:37], 0, v[152:153]
	s_add_i32 m0, s30, 0xc000
	ds_read_b128 v[208:211], v162
	ds_read_b128 v[212:215], v162 offset:1024
	ds_read_b128 v[216:219], v162 offset:2048
	ds_read_b128 v[220:223], v162 offset:3072
	ds_read_b128 v[224:227], v162 offset:4096
	ds_read_b128 v[228:231], v162 offset:5120
	ds_read_b128 v[232:235], v162 offset:6144
	ds_read_b128 v[236:239], v162 offset:7168
	global_load_lds_dwordx4 v[240:241], off
	v_lshl_add_u64 v[240:241], s[36:37], 0, v[154:155]
	s_add_i32 m0, s30, 0xe000
	s_nop 0
	global_load_lds_dwordx4 v[240:241], off
	s_nop 0
	s_nop 0
	s_nop 0
	s_waitcnt vmcnt(8)
	s_waitcnt lgkmcnt(0)
	s_setprio 1
	s_barrier
	v_mfma_f32_16x16x32_bf16 v[126:129], v[156:159], v[208:211], v[126:129]
	v_mfma_f32_16x16x32_bf16 v[122:125], v[168:171], v[208:211], v[122:125]
	v_mfma_f32_16x16x32_bf16 v[110:113], v[156:159], v[216:219], v[110:113]
	v_mfma_f32_16x16x32_bf16 v[106:109], v[168:171], v[216:219], v[106:109]
	v_mfma_f32_16x16x32_bf16 v[94:97], v[156:159], v[224:227], v[94:97]
	v_mfma_f32_16x16x32_bf16 v[90:93], v[168:171], v[224:227], v[90:93]
	v_mfma_f32_16x16x32_bf16 v[78:81], v[156:159], v[232:235], v[78:81]
	v_mfma_f32_16x16x32_bf16 v[74:77], v[168:171], v[232:235], v[74:77]
	s_setprio 0
	s_setprio 1
	v_mfma_f32_16x16x32_bf16 v[126:129], v[164:167], v[212:215], v[126:129]
	v_mfma_f32_16x16x32_bf16 v[122:125], v[172:175], v[212:215], v[122:125]
	v_mfma_f32_16x16x32_bf16 v[110:113], v[164:167], v[220:223], v[110:113]
	v_mfma_f32_16x16x32_bf16 v[106:109], v[172:175], v[220:223], v[106:109]
	v_mfma_f32_16x16x32_bf16 v[94:97], v[164:167], v[228:231], v[94:97]
	v_mfma_f32_16x16x32_bf16 v[90:93], v[172:175], v[228:231], v[90:93]
	v_mfma_f32_16x16x32_bf16 v[78:81], v[164:167], v[236:239], v[78:81]
	v_mfma_f32_16x16x32_bf16 v[74:77], v[172:175], v[236:239], v[74:77]
	s_setprio 0
	s_setprio 1
	v_mfma_f32_16x16x32_bf16 v[118:121], v[176:179], v[208:211], v[118:121]
	v_mfma_f32_16x16x32_bf16 v[114:117], v[184:187], v[208:211], v[114:117]
	v_mfma_f32_16x16x32_bf16 v[102:105], v[176:179], v[216:219], v[102:105]
	v_mfma_f32_16x16x32_bf16 v[98:101], v[184:187], v[216:219], v[98:101]
	v_mfma_f32_16x16x32_bf16 v[86:89], v[176:179], v[224:227], v[86:89]
	v_mfma_f32_16x16x32_bf16 v[82:85], v[184:187], v[224:227], v[82:85]
	v_mfma_f32_16x16x32_bf16 v[70:73], v[176:179], v[232:235], v[70:73]
	v_mfma_f32_16x16x32_bf16 v[66:69], v[184:187], v[232:235], v[66:69]
	s_setprio 0
	s_setprio 1
	v_mfma_f32_16x16x32_bf16 v[118:121], v[180:183], v[212:215], v[118:121]
	v_mfma_f32_16x16x32_bf16 v[114:117], v[204:207], v[212:215], v[114:117]
	v_mfma_f32_16x16x32_bf16 v[102:105], v[180:183], v[220:223], v[102:105]
	v_mfma_f32_16x16x32_bf16 v[98:101], v[204:207], v[220:223], v[98:101]
	v_mfma_f32_16x16x32_bf16 v[86:89], v[180:183], v[228:231], v[86:89]
	v_mfma_f32_16x16x32_bf16 v[82:85], v[204:207], v[228:231], v[82:85]
	v_mfma_f32_16x16x32_bf16 v[70:73], v[180:183], v[236:239], v[70:73]
	v_mfma_f32_16x16x32_bf16 v[66:69], v[204:207], v[236:239], v[66:69]
	s_setprio 0
	s_barrier
	s_add_i32 s73, s73, s28
	v_lshl_add_u64 v[240:241], s[18:19], 0, v[146:147]
	s_mov_b32 m0, s73
	ds_read_b128 v[208:211], v162 offset:16384
	ds_read_b128 v[212:215], v162 offset:17408
	ds_read_b128 v[216:219], v162 offset:18432
	ds_read_b128 v[220:223], v162 offset:19456
	ds_read_b128 v[224:227], v162 offset:20480
	ds_read_b128 v[228:231], v162 offset:21504
	ds_read_b128 v[232:235], v162 offset:22528
	ds_read_b128 v[236:239], v162 offset:23552
	global_load_lds_dwordx4 v[240:241], off
	s_add_i32 m0, s73, 0x2000
	s_add_u32 s78, s18, 0x80000
	v_lshl_add_u64 v[242:243], s[18:19], 0, v[142:143]
	s_addc_u32 s79, s19, 0
	s_add_i32 s73, s76, s28
	global_load_lds_dwordx4 v[242:243], off
	v_lshl_add_u64 v[244:245], s[78:79], 0, v[146:147]
	s_mov_b32 m0, s73
	v_lshl_add_u64 v[246:247], s[42:43], 0, v[144:145]
	global_load_lds_dwordx4 v[244:245], off
	v_lshl_add_u64 v[244:245], s[78:79], 0, v[142:143]
	s_add_i32 m0, s73, 0x2000
	s_nop 0
	global_load_lds_dwordx4 v[244:245], off
	v_lshl_add_u64 v[244:245], s[42:43], 0, v[148:149]
	s_mov_b32 m0, s30
	s_nop 0
	global_load_lds_dwordx4 v[244:245], off
	s_mov_b32 m0, s34
	s_nop 0
	global_load_lds_dwordx4 v[246:247], off
	s_waitcnt vmcnt(8)
	s_waitcnt lgkmcnt(0)
	s_setprio 1
	s_barrier
; #define PG8_STAGE(bufoff, gbase, voff) do { _Pragma("unroll") for (int _i = 0; _i < 2; ++_i) \
;         __builtin_amdgcn_global_load_lds((const unsigned*)((const char*)(gbase) + (voff)[_i]), (PG8_LAS unsigned*)(lds + (bufoff) + ldsw + _i * 8192), 16, 0, 0); } while (0)
; #define PG8_LDA(dst, b, h) do { _Pragma("unroll") for (int m = 0; m < 4; ++m) _Pragma("unroll") for (int k = 0; k < 2; ++k) dst[m][k] = *(const PG8_LAS bf16x8*)(lds + PG8_SA(b, h) + aoff + m * 2048 + k * 1024); } while (0)
; #define PG8_LDB(dst, b, h) do { _Pragma("unroll") for (int n = 0; n < 2; ++n) _Pragma("unroll") for (int k = 0; k < 2; ++k) dst[n][k] = *(const PG8_LAS bf16x8*)(lds + PG8_SB(b, h) + boff + n * 2048 + k * 1024); } while (0)
; #define PG8_MMA(ai, bj, At, Bt) do { __builtin_amdgcn_s_setprio(1); _Pragma("unroll") for (int m = 0; m < 4; ++m) _Pragma("unroll") for (int n = 0; n < 2; ++n) _Pragma("unroll") for (int k = 0; k < 2; ++k) \
;         acc[ai][bj][m][n] = __builtin_amdgcn_mfma_f32_16x16x32_bf16(Bt[n][k], At[m][k], acc[ai][bj][m][n], 0, 0, 0); __builtin_amdgcn_s_setprio(0); } while (0)
; #define PG8_BAR __builtin_amdgcn_s_barrier()
; template <class Epi, class Sched, bool ALIGN_EPI = false, bool SP2 = false>
; __device__ __forceinline__ void gemm_phase(PG8_LAS unsigned char* lds, const Gemm g, const Sched& S, const Epi& E) {
;     ...
;             if constexpr (SP2) {
;             PG8_LDB(B0, 0, 0); PG8_LDB(B1, 0, 1); PG8_SCHED; PG8_LDA(At, 0, 0); PG8_STAGE(PG8_SA(1, 1), a1 + hstep, voffA);
;             PG8_WAIT_V(8); PG8_WAIT_L(0); PG8_BAR; PG8_MMA(0, 0, At, B0); PG8_MMA(0, 1, At, B1); PG8_BAR; PG8_SCHED;
;             PG8_LDA(At, 0, 1); PG8_STAGE(PG8_SB(0, 0), b2, voffB); PG8_STAGE(PG8_SB(0, 1), b2 + hstep, voffB); PG8_STAGE(PG8_SA(0, 0), a2, voffA);
;             PG8_WAIT_V(8); PG8_WAIT_L(0); PG8_BAR; PG8_MMA(1, 0, At, B0); PG8_MMA(1, 1, At, B1); PG8_BAR; PG8_SCHED;
;             PG8_LDB(B0, 1, 0); PG8_LDB(B1, 1, 1); PG8_SCHED; PG8_LDA(At, 1, 0); PG8_STAGE(PG8_SA(0, 1), a2 + hstep, voffA);
;             PG8_WAIT_V(8); PG8_WAIT_L(0); PG8_BAR; PG8_MMA(0, 0, At, B0); PG8_MMA(0, 1, At, B1); PG8_BAR; PG8_SCHED;
;             PG8_LDA(At, 1, 1); PG8_STAGE(PG8_SB(1, 0), b3, voffB); PG8_STAGE(PG8_SB(1, 1), b3 + hstep, voffB); PG8_STAGE(PG8_SA(1, 0), a3, voffA);
;             PG8_WAIT_V(8); PG8_WAIT_L(0); PG8_BAR; PG8_MMA(1, 0, At, B0); PG8_MMA(1, 1, At, B1); PG8_BAR; PG8_SCHED;
	v_mfma_f32_16x16x32_bf16 v[62:65], v[156:159], v[208:211], v[62:65]
	v_mfma_f32_16x16x32_bf16 v[58:61], v[168:171], v[208:211], v[58:61]
	v_mfma_f32_16x16x32_bf16 v[46:49], v[156:159], v[216:219], v[46:49]
	v_mfma_f32_16x16x32_bf16 v[42:45], v[168:171], v[216:219], v[42:45]
	v_mfma_f32_16x16x32_bf16 v[30:33], v[156:159], v[224:227], v[30:33]
	v_mfma_f32_16x16x32_bf16 v[26:29], v[168:171], v[224:227], v[26:29]
	v_mfma_f32_16x16x32_bf16 v[14:17], v[156:159], v[232:235], v[14:17]
	v_mfma_f32_16x16x32_bf16 v[10:13], v[168:171], v[232:235], v[10:13]
	v_mfma_f32_16x16x32_bf16 v[62:65], v[164:167], v[212:215], v[62:65]
	v_mfma_f32_16x16x32_bf16 v[58:61], v[172:175], v[212:215], v[58:61]
	v_mfma_f32_16x16x32_bf16 v[46:49], v[164:167], v[220:223], v[46:49]
	v_mfma_f32_16x16x32_bf16 v[42:45], v[172:175], v[220:223], v[42:45]
	v_mfma_f32_16x16x32_bf16 v[30:33], v[164:167], v[228:231], v[30:33]
	v_mfma_f32_16x16x32_bf16 v[26:29], v[172:175], v[228:231], v[26:29]
	v_mfma_f32_16x16x32_bf16 v[14:17], v[164:167], v[236:239], v[14:17]
	v_mfma_f32_16x16x32_bf16 v[10:13], v[172:175], v[236:239], v[10:13]
	v_mfma_f32_16x16x32_bf16 v[54:57], v[176:179], v[208:211], v[54:57]
	v_mfma_f32_16x16x32_bf16 v[50:53], v[184:187], v[208:211], v[50:53]
	v_mfma_f32_16x16x32_bf16 v[38:41], v[176:179], v[216:219], v[38:41]
	v_mfma_f32_16x16x32_bf16 v[34:37], v[184:187], v[216:219], v[34:37]
	v_mfma_f32_16x16x32_bf16 v[22:25], v[176:179], v[224:227], v[22:25]
	v_mfma_f32_16x16x32_bf16 v[18:21], v[184:187], v[224:227], v[18:21]
	v_mfma_f32_16x16x32_bf16 v[6:9], v[176:179], v[232:235], v[6:9]
	v_mfma_f32_16x16x32_bf16 v[2:5], v[184:187], v[232:235], v[2:5]
	v_mfma_f32_16x16x32_bf16 v[54:57], v[180:183], v[212:215], v[54:57]
	v_mfma_f32_16x16x32_bf16 v[50:53], v[204:207], v[212:215], v[50:53]
	v_mfma_f32_16x16x32_bf16 v[38:41], v[180:183], v[220:223], v[38:41]
	v_mfma_f32_16x16x32_bf16 v[34:37], v[204:207], v[220:223], v[34:37]
	v_mfma_f32_16x16x32_bf16 v[22:25], v[180:183], v[228:231], v[22:25]
	v_mfma_f32_16x16x32_bf16 v[18:21], v[204:207], v[228:231], v[18:21]
	v_mfma_f32_16x16x32_bf16 v[6:9], v[180:183], v[236:239], v[6:9]
	v_mfma_f32_16x16x32_bf16 v[2:5], v[204:207], v[236:239], v[2:5]
	s_setprio 0
	s_barrier
	s_add_i32 s73, 0, 0x18000
	v_add_u32_e32 v163, s73, v160
	s_add_i32 s76, 0, 0x1c000
	ds_read_b128 v[156:159], v163
	ds_read_b128 v[164:167], v163 offset:1024
	ds_read_b128 v[168:171], v163 offset:2048
	ds_read_b128 v[172:175], v163 offset:3072
	v_add_u32_e32 v163, s76, v160
	ds_read_b128 v[176:179], v163
	ds_read_b128 v[180:183], v163 offset:1024
	ds_read_b128 v[184:187], v163 offset:2048
	ds_read_b128 v[204:207], v163 offset:3072
	s_add_u32 s42, s42, 0x80000
	s_addc_u32 s43, s43, 0
	s_mov_b32 m0, s44
	v_lshl_add_u64 v[248:249], s[42:43], 0, v[148:149]
	ds_read_b128 v[208:211], v162 offset:32768
	ds_read_b128 v[212:215], v162 offset:33792
	ds_read_b128 v[216:219], v162 offset:34816
	ds_read_b128 v[220:223], v162 offset:35840
	ds_read_b128 v[224:227], v162 offset:36864
	ds_read_b128 v[228:231], v162 offset:37888
	ds_read_b128 v[232:235], v162 offset:38912
	ds_read_b128 v[236:239], v162 offset:39936
	global_load_lds_dwordx4 v[248:249], off
	v_lshl_add_u64 v[248:249], s[42:43], 0, v[144:145]
	s_mov_b32 m0, s45
	s_nop 0
	global_load_lds_dwordx4 v[248:249], off
	s_waitcnt vmcnt(8)
	s_waitcnt lgkmcnt(0)
	s_setprio 1
	s_barrier
	v_mfma_f32_16x16x32_bf16 v[126:129], v[156:159], v[208:211], v[126:129]
	v_mfma_f32_16x16x32_bf16 v[122:125], v[168:171], v[208:211], v[122:125]
	v_mfma_f32_16x16x32_bf16 v[110:113], v[156:159], v[216:219], v[110:113]
	v_mfma_f32_16x16x32_bf16 v[106:109], v[168:171], v[216:219], v[106:109]
	v_mfma_f32_16x16x32_bf16 v[94:97], v[156:159], v[224:227], v[94:97]
	v_mfma_f32_16x16x32_bf16 v[90:93], v[168:171], v[224:227], v[90:93]
	v_mfma_f32_16x16x32_bf16 v[78:81], v[156:159], v[232:235], v[78:81]
	v_mfma_f32_16x16x32_bf16 v[74:77], v[168:171], v[232:235], v[74:77]
	s_setprio 0
	s_setprio 1
	v_mfma_f32_16x16x32_bf16 v[126:129], v[164:167], v[212:215], v[126:129]
	v_mfma_f32_16x16x32_bf16 v[122:125], v[172:175], v[212:215], v[122:125]
	v_mfma_f32_16x16x32_bf16 v[110:113], v[164:167], v[220:223], v[110:113]
	v_mfma_f32_16x16x32_bf16 v[106:109], v[172:175], v[220:223], v[106:109]
	v_mfma_f32_16x16x32_bf16 v[94:97], v[164:167], v[228:231], v[94:97]
	v_mfma_f32_16x16x32_bf16 v[90:93], v[172:175], v[228:231], v[90:93]
	v_mfma_f32_16x16x32_bf16 v[78:81], v[164:167], v[236:239], v[78:81]
	v_mfma_f32_16x16x32_bf16 v[74:77], v[172:175], v[236:239], v[74:77]
	s_setprio 0
	s_setprio 1
	v_mfma_f32_16x16x32_bf16 v[118:121], v[176:179], v[208:211], v[118:121]
	v_mfma_f32_16x16x32_bf16 v[114:117], v[184:187], v[208:211], v[114:117]
	v_mfma_f32_16x16x32_bf16 v[102:105], v[176:179], v[216:219], v[102:105]
	v_mfma_f32_16x16x32_bf16 v[98:101], v[184:187], v[216:219], v[98:101]
	v_mfma_f32_16x16x32_bf16 v[86:89], v[176:179], v[224:227], v[86:89]
	v_mfma_f32_16x16x32_bf16 v[82:85], v[184:187], v[224:227], v[82:85]
	v_mfma_f32_16x16x32_bf16 v[70:73], v[176:179], v[232:235], v[70:73]
	v_mfma_f32_16x16x32_bf16 v[66:69], v[184:187], v[232:235], v[66:69]
	s_setprio 0
	s_setprio 1
	v_mfma_f32_16x16x32_bf16 v[118:121], v[180:183], v[212:215], v[118:121]
	v_mfma_f32_16x16x32_bf16 v[114:117], v[204:207], v[212:215], v[114:117]
	v_mfma_f32_16x16x32_bf16 v[102:105], v[180:183], v[220:223], v[102:105]
	v_mfma_f32_16x16x32_bf16 v[98:101], v[204:207], v[220:223], v[98:101]
	v_mfma_f32_16x16x32_bf16 v[86:89], v[180:183], v[228:231], v[86:89]
	v_mfma_f32_16x16x32_bf16 v[82:85], v[204:207], v[228:231], v[82:85]
	v_mfma_f32_16x16x32_bf16 v[70:73], v[180:183], v[236:239], v[70:73]
	v_mfma_f32_16x16x32_bf16 v[66:69], v[204:207], v[236:239], v[66:69]
	s_setprio 0
	s_barrier
; #define PG8_STAGE(bufoff, gbase, voff) do { _Pragma("unroll") for (int _i = 0; _i < 2; ++_i) \
;         __builtin_amdgcn_global_load_lds((const unsigned*)((const char*)(gbase) + (voff)[_i]), (PG8_LAS unsigned*)(lds + (bufoff) + ldsw + _i * 8192), 16, 0, 0); } while (0)
; #define PG8_LDA(dst, b, h) do { _Pragma("unroll") for (int m = 0; m < 4; ++m) _Pragma("unroll") for (int k = 0; k < 2; ++k) dst[m][k] = *(const PG8_LAS bf16x8*)(lds + PG8_SA(b, h) + aoff + m * 2048 + k * 1024); } while (0)
; #define PG8_LDB(dst, b, h) do { _Pragma("unroll") for (int n = 0; n < 2; ++n) _Pragma("unroll") for (int k = 0; k < 2; ++k) dst[n][k] = *(const PG8_LAS bf16x8*)(lds + PG8_SB(b, h) + boff + n * 2048 + k * 1024); } while (0)
; #define PG8_MMA(ai, bj, At, Bt) do { __builtin_amdgcn_s_setprio(1); _Pragma("unroll") for (int m = 0; m < 4; ++m) _Pragma("unroll") for (int n = 0; n < 2; ++n) _Pragma("unroll") for (int k = 0; k < 2; ++k) \
;         acc[ai][bj][m][n] = __builtin_amdgcn_mfma_f32_16x16x32_bf16(Bt[n][k], At[m][k], acc[ai][bj][m][n], 0, 0, 0); __builtin_amdgcn_s_setprio(0); } while (0)
; #define PG8_WAIT_V(n) asm volatile("s_waitcnt vmcnt(" #n ")" ::: "memory")
; #define PG8_WAIT_L(n) asm volatile("s_waitcnt lgkmcnt(" #n ")" ::: "memory")
; #define PG8_BAR __builtin_amdgcn_s_barrier()
; #define PG8_SCHED __builtin_amdgcn_sched_barrier(0)
; template <class Epi, class Sched, bool ALIGN_EPI = false, bool SP2 = false>
; __device__ __forceinline__ void gemm_phase(PG8_LAS unsigned char* lds, const Gemm g, const Sched& S, const Epi& E) {
;     ...
;             PG8_WAIT_V(8); PG8_WAIT_L(0); PG8_BAR; PG8_MMA(1, 0, At, B0); PG8_MMA(1, 1, At, B1); PG8_BAR; PG8_SCHED;
;             PG8_LDB(B0, 1, 0); PG8_LDB(B1, 1, 1); PG8_SCHED; PG8_LDA(At, 1, 0); PG8_STAGE(PG8_SA(0, 1), a2 + hstep, voffA);
;             PG8_WAIT_V(8); PG8_WAIT_L(0); PG8_BAR; PG8_MMA(0, 0, At, B0); PG8_MMA(0, 1, At, B1); PG8_BAR; PG8_SCHED;
;             PG8_LDA(At, 1, 1); PG8_STAGE(PG8_SB(1, 0), b3, voffB); PG8_STAGE(PG8_SB(1, 1), b3 + hstep, voffB); PG8_STAGE(PG8_SA(1, 0), a3, voffA);
;             PG8_WAIT_V(8); PG8_WAIT_L(0); PG8_BAR; PG8_MMA(1, 0, At, B0); PG8_MMA(1, 1, At, B1); PG8_BAR; PG8_SCHED;
;     ...
;         if constexpr (ALIGN_EPI) { if (wr == 0) PG8_BAR; }
	s_add_i32 s42, s73, s28
	v_lshl_add_u64 v[240:241], v[240:241], 0, s[68:69]
	s_mov_b32 m0, s42
	ds_read_b128 v[208:211], v162 offset:49152
	ds_read_b128 v[212:215], v162 offset:50176
	ds_read_b128 v[216:219], v162 offset:51200
	ds_read_b128 v[220:223], v162 offset:52224
	ds_read_b128 v[224:227], v162 offset:53248
	ds_read_b128 v[228:231], v162 offset:54272
	ds_read_b128 v[232:235], v162 offset:55296
	ds_read_b128 v[236:239], v162 offset:56320
	global_load_lds_dwordx4 v[240:241], off
	s_add_i32 m0, s42, 0x2000
	s_add_u32 s18, s18, 0x80080
	v_lshl_add_u64 v[240:241], v[242:243], 0, s[68:69]
	s_addc_u32 s19, s19, 0
	s_add_i32 s42, s76, s28
	global_load_lds_dwordx4 v[240:241], off
	v_lshl_add_u64 v[240:241], s[18:19], 0, v[146:147]
	s_mov_b32 m0, s42
	s_nop 0
	global_load_lds_dwordx4 v[240:241], off
	v_lshl_add_u64 v[240:241], s[18:19], 0, v[142:143]
	s_add_i32 m0, s42, 0x2000
	s_nop 0
	global_load_lds_dwordx4 v[240:241], off
	v_lshl_add_u64 v[240:241], v[244:245], 0, s[68:69]
	s_mov_b32 m0, s46
	s_nop 0
	global_load_lds_dwordx4 v[240:241], off
	v_lshl_add_u64 v[240:241], v[246:247], 0, s[68:69]
	s_mov_b32 m0, s47
	s_nop 0
	global_load_lds_dwordx4 v[240:241], off
	s_nop 0
	s_waitcnt vmcnt(8)
	s_waitcnt lgkmcnt(0)
	s_setprio 1
	s_barrier
	v_mfma_f32_16x16x32_bf16 v[62:65], v[156:159], v[208:211], v[62:65]
	v_mfma_f32_16x16x32_bf16 v[58:61], v[168:171], v[208:211], v[58:61]
	v_mfma_f32_16x16x32_bf16 v[46:49], v[156:159], v[216:219], v[46:49]
	v_mfma_f32_16x16x32_bf16 v[42:45], v[168:171], v[216:219], v[42:45]
	v_mfma_f32_16x16x32_bf16 v[30:33], v[156:159], v[224:227], v[30:33]
	v_mfma_f32_16x16x32_bf16 v[26:29], v[168:171], v[224:227], v[26:29]
	v_mfma_f32_16x16x32_bf16 v[14:17], v[156:159], v[232:235], v[14:17]
	v_mfma_f32_16x16x32_bf16 v[10:13], v[168:171], v[232:235], v[10:13]
	v_mfma_f32_16x16x32_bf16 v[62:65], v[164:167], v[212:215], v[62:65]
	v_mfma_f32_16x16x32_bf16 v[58:61], v[172:175], v[212:215], v[58:61]
	v_mfma_f32_16x16x32_bf16 v[46:49], v[164:167], v[220:223], v[46:49]
	v_mfma_f32_16x16x32_bf16 v[42:45], v[172:175], v[220:223], v[42:45]
	v_mfma_f32_16x16x32_bf16 v[30:33], v[164:167], v[228:231], v[30:33]
	v_mfma_f32_16x16x32_bf16 v[26:29], v[172:175], v[228:231], v[26:29]
	v_mfma_f32_16x16x32_bf16 v[14:17], v[164:167], v[236:239], v[14:17]
	v_mfma_f32_16x16x32_bf16 v[10:13], v[172:175], v[236:239], v[10:13]
	v_mfma_f32_16x16x32_bf16 v[54:57], v[176:179], v[208:211], v[54:57]
	v_mfma_f32_16x16x32_bf16 v[50:53], v[184:187], v[208:211], v[50:53]
	v_mfma_f32_16x16x32_bf16 v[38:41], v[176:179], v[216:219], v[38:41]
	v_mfma_f32_16x16x32_bf16 v[34:37], v[184:187], v[216:219], v[34:37]
	v_mfma_f32_16x16x32_bf16 v[22:25], v[176:179], v[224:227], v[22:25]
	v_mfma_f32_16x16x32_bf16 v[18:21], v[184:187], v[224:227], v[18:21]
	v_mfma_f32_16x16x32_bf16 v[6:9], v[176:179], v[232:235], v[6:9]
	v_mfma_f32_16x16x32_bf16 v[2:5], v[184:187], v[232:235], v[2:5]
	v_mfma_f32_16x16x32_bf16 v[54:57], v[180:183], v[212:215], v[54:57]
	v_mfma_f32_16x16x32_bf16 v[50:53], v[204:207], v[212:215], v[50:53]
	v_mfma_f32_16x16x32_bf16 v[38:41], v[180:183], v[220:223], v[38:41]
	v_mfma_f32_16x16x32_bf16 v[34:37], v[204:207], v[220:223], v[34:37]
	v_mfma_f32_16x16x32_bf16 v[22:25], v[180:183], v[228:231], v[22:25]
	v_mfma_f32_16x16x32_bf16 v[18:21], v[204:207], v[228:231], v[18:21]
	v_mfma_f32_16x16x32_bf16 v[6:9], v[180:183], v[236:239], v[6:9]
	v_mfma_f32_16x16x32_bf16 v[2:5], v[204:207], v[236:239], v[2:5]
	s_setprio 0
	s_barrier
	s_add_i32 s67, s67, 2
	s_add_u32 s36, s36, 0x100
	s_addc_u32 s37, s37, 0
	s_add_u32 s62, s62, 0x100
	s_addc_u32 s63, s63, 0
	s_cmp_gt_u32 s67, 29
	s_cbranch_scc0 .LBB0_281
	s_mov_b32 s32, 1
	s_andn2_b64 vcc, s[4:5], s[40:41]
	s_cbranch_vccnz .LBB0_286
	s_cmp_lt_i32 s57, 30
	s_mov_b64 s[18:19], -1
	s_cbranch_scc1 .LBB0_287

; #define PG8_BAR __builtin_amdgcn_s_barrier()
; template <class Epi, class Sched, bool ALIGN_EPI = false, bool SP2 = false>
; __device__ __forceinline__ void gemm_phase(PG8_LAS unsigned char* lds, const Gemm g, const Sched& S, const Epi& E) {
;     ...
;         if (!has_next) break;
; #pragma unroll
;         for (int a = 0; a < 2; ++a)
; #pragma unroll
;             for (int b = 0; b < 2; ++b)
; #pragma unroll
;                 for (int m = 0; m < 4; ++m)
; #pragma unroll
;                     for (int n = 0; n < 2; ++n) acc[a][b][m][n] = (f32x4){0.f, 0.f, 0.f, 0.f};
;         cur = nxt; cA = nA; cB = nB; ++ui;
;         if constexpr (ALIGN_EPI) { if (wr == 1) PG8_BAR; }
.LBB0_289:
	s_andn2_b64 vcc, exec, s[0:1]
	s_cbranch_vccnz .LBB0_276
	s_nop 0
	s_branch .LBB0_276
